# all 8 tile2 GEMM K-loops hand-rewritten with LDS-DMA + pipelined ds_reads; LN1 phase body rewritten: loads of next token and params issued before stores, one counted vmcnt wait per token
# speedup vs baseline: 1.0053x; 1.0053x over previous
.LBB0_552:
	s_and_b32 s34, s33, 0xff
	s_mul_i32 s4, s34, 0xab
	s_lshr_b32 s47, s4, 11
	s_mul_i32 s4, s47, 12
	s_sub_i32 s4, s33, s4
	s_and_b32 s4, s4, 0xff
	s_lshl_b32 s4, s4, 10
	s_or_b32 s48, s4, s15
	s_lshl_b32 s35, s48, 10
	s_lshl_b32 s4, s48, 11
	s_add_u32 s10, s16, s4
	s_addc_u32 s11, s17, 0
	s_lshl_b32 s46, s47, 17
	s_lshl_b32 s4, s47, 18
	s_add_u32 s12, s18, s4
	s_addc_u32 s13, s19, 0
	v_and_b32_e32 v164, 15, v0
	v_bfe_u32 v165, v0, 4, 2
	v_and_b32_e32 v111, 7, v164
	v_xor_b32_e32 v165, v165, v111
	v_lshlrev_b32_e32 v165, 4, v165
	v_lshl_or_b32 v165, v164, 7, v165
	v_bfe_u32 v164, v0, 7, 1
	v_lshl_or_b32 v100, v164, 13, v165
	v_bfe_u32 v164, v0, 6, 1
	v_lshl_or_b32 v158, v164, 13, v165
	v_or_b32_e32 v158, 0x4000, v158
	v_xor_b32_e32 v111, 64, v100
	v_xor_b32_e32 v159, 64, v158
	v_bfe_u32 v164, v0, 3, 3
	v_and_b32_e32 v165, 7, v0
	v_xor_b32_e32 v165, v165, v164
	v_lshlrev_b32_e32 v165, 4, v165
	v_lshl_or_b32 v165, v164, 11, v165
	v_lshrrev_b32_e32 v164, 6, v0
	v_and_b32_e32 v164, 3, v164
	v_lshl_or_b32 v160, v164, 16, v165
	v_add_u32_e32 v161, 0x3c00, v160
	v_add_u32_e32 v162, 0x7800, v160
	v_add_u32_e32 v163, 0xb400, v160
	v_lshlrev_b32_e32 v164, 12, v164
	s_nop 0
	v_readfirstlane_b32 s50, v164
	s_add_u32 s50, s50, 32
	v_mov_b32_e32 v94, 0
	v_mov_b32_e32 v95, 0
	v_mov_b32_e32 v96, 0
	v_mov_b32_e32 v97, 0
	v_mov_b32_e32 v90, 0
	v_mov_b32_e32 v91, 0
	v_mov_b32_e32 v92, 0
	v_mov_b32_e32 v93, 0
	v_mov_b32_e32 v82, 0
	v_mov_b32_e32 v83, 0
	v_mov_b32_e32 v84, 0
	v_mov_b32_e32 v85, 0
	v_mov_b32_e32 v78, 0
	v_mov_b32_e32 v79, 0
	v_mov_b32_e32 v80, 0
	v_mov_b32_e32 v81, 0
	v_mov_b32_e32 v74, 0
	v_mov_b32_e32 v75, 0
	v_mov_b32_e32 v76, 0
	v_mov_b32_e32 v77, 0
	v_mov_b32_e32 v70, 0
	v_mov_b32_e32 v71, 0
	v_mov_b32_e32 v72, 0
	v_mov_b32_e32 v73, 0
	v_mov_b32_e32 v66, 0
	v_mov_b32_e32 v67, 0
	v_mov_b32_e32 v68, 0
	v_mov_b32_e32 v69, 0
	v_mov_b32_e32 v58, 0
	v_mov_b32_e32 v59, 0
	v_mov_b32_e32 v60, 0
	v_mov_b32_e32 v61, 0
	v_mov_b32_e32 v26, 0
	v_mov_b32_e32 v27, 0
	v_mov_b32_e32 v28, 0
	v_mov_b32_e32 v29, 0
	v_mov_b32_e32 v22, 0
	v_mov_b32_e32 v23, 0
	v_mov_b32_e32 v24, 0
	v_mov_b32_e32 v25, 0
	v_mov_b32_e32 v18, 0
	v_mov_b32_e32 v19, 0
	v_mov_b32_e32 v20, 0
	v_mov_b32_e32 v21, 0
	v_mov_b32_e32 v14, 0
	v_mov_b32_e32 v15, 0
	v_mov_b32_e32 v16, 0
	v_mov_b32_e32 v17, 0
	v_mov_b32_e32 v10, 0
	v_mov_b32_e32 v11, 0
	v_mov_b32_e32 v12, 0
	v_mov_b32_e32 v13, 0
	v_mov_b32_e32 v6, 0
	v_mov_b32_e32 v7, 0
	v_mov_b32_e32 v8, 0
	v_mov_b32_e32 v9, 0
	v_mov_b32_e32 v2, 0
	v_mov_b32_e32 v3, 0
	v_mov_b32_e32 v4, 0
	v_mov_b32_e32 v5, 0
	v_mov_b32_e32 v86, 0
	v_mov_b32_e32 v87, 0
	v_mov_b32_e32 v88, 0
	v_mov_b32_e32 v89, 0
	v_mov_b32_e32 v114, 0
	v_mov_b32_e32 v115, 0
	v_mov_b32_e32 v116, 0
	v_mov_b32_e32 v117, 0
	v_mov_b32_e32 v118, 0
	v_mov_b32_e32 v119, 0
	v_mov_b32_e32 v120, 0
	v_mov_b32_e32 v121, 0
	v_mov_b32_e32 v122, 0
	v_mov_b32_e32 v123, 0
	v_mov_b32_e32 v124, 0
	v_mov_b32_e32 v125, 0
	v_mov_b32_e32 v138, 0
	v_mov_b32_e32 v139, 0
	v_mov_b32_e32 v140, 0
	v_mov_b32_e32 v141, 0
	v_mov_b32_e32 v142, 0
	v_mov_b32_e32 v143, 0
	v_mov_b32_e32 v144, 0
	v_mov_b32_e32 v145, 0
	v_mov_b32_e32 v146, 0
	v_mov_b32_e32 v147, 0
	v_mov_b32_e32 v148, 0
	v_mov_b32_e32 v149, 0
	v_mov_b32_e32 v150, 0
	v_mov_b32_e32 v151, 0
	v_mov_b32_e32 v152, 0
	v_mov_b32_e32 v153, 0
	v_mov_b32_e32 v154, 0
	v_mov_b32_e32 v155, 0
	v_mov_b32_e32 v156, 0
	v_mov_b32_e32 v157, 0
	s_waitcnt lgkmcnt(0)
	s_barrier
	s_add_u32 m0, s50, 0
	s_nop 0
	global_load_lds_dwordx4 v160, s[10:11] offset:0
	global_load_lds_dwordx4 v161, s[10:11] offset:1024
	global_load_lds_dwordx4 v162, s[10:11] offset:2048
	global_load_lds_dwordx4 v163, s[10:11] offset:3072
	s_add_u32 m0, s50, 16384
	s_nop 0
	global_load_lds_dwordx4 v160, s[12:13] offset:0
	global_load_lds_dwordx4 v161, s[12:13] offset:1024
	global_load_lds_dwordx4 v162, s[12:13] offset:2048
	global_load_lds_dwordx4 v163, s[12:13] offset:3072
	s_add_u32 s10, s10, 0x80
	s_addc_u32 s11, s11, 0
	s_add_u32 s12, s12, 0x80
	s_addc_u32 s13, s13, 0
	s_mov_b32 s49, 0
	s_waitcnt vmcnt(0)
.Lk_aol0a_loop:
	s_barrier
	s_add_u32 m0, s50, 32768
	v_mfma_f32_16x16x32_bf16 v[94:97], v[114:117], v[142:145], v[94:97]
	ds_read_b128 v[30:33], v100 offset:32
	global_load_lds_dwordx4 v160, s[10:11] offset:0
	v_mfma_f32_16x16x32_bf16 v[90:93], v[114:117], v[146:149], v[90:93]
	ds_read_b128 v[46:49], v158 offset:32
	global_load_lds_dwordx4 v161, s[10:11] offset:1024
	v_mfma_f32_16x16x32_bf16 v[82:85], v[114:117], v[150:153], v[82:85]
	ds_read_b128 v[50:53], v158 offset:2080
	global_load_lds_dwordx4 v162, s[10:11] offset:2048
	v_mfma_f32_16x16x32_bf16 v[78:81], v[114:117], v[154:157], v[78:81]
	ds_read_b128 v[34:37], v100 offset:2080
	global_load_lds_dwordx4 v163, s[10:11] offset:3072
	s_add_u32 m0, s50, 49152
	v_mfma_f32_16x16x32_bf16 v[74:77], v[118:121], v[142:145], v[74:77]
	ds_read_b128 v[54:57], v158 offset:4128
	global_load_lds_dwordx4 v160, s[12:13] offset:0
	v_mfma_f32_16x16x32_bf16 v[70:73], v[118:121], v[146:149], v[70:73]
	ds_read_b128 v[62:65], v158 offset:6176
	global_load_lds_dwordx4 v161, s[12:13] offset:1024
	v_mfma_f32_16x16x32_bf16 v[66:69], v[118:121], v[150:153], v[66:69]
	ds_read_b128 v[38:41], v100 offset:4128
	global_load_lds_dwordx4 v162, s[12:13] offset:2048
	v_mfma_f32_16x16x32_bf16 v[58:61], v[118:121], v[154:157], v[58:61]
	ds_read_b128 v[42:45], v100 offset:6176
	global_load_lds_dwordx4 v163, s[12:13] offset:3072
	v_mfma_f32_16x16x32_bf16 v[26:29], v[122:125], v[142:145], v[26:29]
	v_mfma_f32_16x16x32_bf16 v[22:25], v[122:125], v[146:149], v[22:25]
	v_mfma_f32_16x16x32_bf16 v[18:21], v[122:125], v[150:153], v[18:21]
	v_mfma_f32_16x16x32_bf16 v[14:17], v[122:125], v[154:157], v[14:17]
	v_mfma_f32_16x16x32_bf16 v[10:13], v[138:141], v[142:145], v[10:13]
	v_mfma_f32_16x16x32_bf16 v[6:9], v[138:141], v[146:149], v[6:9]
	v_mfma_f32_16x16x32_bf16 v[2:5], v[138:141], v[150:153], v[2:5]
	v_mfma_f32_16x16x32_bf16 v[86:89], v[138:141], v[154:157], v[86:89]
	s_add_u32 s10, s10, 0x80
	s_addc_u32 s11, s11, 0
	s_add_u32 s12, s12, 0x80
	s_addc_u32 s13, s13, 0
	s_waitcnt lgkmcnt(0)
	v_mfma_f32_16x16x32_bf16 v[94:97], v[30:33], v[46:49], v[94:97]
	ds_read_b128 v[114:117], v111 offset:32
	v_mfma_f32_16x16x32_bf16 v[90:93], v[30:33], v[50:53], v[90:93]
	ds_read_b128 v[142:145], v159 offset:32
	v_mfma_f32_16x16x32_bf16 v[82:85], v[30:33], v[54:57], v[82:85]
	ds_read_b128 v[146:149], v159 offset:2080
	v_mfma_f32_16x16x32_bf16 v[78:81], v[30:33], v[62:65], v[78:81]
	ds_read_b128 v[118:121], v111 offset:2080
	v_mfma_f32_16x16x32_bf16 v[74:77], v[34:37], v[46:49], v[74:77]
	ds_read_b128 v[150:153], v159 offset:4128
	v_mfma_f32_16x16x32_bf16 v[70:73], v[34:37], v[50:53], v[70:73]
	ds_read_b128 v[154:157], v159 offset:6176
	v_mfma_f32_16x16x32_bf16 v[66:69], v[34:37], v[54:57], v[66:69]
	ds_read_b128 v[122:125], v111 offset:4128
	v_mfma_f32_16x16x32_bf16 v[58:61], v[34:37], v[62:65], v[58:61]
	ds_read_b128 v[138:141], v111 offset:6176
	v_mfma_f32_16x16x32_bf16 v[26:29], v[38:41], v[46:49], v[26:29]
	v_mfma_f32_16x16x32_bf16 v[22:25], v[38:41], v[50:53], v[22:25]
	v_mfma_f32_16x16x32_bf16 v[18:21], v[38:41], v[54:57], v[18:21]
	v_mfma_f32_16x16x32_bf16 v[14:17], v[38:41], v[62:65], v[14:17]
	v_mfma_f32_16x16x32_bf16 v[10:13], v[42:45], v[46:49], v[10:13]
	v_mfma_f32_16x16x32_bf16 v[6:9], v[42:45], v[50:53], v[6:9]
	v_mfma_f32_16x16x32_bf16 v[2:5], v[42:45], v[54:57], v[2:5]
	v_mfma_f32_16x16x32_bf16 v[86:89], v[42:45], v[62:65], v[86:89]
	s_waitcnt lgkmcnt(0)
	s_waitcnt vmcnt(0)
	s_barrier
	s_add_u32 m0, s50, 0
	v_mfma_f32_16x16x32_bf16 v[94:97], v[114:117], v[142:145], v[94:97]
	ds_read_b128 v[30:33], v100 offset:32800
	global_load_lds_dwordx4 v160, s[10:11] offset:0
	v_mfma_f32_16x16x32_bf16 v[90:93], v[114:117], v[146:149], v[90:93]
	ds_read_b128 v[46:49], v158 offset:32800
	global_load_lds_dwordx4 v161, s[10:11] offset:1024
	v_mfma_f32_16x16x32_bf16 v[82:85], v[114:117], v[150:153], v[82:85]
	ds_read_b128 v[50:53], v158 offset:34848
	global_load_lds_dwordx4 v162, s[10:11] offset:2048
	v_mfma_f32_16x16x32_bf16 v[78:81], v[114:117], v[154:157], v[78:81]
	ds_read_b128 v[34:37], v100 offset:34848
	global_load_lds_dwordx4 v163, s[10:11] offset:3072
	s_add_u32 m0, s50, 16384
	v_mfma_f32_16x16x32_bf16 v[74:77], v[118:121], v[142:145], v[74:77]
	ds_read_b128 v[54:57], v158 offset:36896
	global_load_lds_dwordx4 v160, s[12:13] offset:0
	v_mfma_f32_16x16x32_bf16 v[70:73], v[118:121], v[146:149], v[70:73]
	ds_read_b128 v[62:65], v158 offset:38944
	global_load_lds_dwordx4 v161, s[12:13] offset:1024
	v_mfma_f32_16x16x32_bf16 v[66:69], v[118:121], v[150:153], v[66:69]
	ds_read_b128 v[38:41], v100 offset:36896
	global_load_lds_dwordx4 v162, s[12:13] offset:2048
	v_mfma_f32_16x16x32_bf16 v[58:61], v[118:121], v[154:157], v[58:61]
	ds_read_b128 v[42:45], v100 offset:38944
	global_load_lds_dwordx4 v163, s[12:13] offset:3072
	v_mfma_f32_16x16x32_bf16 v[26:29], v[122:125], v[142:145], v[26:29]
	v_mfma_f32_16x16x32_bf16 v[22:25], v[122:125], v[146:149], v[22:25]
	v_mfma_f32_16x16x32_bf16 v[18:21], v[122:125], v[150:153], v[18:21]
	v_mfma_f32_16x16x32_bf16 v[14:17], v[122:125], v[154:157], v[14:17]
	v_mfma_f32_16x16x32_bf16 v[10:13], v[138:141], v[142:145], v[10:13]
	v_mfma_f32_16x16x32_bf16 v[6:9], v[138:141], v[146:149], v[6:9]
	v_mfma_f32_16x16x32_bf16 v[2:5], v[138:141], v[150:153], v[2:5]
	v_mfma_f32_16x16x32_bf16 v[86:89], v[138:141], v[154:157], v[86:89]
	s_add_u32 s10, s10, 0x80
	s_addc_u32 s11, s11, 0
	s_add_u32 s12, s12, 0x80
	s_addc_u32 s13, s13, 0
	s_waitcnt lgkmcnt(0)
	v_mfma_f32_16x16x32_bf16 v[94:97], v[30:33], v[46:49], v[94:97]
	ds_read_b128 v[114:117], v111 offset:32800
	v_mfma_f32_16x16x32_bf16 v[90:93], v[30:33], v[50:53], v[90:93]
	ds_read_b128 v[142:145], v159 offset:32800
	v_mfma_f32_16x16x32_bf16 v[82:85], v[30:33], v[54:57], v[82:85]
	ds_read_b128 v[146:149], v159 offset:34848
	v_mfma_f32_16x16x32_bf16 v[78:81], v[30:33], v[62:65], v[78:81]
	ds_read_b128 v[118:121], v111 offset:34848
	v_mfma_f32_16x16x32_bf16 v[74:77], v[34:37], v[46:49], v[74:77]
	ds_read_b128 v[150:153], v159 offset:36896
	v_mfma_f32_16x16x32_bf16 v[70:73], v[34:37], v[50:53], v[70:73]
	ds_read_b128 v[154:157], v159 offset:38944
	v_mfma_f32_16x16x32_bf16 v[66:69], v[34:37], v[54:57], v[66:69]
	ds_read_b128 v[122:125], v111 offset:36896
	v_mfma_f32_16x16x32_bf16 v[58:61], v[34:37], v[62:65], v[58:61]
	ds_read_b128 v[138:141], v111 offset:38944
	v_mfma_f32_16x16x32_bf16 v[26:29], v[38:41], v[46:49], v[26:29]
	v_mfma_f32_16x16x32_bf16 v[22:25], v[38:41], v[50:53], v[22:25]
	v_mfma_f32_16x16x32_bf16 v[18:21], v[38:41], v[54:57], v[18:21]
	v_mfma_f32_16x16x32_bf16 v[14:17], v[38:41], v[62:65], v[14:17]
	v_mfma_f32_16x16x32_bf16 v[10:13], v[42:45], v[46:49], v[10:13]
	v_mfma_f32_16x16x32_bf16 v[6:9], v[42:45], v[50:53], v[6:9]
	v_mfma_f32_16x16x32_bf16 v[2:5], v[42:45], v[54:57], v[2:5]
	v_mfma_f32_16x16x32_bf16 v[86:89], v[42:45], v[62:65], v[86:89]
	s_waitcnt lgkmcnt(0)
	s_waitcnt vmcnt(0)
	s_add_u32 s49, s49, 1
	s_cmp_lt_u32 s49, 7
	s_cbranch_scc1 .Lk_aol0a_loop
	s_barrier
	s_add_u32 m0, s50, 32768
	v_mfma_f32_16x16x32_bf16 v[94:97], v[114:117], v[142:145], v[94:97]
	ds_read_b128 v[30:33], v100 offset:32
	global_load_lds_dwordx4 v160, s[10:11] offset:0
	v_mfma_f32_16x16x32_bf16 v[90:93], v[114:117], v[146:149], v[90:93]
	ds_read_b128 v[46:49], v158 offset:32
	global_load_lds_dwordx4 v161, s[10:11] offset:1024
	v_mfma_f32_16x16x32_bf16 v[82:85], v[114:117], v[150:153], v[82:85]
	ds_read_b128 v[50:53], v158 offset:2080
	global_load_lds_dwordx4 v162, s[10:11] offset:2048
	v_mfma_f32_16x16x32_bf16 v[78:81], v[114:117], v[154:157], v[78:81]
	ds_read_b128 v[34:37], v100 offset:2080
	global_load_lds_dwordx4 v163, s[10:11] offset:3072
	s_add_u32 m0, s50, 49152
	v_mfma_f32_16x16x32_bf16 v[74:77], v[118:121], v[142:145], v[74:77]
	ds_read_b128 v[54:57], v158 offset:4128
	global_load_lds_dwordx4 v160, s[12:13] offset:0
	v_mfma_f32_16x16x32_bf16 v[70:73], v[118:121], v[146:149], v[70:73]
	ds_read_b128 v[62:65], v158 offset:6176
	global_load_lds_dwordx4 v161, s[12:13] offset:1024
	v_mfma_f32_16x16x32_bf16 v[66:69], v[118:121], v[150:153], v[66:69]
	ds_read_b128 v[38:41], v100 offset:4128
	global_load_lds_dwordx4 v162, s[12:13] offset:2048
	v_mfma_f32_16x16x32_bf16 v[58:61], v[118:121], v[154:157], v[58:61]
	ds_read_b128 v[42:45], v100 offset:6176
	global_load_lds_dwordx4 v163, s[12:13] offset:3072
	v_mfma_f32_16x16x32_bf16 v[26:29], v[122:125], v[142:145], v[26:29]
	v_mfma_f32_16x16x32_bf16 v[22:25], v[122:125], v[146:149], v[22:25]
	v_mfma_f32_16x16x32_bf16 v[18:21], v[122:125], v[150:153], v[18:21]
	v_mfma_f32_16x16x32_bf16 v[14:17], v[122:125], v[154:157], v[14:17]
	v_mfma_f32_16x16x32_bf16 v[10:13], v[138:141], v[142:145], v[10:13]
	v_mfma_f32_16x16x32_bf16 v[6:9], v[138:141], v[146:149], v[6:9]
	v_mfma_f32_16x16x32_bf16 v[2:5], v[138:141], v[150:153], v[2:5]
	v_mfma_f32_16x16x32_bf16 v[86:89], v[138:141], v[154:157], v[86:89]
	s_add_u32 s10, s10, 0x80
	s_addc_u32 s11, s11, 0
	s_add_u32 s12, s12, 0x80
	s_addc_u32 s13, s13, 0
	s_waitcnt lgkmcnt(0)
	v_mfma_f32_16x16x32_bf16 v[94:97], v[30:33], v[46:49], v[94:97]
	ds_read_b128 v[114:117], v111 offset:32
	v_mfma_f32_16x16x32_bf16 v[90:93], v[30:33], v[50:53], v[90:93]
	ds_read_b128 v[142:145], v159 offset:32
	v_mfma_f32_16x16x32_bf16 v[82:85], v[30:33], v[54:57], v[82:85]
	ds_read_b128 v[146:149], v159 offset:2080
	v_mfma_f32_16x16x32_bf16 v[78:81], v[30:33], v[62:65], v[78:81]
	ds_read_b128 v[118:121], v111 offset:2080
	v_mfma_f32_16x16x32_bf16 v[74:77], v[34:37], v[46:49], v[74:77]
	ds_read_b128 v[150:153], v159 offset:4128
	v_mfma_f32_16x16x32_bf16 v[70:73], v[34:37], v[50:53], v[70:73]
	ds_read_b128 v[154:157], v159 offset:6176
	v_mfma_f32_16x16x32_bf16 v[66:69], v[34:37], v[54:57], v[66:69]
	ds_read_b128 v[122:125], v111 offset:4128
	v_mfma_f32_16x16x32_bf16 v[58:61], v[34:37], v[62:65], v[58:61]
	ds_read_b128 v[138:141], v111 offset:6176
	v_mfma_f32_16x16x32_bf16 v[26:29], v[38:41], v[46:49], v[26:29]
	v_mfma_f32_16x16x32_bf16 v[22:25], v[38:41], v[50:53], v[22:25]
	v_mfma_f32_16x16x32_bf16 v[18:21], v[38:41], v[54:57], v[18:21]
	v_mfma_f32_16x16x32_bf16 v[14:17], v[38:41], v[62:65], v[14:17]
	v_mfma_f32_16x16x32_bf16 v[10:13], v[42:45], v[46:49], v[10:13]
	v_mfma_f32_16x16x32_bf16 v[6:9], v[42:45], v[50:53], v[6:9]
	v_mfma_f32_16x16x32_bf16 v[2:5], v[42:45], v[54:57], v[2:5]
	v_mfma_f32_16x16x32_bf16 v[86:89], v[42:45], v[62:65], v[86:89]
	s_waitcnt lgkmcnt(0)
	s_waitcnt vmcnt(0)
	s_barrier
	v_mfma_f32_16x16x32_bf16 v[94:97], v[114:117], v[142:145], v[94:97]
	ds_read_b128 v[30:33], v100 offset:32800
	v_mfma_f32_16x16x32_bf16 v[90:93], v[114:117], v[146:149], v[90:93]
	ds_read_b128 v[46:49], v158 offset:32800
	v_mfma_f32_16x16x32_bf16 v[82:85], v[114:117], v[150:153], v[82:85]
	ds_read_b128 v[50:53], v158 offset:34848
	v_mfma_f32_16x16x32_bf16 v[78:81], v[114:117], v[154:157], v[78:81]
	ds_read_b128 v[34:37], v100 offset:34848
	v_mfma_f32_16x16x32_bf16 v[74:77], v[118:121], v[142:145], v[74:77]
	ds_read_b128 v[54:57], v158 offset:36896
	v_mfma_f32_16x16x32_bf16 v[70:73], v[118:121], v[146:149], v[70:73]
	ds_read_b128 v[62:65], v158 offset:38944
	v_mfma_f32_16x16x32_bf16 v[66:69], v[118:121], v[150:153], v[66:69]
	ds_read_b128 v[38:41], v100 offset:36896
	v_mfma_f32_16x16x32_bf16 v[58:61], v[118:121], v[154:157], v[58:61]
	ds_read_b128 v[42:45], v100 offset:38944
	v_mfma_f32_16x16x32_bf16 v[26:29], v[122:125], v[142:145], v[26:29]
	v_mfma_f32_16x16x32_bf16 v[22:25], v[122:125], v[146:149], v[22:25]
	v_mfma_f32_16x16x32_bf16 v[18:21], v[122:125], v[150:153], v[18:21]
	v_mfma_f32_16x16x32_bf16 v[14:17], v[122:125], v[154:157], v[14:17]
	v_mfma_f32_16x16x32_bf16 v[10:13], v[138:141], v[142:145], v[10:13]
	v_mfma_f32_16x16x32_bf16 v[6:9], v[138:141], v[146:149], v[6:9]
	v_mfma_f32_16x16x32_bf16 v[2:5], v[138:141], v[150:153], v[2:5]
	v_mfma_f32_16x16x32_bf16 v[86:89], v[138:141], v[154:157], v[86:89]
	s_waitcnt lgkmcnt(0)
	v_mfma_f32_16x16x32_bf16 v[94:97], v[30:33], v[46:49], v[94:97]
	ds_read_b128 v[114:117], v111 offset:32800
	v_mfma_f32_16x16x32_bf16 v[90:93], v[30:33], v[50:53], v[90:93]
	ds_read_b128 v[142:145], v159 offset:32800
	v_mfma_f32_16x16x32_bf16 v[82:85], v[30:33], v[54:57], v[82:85]
	ds_read_b128 v[146:149], v159 offset:34848
	v_mfma_f32_16x16x32_bf16 v[78:81], v[30:33], v[62:65], v[78:81]
	ds_read_b128 v[118:121], v111 offset:34848
	v_mfma_f32_16x16x32_bf16 v[74:77], v[34:37], v[46:49], v[74:77]
	ds_read_b128 v[150:153], v159 offset:36896
	v_mfma_f32_16x16x32_bf16 v[70:73], v[34:37], v[50:53], v[70:73]
	ds_read_b128 v[154:157], v159 offset:38944
	v_mfma_f32_16x16x32_bf16 v[66:69], v[34:37], v[54:57], v[66:69]
	ds_read_b128 v[122:125], v111 offset:36896
	v_mfma_f32_16x16x32_bf16 v[58:61], v[34:37], v[62:65], v[58:61]
	ds_read_b128 v[138:141], v111 offset:38944
	v_mfma_f32_16x16x32_bf16 v[26:29], v[38:41], v[46:49], v[26:29]
	v_mfma_f32_16x16x32_bf16 v[22:25], v[38:41], v[50:53], v[22:25]
	v_mfma_f32_16x16x32_bf16 v[18:21], v[38:41], v[54:57], v[18:21]
	v_mfma_f32_16x16x32_bf16 v[14:17], v[38:41], v[62:65], v[14:17]
	v_mfma_f32_16x16x32_bf16 v[10:13], v[42:45], v[46:49], v[10:13]
	v_mfma_f32_16x16x32_bf16 v[6:9], v[42:45], v[50:53], v[6:9]
	v_mfma_f32_16x16x32_bf16 v[2:5], v[42:45], v[54:57], v[2:5]
	v_mfma_f32_16x16x32_bf16 v[86:89], v[42:45], v[62:65], v[86:89]
	s_waitcnt lgkmcnt(0)
	v_mfma_f32_16x16x32_bf16 v[94:97], v[114:117], v[142:145], v[94:97]
	v_mfma_f32_16x16x32_bf16 v[90:93], v[114:117], v[146:149], v[90:93]
	v_mfma_f32_16x16x32_bf16 v[82:85], v[114:117], v[150:153], v[82:85]
	v_mfma_f32_16x16x32_bf16 v[78:81], v[114:117], v[154:157], v[78:81]
	v_mfma_f32_16x16x32_bf16 v[74:77], v[118:121], v[142:145], v[74:77]
	v_mfma_f32_16x16x32_bf16 v[70:73], v[118:121], v[146:149], v[70:73]
	v_mfma_f32_16x16x32_bf16 v[66:69], v[118:121], v[150:153], v[66:69]
	v_mfma_f32_16x16x32_bf16 v[58:61], v[118:121], v[154:157], v[58:61]
	v_mfma_f32_16x16x32_bf16 v[26:29], v[122:125], v[142:145], v[26:29]
	v_mfma_f32_16x16x32_bf16 v[22:25], v[122:125], v[146:149], v[22:25]
	v_mfma_f32_16x16x32_bf16 v[18:21], v[122:125], v[150:153], v[18:21]
	v_mfma_f32_16x16x32_bf16 v[14:17], v[122:125], v[154:157], v[14:17]
	v_mfma_f32_16x16x32_bf16 v[10:13], v[138:141], v[142:145], v[10:13]
	v_mfma_f32_16x16x32_bf16 v[6:9], v[138:141], v[146:149], v[6:9]
	v_mfma_f32_16x16x32_bf16 v[2:5], v[138:141], v[150:153], v[2:5]
	v_mfma_f32_16x16x32_bf16 v[86:89], v[138:141], v[154:157], v[86:89]
	s_mul_i32 s4, s31, s25
	s_add_i32 s4, s4, s30
	s_and_b32 s4, s4, 0xff
	s_waitcnt vmcnt(7)
	v_lshl_or_b32 v30, s4, 10, v132
	s_mul_hi_u32 s4, s4, 0x15555556
	s_mulk_i32 s4, 0xd000
	v_add_u32_e32 v30, s4, v30
	s_lshl_b32 s4, s47, 8
	v_add_u32_e32 v138, 0x400, v129
	v_add_u32_e32 v139, 0x2000, v129
	v_add_u32_e32 v140, 0x2400, v129
	v_add_u32_e32 v141, 0x4000, v129
	v_add_u32_e32 v142, 0x4400, v129
	v_add_u32_e32 v143, 0x4800, v129
	v_add_u32_e32 v144, 0x6000, v129
	v_add_u32_e32 v145, 0x6400, v129
	v_add_u32_e32 v146, 0x6800, v129
	v_lshl_add_u64 v[114:115], v[102:103], 0, s[4:5]
	v_cmp_gt_u32_e32 vcc, s29, v30
	s_barrier
	ds_write2_b32 v129, v94, v90 offset1:16
	ds_write2_b32 v129, v95, v91 offset0:132 offset1:148
	ds_write2_b32 v138, v96, v92 offset0:8 offset1:24
	ds_write2_b32 v138, v97, v93 offset0:140 offset1:156
	ds_write2_b32 v129, v82, v78 offset0:32 offset1:48
	ds_write2_b32 v129, v83, v79 offset0:164 offset1:180
	ds_write2_b32 v138, v84, v80 offset0:40 offset1:56
	ds_write2_b32 v138, v85, v81 offset0:172 offset1:188
	ds_write2_b32 v139, v74, v70 offset0:64 offset1:80
	ds_write2_b32 v139, v75, v71 offset0:196 offset1:212
	ds_write2_b32 v140, v76, v72 offset0:72 offset1:88
	ds_write2_b32 v140, v77, v73 offset0:204 offset1:220
	ds_write2_b32 v139, v66, v58 offset0:96 offset1:112
	ds_write2_b32 v139, v67, v59 offset0:228 offset1:244
	ds_write2_b32 v140, v68, v60 offset0:104 offset1:120
	ds_write2_b32 v140, v69, v61 offset0:236 offset1:252
	ds_write2_b32 v141, v26, v22 offset0:128 offset1:144
	ds_write2_b32 v142, v27, v23 offset0:4 offset1:20
	ds_write2_b32 v142, v28, v24 offset0:136 offset1:152
	ds_write2_b32 v143, v29, v25 offset0:12 offset1:28
	ds_write2_b32 v141, v18, v14 offset0:160 offset1:176
	ds_write2_b32 v142, v19, v15 offset0:36 offset1:52
	ds_write2_b32 v142, v20, v16 offset0:168 offset1:184
	ds_write2_b32 v143, v21, v17 offset0:44 offset1:60
	ds_write2_b32 v144, v10, v6 offset0:192 offset1:208
	ds_write2_b32 v145, v11, v7 offset0:68 offset1:84
	ds_write2_b32 v145, v12, v8 offset0:200 offset1:216
	ds_write2_b32 v146, v13, v9 offset0:76 offset1:92
	ds_write2_b32 v144, v2, v86 offset0:224 offset1:240
	ds_write2_b32 v145, v3, v87 offset0:100 offset1:116
	ds_write2_b32 v145, v4, v88 offset0:232 offset1:248
	ds_write2_b32 v146, v5, v89 offset0:108 offset1:124
	s_waitcnt lgkmcnt(0)
	s_barrier
	s_and_saveexec_b64 s[10:11], vcc
	s_xor_b64 s[10:11], exec, s[10:11]
	s_cbranch_execz .LBB0_557
	s_mov_b32 s4, s48
	s_mov_b32 s12, 1
	s_mov_b32 s13, 0
	s_mov_b32 s49, 8

.LBB0_560:
	s_or_b64 exec, exec, s[10:11]
	s_lshl_b32 s10, s47, 7
	s_lshl_b32 s4, s35, 1
	s_add_u32 s12, s21, s4
	s_addc_u32 s13, s22, 0
	s_lshl_b32 s4, s46, 1
	v_mov_b32_e32 v111, v101
	s_add_u32 s46, s23, s4
	s_addc_u32 s47, s24, 0
	s_waitcnt lgkmcnt(0)
	s_barrier
	ds_read2_b32 v[26:27], v129 offset1:16
	ds_read2_b32 v[148:149], v129 offset0:132 offset1:148
	ds_read2_b32 v[28:29], v138 offset0:8 offset1:24
	ds_read2_b32 v[150:151], v138 offset0:140 offset1:156
	ds_read2_b32 v[22:23], v129 offset0:32 offset1:48
	ds_read2_b32 v[152:153], v129 offset0:164 offset1:180
	ds_read2_b32 v[24:25], v138 offset0:40 offset1:56
	ds_read2_b32 v[154:155], v138 offset0:172 offset1:188
	ds_read2_b32 v[18:19], v139 offset0:64 offset1:80
	ds_read2_b32 v[156:157], v139 offset0:196 offset1:212
	ds_read2_b32 v[20:21], v140 offset0:72 offset1:88
	ds_read2_b32 v[158:159], v140 offset0:204 offset1:220
	ds_read2_b32 v[14:15], v139 offset0:96 offset1:112
	ds_read2_b32 v[160:161], v139 offset0:228 offset1:244
	ds_read2_b32 v[16:17], v140 offset0:104 offset1:120
	ds_read2_b32 v[162:163], v140 offset0:236 offset1:252
	ds_read2_b32 v[10:11], v141 offset0:128 offset1:144
	ds_read2_b32 v[164:165], v142 offset0:4 offset1:20
	ds_read2_b32 v[12:13], v142 offset0:136 offset1:152
	ds_read2_b32 v[166:167], v143 offset0:12 offset1:28
	ds_read2_b32 v[6:7], v141 offset0:160 offset1:176
	ds_read2_b32 v[168:169], v142 offset0:36 offset1:52
	ds_read2_b32 v[8:9], v142 offset0:168 offset1:184
	ds_read2_b32 v[170:171], v143 offset0:44 offset1:60
	ds_read2_b32 v[2:3], v144 offset0:192 offset1:208
	ds_read2_b32 v[172:173], v145 offset0:68 offset1:84
	ds_read2_b32 v[4:5], v145 offset0:200 offset1:216
	ds_read2_b32 v[174:175], v146 offset0:76 offset1:92
	ds_read2_b32 v[30:31], v144 offset0:224 offset1:240
	ds_read2_b32 v[176:177], v145 offset0:100 offset1:116
	ds_read2_b32 v[32:33], v145 offset0:232 offset1:248
	ds_read2_b32 v[180:181], v146 offset0:108 offset1:124
	s_waitcnt lgkmcnt(0)
	s_barrier
	v_mov_b32_e32 v94, v31
	v_mov_b32_e32 v95, v177
	v_mov_b32_e32 v96, v33
	v_mov_b32_e32 v97, v181
	v_mov_b32_e32 v31, v176
	v_mov_b32_e32 v33, v180
	v_mov_b32_e32 v66, v3
	v_mov_b32_e32 v67, v173
	v_mov_b32_e32 v68, v5
	v_mov_b32_e32 v69, v175
	v_mov_b32_e32 v3, v172
	v_mov_b32_e32 v5, v174
	v_mov_b32_e32 v70, v7
	v_mov_b32_e32 v71, v169
	v_mov_b32_e32 v72, v9
	v_mov_b32_e32 v73, v171
	v_mov_b32_e32 v7, v168
	v_mov_b32_e32 v9, v170
	v_mov_b32_e32 v74, v11
	v_mov_b32_e32 v75, v165
	v_mov_b32_e32 v76, v13
	v_mov_b32_e32 v77, v167
	v_mov_b32_e32 v11, v164
	v_mov_b32_e32 v13, v166
	v_mov_b32_e32 v78, v15
	v_mov_b32_e32 v79, v161
	v_mov_b32_e32 v80, v17
	v_mov_b32_e32 v81, v163
	v_mov_b32_e32 v15, v160
	v_mov_b32_e32 v17, v162
	v_mov_b32_e32 v82, v19
	v_mov_b32_e32 v83, v157
	v_mov_b32_e32 v84, v21
	v_mov_b32_e32 v85, v159
	v_mov_b32_e32 v19, v156
	v_mov_b32_e32 v21, v158
	v_mov_b32_e32 v86, v23
	v_mov_b32_e32 v87, v153
	v_mov_b32_e32 v88, v25
	v_mov_b32_e32 v89, v155
	v_mov_b32_e32 v23, v152
	v_mov_b32_e32 v25, v154
	v_mov_b32_e32 v90, v27
	v_mov_b32_e32 v91, v149
	v_mov_b32_e32 v92, v29
	v_mov_b32_e32 v93, v151
	v_mov_b32_e32 v27, v148
	v_mov_b32_e32 v29, v150
	s_waitcnt lgkmcnt(0)
	s_barrier
	v_and_b32_e32 v174, 15, v0
	v_bfe_u32 v175, v0, 4, 2
	v_and_b32_e32 v111, 7, v174
	v_xor_b32_e32 v175, v175, v111
	v_lshlrev_b32_e32 v175, 4, v175
	v_lshl_or_b32 v175, v174, 7, v175
	v_bfe_u32 v174, v0, 7, 1
	v_lshl_or_b32 v100, v174, 13, v175
	v_bfe_u32 v174, v0, 6, 1
	v_lshl_or_b32 v168, v174, 13, v175
	v_or_b32_e32 v168, 0x4000, v168
	v_xor_b32_e32 v111, 64, v100
	v_xor_b32_e32 v169, 64, v168
	v_bfe_u32 v174, v0, 3, 3
	v_and_b32_e32 v175, 7, v0
	v_xor_b32_e32 v175, v175, v174
	v_lshlrev_b32_e32 v175, 4, v175
	v_lshl_or_b32 v175, v174, 11, v175
	v_lshrrev_b32_e32 v174, 6, v0
	v_and_b32_e32 v174, 3, v174
	v_lshl_or_b32 v170, v174, 16, v175
	v_add_u32_e32 v171, 0x3c00, v170
	v_add_u32_e32 v172, 0x7800, v170
	v_add_u32_e32 v173, 0xb400, v170
	v_lshlrev_b32_e32 v174, 12, v174
	s_nop 0
	v_readfirstlane_b32 s4, v174
	s_add_u32 s4, s4, 32
	v_mov_b32_e32 v116, 0
	v_mov_b32_e32 v117, 0
	v_mov_b32_e32 v118, 0
	v_mov_b32_e32 v119, 0
	v_mov_b32_e32 v120, 0
	v_mov_b32_e32 v121, 0
	v_mov_b32_e32 v122, 0
	v_mov_b32_e32 v123, 0
	v_mov_b32_e32 v124, 0
	v_mov_b32_e32 v125, 0
	v_mov_b32_e32 v126, 0
	v_mov_b32_e32 v127, 0
	v_mov_b32_e32 v148, 0
	v_mov_b32_e32 v149, 0
	v_mov_b32_e32 v150, 0
	v_mov_b32_e32 v151, 0
	v_mov_b32_e32 v152, 0
	v_mov_b32_e32 v153, 0
	v_mov_b32_e32 v154, 0
	v_mov_b32_e32 v155, 0
	v_mov_b32_e32 v156, 0
	v_mov_b32_e32 v157, 0
	v_mov_b32_e32 v158, 0
	v_mov_b32_e32 v159, 0
	v_mov_b32_e32 v160, 0
	v_mov_b32_e32 v161, 0
	v_mov_b32_e32 v162, 0
	v_mov_b32_e32 v163, 0
	v_mov_b32_e32 v164, 0
	v_mov_b32_e32 v165, 0
	v_mov_b32_e32 v166, 0
	v_mov_b32_e32 v167, 0
	s_waitcnt lgkmcnt(0)
	s_barrier
	s_add_u32 m0, s4, 0
	s_nop 0
	global_load_lds_dwordx4 v170, s[12:13] offset:0
	global_load_lds_dwordx4 v171, s[12:13] offset:1024
	global_load_lds_dwordx4 v172, s[12:13] offset:2048
	global_load_lds_dwordx4 v173, s[12:13] offset:3072
	s_add_u32 m0, s4, 16384
	s_nop 0
	global_load_lds_dwordx4 v170, s[46:47] offset:0
	global_load_lds_dwordx4 v171, s[46:47] offset:1024
	global_load_lds_dwordx4 v172, s[46:47] offset:2048
	global_load_lds_dwordx4 v173, s[46:47] offset:3072
	s_add_u32 s12, s12, 0x80
	s_addc_u32 s13, s13, 0
	s_add_u32 s46, s46, 0x80
	s_addc_u32 s47, s47, 0
	s_mov_b32 s11, 0
	s_waitcnt vmcnt(0)
.Lk_aol0b_loop:
	s_barrier
	s_add_u32 m0, s4, 32768
	v_mfma_f32_16x16x32_bf16 v[26:29], v[116:119], v[152:155], v[26:29]
	ds_read_b128 v[34:37], v100 offset:32
	global_load_lds_dwordx4 v170, s[12:13] offset:0
	v_mfma_f32_16x16x32_bf16 v[90:93], v[116:119], v[156:159], v[90:93]
	ds_read_b128 v[50:53], v168 offset:32
	global_load_lds_dwordx4 v171, s[12:13] offset:1024
	v_mfma_f32_16x16x32_bf16 v[22:25], v[116:119], v[160:163], v[22:25]
	ds_read_b128 v[54:57], v168 offset:2080
	global_load_lds_dwordx4 v172, s[12:13] offset:2048
	v_mfma_f32_16x16x32_bf16 v[86:89], v[116:119], v[164:167], v[86:89]
	ds_read_b128 v[38:41], v100 offset:2080
	global_load_lds_dwordx4 v173, s[12:13] offset:3072
	s_add_u32 m0, s4, 49152
	v_mfma_f32_16x16x32_bf16 v[18:21], v[120:123], v[152:155], v[18:21]
	ds_read_b128 v[58:61], v168 offset:4128
	global_load_lds_dwordx4 v170, s[46:47] offset:0
	v_mfma_f32_16x16x32_bf16 v[82:85], v[120:123], v[156:159], v[82:85]
	ds_read_b128 v[62:65], v168 offset:6176
	global_load_lds_dwordx4 v171, s[46:47] offset:1024
	v_mfma_f32_16x16x32_bf16 v[14:17], v[120:123], v[160:163], v[14:17]
	ds_read_b128 v[42:45], v100 offset:4128
	global_load_lds_dwordx4 v172, s[46:47] offset:2048
	v_mfma_f32_16x16x32_bf16 v[78:81], v[120:123], v[164:167], v[78:81]
	ds_read_b128 v[46:49], v100 offset:6176
	global_load_lds_dwordx4 v173, s[46:47] offset:3072
	v_mfma_f32_16x16x32_bf16 v[10:13], v[124:127], v[152:155], v[10:13]
	v_mfma_f32_16x16x32_bf16 v[74:77], v[124:127], v[156:159], v[74:77]
	v_mfma_f32_16x16x32_bf16 v[6:9], v[124:127], v[160:163], v[6:9]
	v_mfma_f32_16x16x32_bf16 v[70:73], v[124:127], v[164:167], v[70:73]
	v_mfma_f32_16x16x32_bf16 v[2:5], v[148:151], v[152:155], v[2:5]
	v_mfma_f32_16x16x32_bf16 v[66:69], v[148:151], v[156:159], v[66:69]
	v_mfma_f32_16x16x32_bf16 v[30:33], v[148:151], v[160:163], v[30:33]
	v_mfma_f32_16x16x32_bf16 v[94:97], v[148:151], v[164:167], v[94:97]
	s_add_u32 s12, s12, 0x80
	s_addc_u32 s13, s13, 0
	s_add_u32 s46, s46, 0x80
	s_addc_u32 s47, s47, 0
	s_waitcnt lgkmcnt(0)
	v_mfma_f32_16x16x32_bf16 v[26:29], v[34:37], v[50:53], v[26:29]
	ds_read_b128 v[116:119], v111 offset:32
	v_mfma_f32_16x16x32_bf16 v[90:93], v[34:37], v[54:57], v[90:93]
	ds_read_b128 v[152:155], v169 offset:32
	v_mfma_f32_16x16x32_bf16 v[22:25], v[34:37], v[58:61], v[22:25]
	ds_read_b128 v[156:159], v169 offset:2080
	v_mfma_f32_16x16x32_bf16 v[86:89], v[34:37], v[62:65], v[86:89]
	ds_read_b128 v[120:123], v111 offset:2080
	v_mfma_f32_16x16x32_bf16 v[18:21], v[38:41], v[50:53], v[18:21]
	ds_read_b128 v[160:163], v169 offset:4128
	v_mfma_f32_16x16x32_bf16 v[82:85], v[38:41], v[54:57], v[82:85]
	ds_read_b128 v[164:167], v169 offset:6176
	v_mfma_f32_16x16x32_bf16 v[14:17], v[38:41], v[58:61], v[14:17]
	ds_read_b128 v[124:127], v111 offset:4128
	v_mfma_f32_16x16x32_bf16 v[78:81], v[38:41], v[62:65], v[78:81]
	ds_read_b128 v[148:151], v111 offset:6176
	v_mfma_f32_16x16x32_bf16 v[10:13], v[42:45], v[50:53], v[10:13]
	v_mfma_f32_16x16x32_bf16 v[74:77], v[42:45], v[54:57], v[74:77]
	v_mfma_f32_16x16x32_bf16 v[6:9], v[42:45], v[58:61], v[6:9]
	v_mfma_f32_16x16x32_bf16 v[70:73], v[42:45], v[62:65], v[70:73]
	v_mfma_f32_16x16x32_bf16 v[2:5], v[46:49], v[50:53], v[2:5]
	v_mfma_f32_16x16x32_bf16 v[66:69], v[46:49], v[54:57], v[66:69]
	v_mfma_f32_16x16x32_bf16 v[30:33], v[46:49], v[58:61], v[30:33]
	v_mfma_f32_16x16x32_bf16 v[94:97], v[46:49], v[62:65], v[94:97]
	s_waitcnt lgkmcnt(0)
	s_waitcnt vmcnt(0)
	s_barrier
	s_add_u32 m0, s4, 0
	v_mfma_f32_16x16x32_bf16 v[26:29], v[116:119], v[152:155], v[26:29]
	ds_read_b128 v[34:37], v100 offset:32800
	global_load_lds_dwordx4 v170, s[12:13] offset:0
	v_mfma_f32_16x16x32_bf16 v[90:93], v[116:119], v[156:159], v[90:93]
	ds_read_b128 v[50:53], v168 offset:32800
	global_load_lds_dwordx4 v171, s[12:13] offset:1024
	v_mfma_f32_16x16x32_bf16 v[22:25], v[116:119], v[160:163], v[22:25]
	ds_read_b128 v[54:57], v168 offset:34848
	global_load_lds_dwordx4 v172, s[12:13] offset:2048
	v_mfma_f32_16x16x32_bf16 v[86:89], v[116:119], v[164:167], v[86:89]
	ds_read_b128 v[38:41], v100 offset:34848
	global_load_lds_dwordx4 v173, s[12:13] offset:3072
	s_add_u32 m0, s4, 16384
	v_mfma_f32_16x16x32_bf16 v[18:21], v[120:123], v[152:155], v[18:21]
	ds_read_b128 v[58:61], v168 offset:36896
	global_load_lds_dwordx4 v170, s[46:47] offset:0
	v_mfma_f32_16x16x32_bf16 v[82:85], v[120:123], v[156:159], v[82:85]
	ds_read_b128 v[62:65], v168 offset:38944
	global_load_lds_dwordx4 v171, s[46:47] offset:1024
	v_mfma_f32_16x16x32_bf16 v[14:17], v[120:123], v[160:163], v[14:17]
	ds_read_b128 v[42:45], v100 offset:36896
	global_load_lds_dwordx4 v172, s[46:47] offset:2048
	v_mfma_f32_16x16x32_bf16 v[78:81], v[120:123], v[164:167], v[78:81]
	ds_read_b128 v[46:49], v100 offset:38944
	global_load_lds_dwordx4 v173, s[46:47] offset:3072
	v_mfma_f32_16x16x32_bf16 v[10:13], v[124:127], v[152:155], v[10:13]
	v_mfma_f32_16x16x32_bf16 v[74:77], v[124:127], v[156:159], v[74:77]
	v_mfma_f32_16x16x32_bf16 v[6:9], v[124:127], v[160:163], v[6:9]
	v_mfma_f32_16x16x32_bf16 v[70:73], v[124:127], v[164:167], v[70:73]
	v_mfma_f32_16x16x32_bf16 v[2:5], v[148:151], v[152:155], v[2:5]
	v_mfma_f32_16x16x32_bf16 v[66:69], v[148:151], v[156:159], v[66:69]
	v_mfma_f32_16x16x32_bf16 v[30:33], v[148:151], v[160:163], v[30:33]
	v_mfma_f32_16x16x32_bf16 v[94:97], v[148:151], v[164:167], v[94:97]
	s_add_u32 s12, s12, 0x80
	s_addc_u32 s13, s13, 0
	s_add_u32 s46, s46, 0x80
	s_addc_u32 s47, s47, 0
	s_waitcnt lgkmcnt(0)
	v_mfma_f32_16x16x32_bf16 v[26:29], v[34:37], v[50:53], v[26:29]
	ds_read_b128 v[116:119], v111 offset:32800
	v_mfma_f32_16x16x32_bf16 v[90:93], v[34:37], v[54:57], v[90:93]
	ds_read_b128 v[152:155], v169 offset:32800
	v_mfma_f32_16x16x32_bf16 v[22:25], v[34:37], v[58:61], v[22:25]
	ds_read_b128 v[156:159], v169 offset:34848
	v_mfma_f32_16x16x32_bf16 v[86:89], v[34:37], v[62:65], v[86:89]
	ds_read_b128 v[120:123], v111 offset:34848
	v_mfma_f32_16x16x32_bf16 v[18:21], v[38:41], v[50:53], v[18:21]
	ds_read_b128 v[160:163], v169 offset:36896
	v_mfma_f32_16x16x32_bf16 v[82:85], v[38:41], v[54:57], v[82:85]
	ds_read_b128 v[164:167], v169 offset:38944
	v_mfma_f32_16x16x32_bf16 v[14:17], v[38:41], v[58:61], v[14:17]
	ds_read_b128 v[124:127], v111 offset:36896
	v_mfma_f32_16x16x32_bf16 v[78:81], v[38:41], v[62:65], v[78:81]
	ds_read_b128 v[148:151], v111 offset:38944
	v_mfma_f32_16x16x32_bf16 v[10:13], v[42:45], v[50:53], v[10:13]
	v_mfma_f32_16x16x32_bf16 v[74:77], v[42:45], v[54:57], v[74:77]
	v_mfma_f32_16x16x32_bf16 v[6:9], v[42:45], v[58:61], v[6:9]
	v_mfma_f32_16x16x32_bf16 v[70:73], v[42:45], v[62:65], v[70:73]
	v_mfma_f32_16x16x32_bf16 v[2:5], v[46:49], v[50:53], v[2:5]
	v_mfma_f32_16x16x32_bf16 v[66:69], v[46:49], v[54:57], v[66:69]
	v_mfma_f32_16x16x32_bf16 v[30:33], v[46:49], v[58:61], v[30:33]
	v_mfma_f32_16x16x32_bf16 v[94:97], v[46:49], v[62:65], v[94:97]
	s_waitcnt lgkmcnt(0)
	s_waitcnt vmcnt(0)
	s_add_u32 s11, s11, 1
	s_cmp_lt_u32 s11, 7
	s_cbranch_scc1 .Lk_aol0b_loop
	s_barrier
	s_add_u32 m0, s4, 32768
	v_mfma_f32_16x16x32_bf16 v[26:29], v[116:119], v[152:155], v[26:29]
	ds_read_b128 v[34:37], v100 offset:32
	global_load_lds_dwordx4 v170, s[12:13] offset:0
	v_mfma_f32_16x16x32_bf16 v[90:93], v[116:119], v[156:159], v[90:93]
	ds_read_b128 v[50:53], v168 offset:32
	global_load_lds_dwordx4 v171, s[12:13] offset:1024
	v_mfma_f32_16x16x32_bf16 v[22:25], v[116:119], v[160:163], v[22:25]
	ds_read_b128 v[54:57], v168 offset:2080
	global_load_lds_dwordx4 v172, s[12:13] offset:2048
	v_mfma_f32_16x16x32_bf16 v[86:89], v[116:119], v[164:167], v[86:89]
	ds_read_b128 v[38:41], v100 offset:2080
	global_load_lds_dwordx4 v173, s[12:13] offset:3072
	s_add_u32 m0, s4, 49152
	v_mfma_f32_16x16x32_bf16 v[18:21], v[120:123], v[152:155], v[18:21]
	ds_read_b128 v[58:61], v168 offset:4128
	global_load_lds_dwordx4 v170, s[46:47] offset:0
	v_mfma_f32_16x16x32_bf16 v[82:85], v[120:123], v[156:159], v[82:85]
	ds_read_b128 v[62:65], v168 offset:6176
	global_load_lds_dwordx4 v171, s[46:47] offset:1024
	v_mfma_f32_16x16x32_bf16 v[14:17], v[120:123], v[160:163], v[14:17]
	ds_read_b128 v[42:45], v100 offset:4128
	global_load_lds_dwordx4 v172, s[46:47] offset:2048
	v_mfma_f32_16x16x32_bf16 v[78:81], v[120:123], v[164:167], v[78:81]
	ds_read_b128 v[46:49], v100 offset:6176
	global_load_lds_dwordx4 v173, s[46:47] offset:3072
	v_mfma_f32_16x16x32_bf16 v[10:13], v[124:127], v[152:155], v[10:13]
	v_mfma_f32_16x16x32_bf16 v[74:77], v[124:127], v[156:159], v[74:77]
	v_mfma_f32_16x16x32_bf16 v[6:9], v[124:127], v[160:163], v[6:9]
	v_mfma_f32_16x16x32_bf16 v[70:73], v[124:127], v[164:167], v[70:73]
	v_mfma_f32_16x16x32_bf16 v[2:5], v[148:151], v[152:155], v[2:5]
	v_mfma_f32_16x16x32_bf16 v[66:69], v[148:151], v[156:159], v[66:69]
	v_mfma_f32_16x16x32_bf16 v[30:33], v[148:151], v[160:163], v[30:33]
	v_mfma_f32_16x16x32_bf16 v[94:97], v[148:151], v[164:167], v[94:97]
	s_add_u32 s12, s12, 0x80
	s_addc_u32 s13, s13, 0
	s_add_u32 s46, s46, 0x80
	s_addc_u32 s47, s47, 0
	s_waitcnt lgkmcnt(0)
	v_mfma_f32_16x16x32_bf16 v[26:29], v[34:37], v[50:53], v[26:29]
	ds_read_b128 v[116:119], v111 offset:32
	v_mfma_f32_16x16x32_bf16 v[90:93], v[34:37], v[54:57], v[90:93]
	ds_read_b128 v[152:155], v169 offset:32
	v_mfma_f32_16x16x32_bf16 v[22:25], v[34:37], v[58:61], v[22:25]
	ds_read_b128 v[156:159], v169 offset:2080
	v_mfma_f32_16x16x32_bf16 v[86:89], v[34:37], v[62:65], v[86:89]
	ds_read_b128 v[120:123], v111 offset:2080
	v_mfma_f32_16x16x32_bf16 v[18:21], v[38:41], v[50:53], v[18:21]
	ds_read_b128 v[160:163], v169 offset:4128
	v_mfma_f32_16x16x32_bf16 v[82:85], v[38:41], v[54:57], v[82:85]
	ds_read_b128 v[164:167], v169 offset:6176
	v_mfma_f32_16x16x32_bf16 v[14:17], v[38:41], v[58:61], v[14:17]
	ds_read_b128 v[124:127], v111 offset:4128
	v_mfma_f32_16x16x32_bf16 v[78:81], v[38:41], v[62:65], v[78:81]
	ds_read_b128 v[148:151], v111 offset:6176
	v_mfma_f32_16x16x32_bf16 v[10:13], v[42:45], v[50:53], v[10:13]
	v_mfma_f32_16x16x32_bf16 v[74:77], v[42:45], v[54:57], v[74:77]
	v_mfma_f32_16x16x32_bf16 v[6:9], v[42:45], v[58:61], v[6:9]
	v_mfma_f32_16x16x32_bf16 v[70:73], v[42:45], v[62:65], v[70:73]
	v_mfma_f32_16x16x32_bf16 v[2:5], v[46:49], v[50:53], v[2:5]
	v_mfma_f32_16x16x32_bf16 v[66:69], v[46:49], v[54:57], v[66:69]
	v_mfma_f32_16x16x32_bf16 v[30:33], v[46:49], v[58:61], v[30:33]
	v_mfma_f32_16x16x32_bf16 v[94:97], v[46:49], v[62:65], v[94:97]
	s_waitcnt lgkmcnt(0)
	s_waitcnt vmcnt(0)
	s_barrier
	v_mfma_f32_16x16x32_bf16 v[26:29], v[116:119], v[152:155], v[26:29]
	ds_read_b128 v[34:37], v100 offset:32800
	v_mfma_f32_16x16x32_bf16 v[90:93], v[116:119], v[156:159], v[90:93]
	ds_read_b128 v[50:53], v168 offset:32800
	v_mfma_f32_16x16x32_bf16 v[22:25], v[116:119], v[160:163], v[22:25]
	ds_read_b128 v[54:57], v168 offset:34848
	v_mfma_f32_16x16x32_bf16 v[86:89], v[116:119], v[164:167], v[86:89]
	ds_read_b128 v[38:41], v100 offset:34848
	v_mfma_f32_16x16x32_bf16 v[18:21], v[120:123], v[152:155], v[18:21]
	ds_read_b128 v[58:61], v168 offset:36896
	v_mfma_f32_16x16x32_bf16 v[82:85], v[120:123], v[156:159], v[82:85]
	ds_read_b128 v[62:65], v168 offset:38944
	v_mfma_f32_16x16x32_bf16 v[14:17], v[120:123], v[160:163], v[14:17]
	ds_read_b128 v[42:45], v100 offset:36896
	v_mfma_f32_16x16x32_bf16 v[78:81], v[120:123], v[164:167], v[78:81]
	ds_read_b128 v[46:49], v100 offset:38944
	v_mfma_f32_16x16x32_bf16 v[10:13], v[124:127], v[152:155], v[10:13]
	v_mfma_f32_16x16x32_bf16 v[74:77], v[124:127], v[156:159], v[74:77]
	v_mfma_f32_16x16x32_bf16 v[6:9], v[124:127], v[160:163], v[6:9]
	v_mfma_f32_16x16x32_bf16 v[70:73], v[124:127], v[164:167], v[70:73]
	v_mfma_f32_16x16x32_bf16 v[2:5], v[148:151], v[152:155], v[2:5]
	v_mfma_f32_16x16x32_bf16 v[66:69], v[148:151], v[156:159], v[66:69]
	v_mfma_f32_16x16x32_bf16 v[30:33], v[148:151], v[160:163], v[30:33]
	v_mfma_f32_16x16x32_bf16 v[94:97], v[148:151], v[164:167], v[94:97]
	s_waitcnt lgkmcnt(0)
	v_mfma_f32_16x16x32_bf16 v[26:29], v[34:37], v[50:53], v[26:29]
	ds_read_b128 v[116:119], v111 offset:32800
	v_mfma_f32_16x16x32_bf16 v[90:93], v[34:37], v[54:57], v[90:93]
	ds_read_b128 v[152:155], v169 offset:32800
	v_mfma_f32_16x16x32_bf16 v[22:25], v[34:37], v[58:61], v[22:25]
	ds_read_b128 v[156:159], v169 offset:34848
	v_mfma_f32_16x16x32_bf16 v[86:89], v[34:37], v[62:65], v[86:89]
	ds_read_b128 v[120:123], v111 offset:34848
	v_mfma_f32_16x16x32_bf16 v[18:21], v[38:41], v[50:53], v[18:21]
	ds_read_b128 v[160:163], v169 offset:36896
	v_mfma_f32_16x16x32_bf16 v[82:85], v[38:41], v[54:57], v[82:85]
	ds_read_b128 v[164:167], v169 offset:38944
	v_mfma_f32_16x16x32_bf16 v[14:17], v[38:41], v[58:61], v[14:17]
	ds_read_b128 v[124:127], v111 offset:36896
	v_mfma_f32_16x16x32_bf16 v[78:81], v[38:41], v[62:65], v[78:81]
	ds_read_b128 v[148:151], v111 offset:38944
	v_mfma_f32_16x16x32_bf16 v[10:13], v[42:45], v[50:53], v[10:13]
	v_mfma_f32_16x16x32_bf16 v[74:77], v[42:45], v[54:57], v[74:77]
	v_mfma_f32_16x16x32_bf16 v[6:9], v[42:45], v[58:61], v[6:9]
	v_mfma_f32_16x16x32_bf16 v[70:73], v[42:45], v[62:65], v[70:73]
	v_mfma_f32_16x16x32_bf16 v[2:5], v[46:49], v[50:53], v[2:5]
	v_mfma_f32_16x16x32_bf16 v[66:69], v[46:49], v[54:57], v[66:69]
	v_mfma_f32_16x16x32_bf16 v[30:33], v[46:49], v[58:61], v[30:33]
	v_mfma_f32_16x16x32_bf16 v[94:97], v[46:49], v[62:65], v[94:97]
	s_waitcnt lgkmcnt(0)
	v_mfma_f32_16x16x32_bf16 v[26:29], v[116:119], v[152:155], v[26:29]
	v_mfma_f32_16x16x32_bf16 v[90:93], v[116:119], v[156:159], v[90:93]
	v_mfma_f32_16x16x32_bf16 v[22:25], v[116:119], v[160:163], v[22:25]
	v_mfma_f32_16x16x32_bf16 v[86:89], v[116:119], v[164:167], v[86:89]
	v_mfma_f32_16x16x32_bf16 v[18:21], v[120:123], v[152:155], v[18:21]
	v_mfma_f32_16x16x32_bf16 v[82:85], v[120:123], v[156:159], v[82:85]
	v_mfma_f32_16x16x32_bf16 v[14:17], v[120:123], v[160:163], v[14:17]
	v_mfma_f32_16x16x32_bf16 v[78:81], v[120:123], v[164:167], v[78:81]
	v_mfma_f32_16x16x32_bf16 v[10:13], v[124:127], v[152:155], v[10:13]
	v_mfma_f32_16x16x32_bf16 v[74:77], v[124:127], v[156:159], v[74:77]
	v_mfma_f32_16x16x32_bf16 v[6:9], v[124:127], v[160:163], v[6:9]
	v_mfma_f32_16x16x32_bf16 v[70:73], v[124:127], v[164:167], v[70:73]
	v_mfma_f32_16x16x32_bf16 v[2:5], v[148:151], v[152:155], v[2:5]
	v_mfma_f32_16x16x32_bf16 v[66:69], v[148:151], v[156:159], v[66:69]
	v_mfma_f32_16x16x32_bf16 v[30:33], v[148:151], v[160:163], v[30:33]
	v_mfma_f32_16x16x32_bf16 v[94:97], v[148:151], v[164:167], v[94:97]
	s_lshl_b32 s4, s10, 1
	s_barrier
	ds_write2_b32 v129, v26, v90 offset1:16
	ds_write2_b32 v129, v27, v91 offset0:132 offset1:148
	ds_write2_b32 v138, v28, v92 offset0:8 offset1:24
	ds_write2_b32 v138, v29, v93 offset0:140 offset1:156
	ds_write2_b32 v129, v22, v86 offset0:32 offset1:48
	ds_write2_b32 v129, v23, v87 offset0:164 offset1:180
	ds_write2_b32 v138, v24, v88 offset0:40 offset1:56
	ds_write2_b32 v138, v25, v89 offset0:172 offset1:188
	ds_write2_b32 v139, v18, v82 offset0:64 offset1:80
	ds_write2_b32 v139, v19, v83 offset0:196 offset1:212
	ds_write2_b32 v140, v20, v84 offset0:72 offset1:88
	ds_write2_b32 v140, v21, v85 offset0:204 offset1:220
	ds_write2_b32 v139, v14, v78 offset0:96 offset1:112
	ds_write2_b32 v139, v15, v79 offset0:228 offset1:244
	ds_write2_b32 v140, v16, v80 offset0:104 offset1:120
	ds_write2_b32 v140, v17, v81 offset0:236 offset1:252
	ds_write2_b32 v141, v10, v74 offset0:128 offset1:144
	ds_write2_b32 v142, v11, v75 offset0:4 offset1:20
	ds_write2_b32 v142, v12, v76 offset0:136 offset1:152
	ds_write2_b32 v143, v13, v77 offset0:12 offset1:28
	ds_write2_b32 v141, v6, v70 offset0:160 offset1:176
	ds_write2_b32 v142, v7, v71 offset0:36 offset1:52
	ds_write2_b32 v142, v8, v72 offset0:168 offset1:184
	ds_write2_b32 v143, v9, v73 offset0:44 offset1:60
	ds_write2_b32 v144, v2, v66 offset0:192 offset1:208
	ds_write2_b32 v145, v3, v67 offset0:68 offset1:84
	ds_write2_b32 v145, v4, v68 offset0:200 offset1:216
	ds_write2_b32 v146, v5, v69 offset0:76 offset1:92
	ds_write2_b32 v144, v30, v94 offset0:224 offset1:240
	ds_write2_b32 v145, v31, v95 offset0:100 offset1:116
	ds_write2_b32 v145, v32, v96 offset0:232 offset1:248
	ds_write2_b32 v146, v33, v97 offset0:108 offset1:124
	v_lshl_add_u64 v[2:3], v[106:107], 0, s[4:5]
	s_lshl_b32 s4, s34, 10
	s_mul_hi_u32 s10, s34, 0x15555556
	v_or_b32_e32 v4, s4, v134
	s_mulk_i32 s10, 0x3000
	v_or_b32_e32 v5, s4, v132
	v_subrev_u32_e32 v4, s10, v4
	v_subrev_u32_e32 v100, s10, v5
	s_mov_b32 s4, 0
	s_waitcnt lgkmcnt(0)
	s_barrier

.LBB0_634:
	s_and_b32 s31, s30, 0xff
	s_mul_i32 s4, s31, 0xab
	s_lshr_b32 s33, s4, 11
	s_mul_i32 s4, s33, 12
	s_sub_i32 s4, s30, s4
	s_and_b32 s4, s4, 0xff
	s_lshl_b32 s4, s4, 21
	s_or_b32 s4, s4, s23
	s_add_u32 s14, s18, s4
	s_addc_u32 s15, s19, 0
	s_lshl_b32 s4, s33, 18
	s_add_u32 s16, s20, s4
	s_addc_u32 s17, s21, 0
	v_and_b32_e32 v162, 15, v0
	v_bfe_u32 v163, v0, 4, 2
	v_and_b32_e32 v109, 7, v162
	v_xor_b32_e32 v163, v163, v109
	v_lshlrev_b32_e32 v163, 4, v163
	v_lshl_or_b32 v163, v162, 7, v163
	v_bfe_u32 v162, v0, 7, 1
	v_lshl_or_b32 v100, v162, 13, v163
	v_bfe_u32 v162, v0, 6, 1
	v_lshl_or_b32 v156, v162, 13, v163
	v_or_b32_e32 v156, 0x4000, v156
	v_xor_b32_e32 v109, 64, v100
	v_xor_b32_e32 v157, 64, v156
	v_bfe_u32 v162, v0, 3, 3
	v_and_b32_e32 v163, 7, v0
	v_xor_b32_e32 v163, v163, v162
	v_lshlrev_b32_e32 v163, 4, v163
	v_lshl_or_b32 v163, v162, 11, v163
	v_lshrrev_b32_e32 v162, 6, v0
	v_and_b32_e32 v162, 3, v162
	v_lshl_or_b32 v158, v162, 16, v163
	v_add_u32_e32 v159, 0x3c00, v158
	v_add_u32_e32 v160, 0x7800, v158
	v_add_u32_e32 v161, 0xb400, v158
	v_lshlrev_b32_e32 v162, 12, v162
	s_nop 0
	v_readfirstlane_b32 s35, v162
	s_add_u32 s35, s35, 32
	v_mov_b32_e32 v94, 0
	v_mov_b32_e32 v95, 0
	v_mov_b32_e32 v96, 0
	v_mov_b32_e32 v97, 0
	v_mov_b32_e32 v90, 0
	v_mov_b32_e32 v91, 0
	v_mov_b32_e32 v92, 0
	v_mov_b32_e32 v93, 0
	v_mov_b32_e32 v82, 0
	v_mov_b32_e32 v83, 0
	v_mov_b32_e32 v84, 0
	v_mov_b32_e32 v85, 0
	v_mov_b32_e32 v78, 0
	v_mov_b32_e32 v79, 0
	v_mov_b32_e32 v80, 0
	v_mov_b32_e32 v81, 0
	v_mov_b32_e32 v74, 0
	v_mov_b32_e32 v75, 0
	v_mov_b32_e32 v76, 0
	v_mov_b32_e32 v77, 0
	v_mov_b32_e32 v70, 0
	v_mov_b32_e32 v71, 0
	v_mov_b32_e32 v72, 0
	v_mov_b32_e32 v73, 0
	v_mov_b32_e32 v66, 0
	v_mov_b32_e32 v67, 0
	v_mov_b32_e32 v68, 0
	v_mov_b32_e32 v69, 0
	v_mov_b32_e32 v62, 0
	v_mov_b32_e32 v63, 0
	v_mov_b32_e32 v64, 0
	v_mov_b32_e32 v65, 0
	v_mov_b32_e32 v34, 0
	v_mov_b32_e32 v35, 0
	v_mov_b32_e32 v36, 0
	v_mov_b32_e32 v37, 0
	v_mov_b32_e32 v26, 0
	v_mov_b32_e32 v27, 0
	v_mov_b32_e32 v28, 0
	v_mov_b32_e32 v29, 0
	v_mov_b32_e32 v18, 0
	v_mov_b32_e32 v19, 0
	v_mov_b32_e32 v20, 0
	v_mov_b32_e32 v21, 0
	v_mov_b32_e32 v14, 0
	v_mov_b32_e32 v15, 0
	v_mov_b32_e32 v16, 0
	v_mov_b32_e32 v17, 0
	v_mov_b32_e32 v10, 0
	v_mov_b32_e32 v11, 0
	v_mov_b32_e32 v12, 0
	v_mov_b32_e32 v13, 0
	v_mov_b32_e32 v6, 0
	v_mov_b32_e32 v7, 0
	v_mov_b32_e32 v8, 0
	v_mov_b32_e32 v9, 0
	v_mov_b32_e32 v2, 0
	v_mov_b32_e32 v3, 0
	v_mov_b32_e32 v4, 0
	v_mov_b32_e32 v5, 0
	v_mov_b32_e32 v86, 0
	v_mov_b32_e32 v87, 0
	v_mov_b32_e32 v88, 0
	v_mov_b32_e32 v89, 0
	v_mov_b32_e32 v110, 0
	v_mov_b32_e32 v111, 0
	v_mov_b32_e32 v112, 0
	v_mov_b32_e32 v113, 0
	v_mov_b32_e32 v114, 0
	v_mov_b32_e32 v115, 0
	v_mov_b32_e32 v116, 0
	v_mov_b32_e32 v117, 0
	v_mov_b32_e32 v118, 0
	v_mov_b32_e32 v119, 0
	v_mov_b32_e32 v120, 0
	v_mov_b32_e32 v121, 0
	v_mov_b32_e32 v136, 0
	v_mov_b32_e32 v137, 0
	v_mov_b32_e32 v138, 0
	v_mov_b32_e32 v139, 0
	v_mov_b32_e32 v140, 0
	v_mov_b32_e32 v141, 0
	v_mov_b32_e32 v142, 0
	v_mov_b32_e32 v143, 0
	v_mov_b32_e32 v144, 0
	v_mov_b32_e32 v145, 0
	v_mov_b32_e32 v146, 0
	v_mov_b32_e32 v147, 0
	v_mov_b32_e32 v148, 0
	v_mov_b32_e32 v149, 0
	v_mov_b32_e32 v150, 0
	v_mov_b32_e32 v151, 0
	v_mov_b32_e32 v152, 0
	v_mov_b32_e32 v153, 0
	v_mov_b32_e32 v154, 0
	v_mov_b32_e32 v155, 0
	s_waitcnt lgkmcnt(0)
	s_barrier
	s_add_u32 m0, s35, 0
	s_nop 0
	global_load_lds_dwordx4 v158, s[14:15] offset:0
	global_load_lds_dwordx4 v159, s[14:15] offset:1024
	global_load_lds_dwordx4 v160, s[14:15] offset:2048
	global_load_lds_dwordx4 v161, s[14:15] offset:3072
	s_add_u32 m0, s35, 16384
	s_nop 0
	global_load_lds_dwordx4 v158, s[16:17] offset:0
	global_load_lds_dwordx4 v159, s[16:17] offset:1024
	global_load_lds_dwordx4 v160, s[16:17] offset:2048
	global_load_lds_dwordx4 v161, s[16:17] offset:3072
	s_add_u32 s14, s14, 0x80
	s_addc_u32 s15, s15, 0
	s_add_u32 s16, s16, 0x80
	s_addc_u32 s17, s17, 0
	s_mov_b32 s34, 0
	s_waitcnt vmcnt(0)
.Lk_outl0_loop:
	s_barrier
	s_add_u32 m0, s35, 32768
	v_mfma_f32_16x16x32_bf16 v[94:97], v[110:113], v[140:143], v[94:97]
	ds_read_b128 v[22:25], v100 offset:32
	global_load_lds_dwordx4 v158, s[14:15] offset:0
	v_mfma_f32_16x16x32_bf16 v[90:93], v[110:113], v[144:147], v[90:93]
	ds_read_b128 v[46:49], v156 offset:32
	global_load_lds_dwordx4 v159, s[14:15] offset:1024
	v_mfma_f32_16x16x32_bf16 v[82:85], v[110:113], v[148:151], v[82:85]
	ds_read_b128 v[50:53], v156 offset:2080
	global_load_lds_dwordx4 v160, s[14:15] offset:2048
	v_mfma_f32_16x16x32_bf16 v[78:81], v[110:113], v[152:155], v[78:81]
	ds_read_b128 v[30:33], v100 offset:2080
	global_load_lds_dwordx4 v161, s[14:15] offset:3072
	s_add_u32 m0, s35, 49152
	v_mfma_f32_16x16x32_bf16 v[74:77], v[114:117], v[140:143], v[74:77]
	ds_read_b128 v[54:57], v156 offset:4128
	global_load_lds_dwordx4 v158, s[16:17] offset:0
	v_mfma_f32_16x16x32_bf16 v[70:73], v[114:117], v[144:147], v[70:73]
	ds_read_b128 v[58:61], v156 offset:6176
	global_load_lds_dwordx4 v159, s[16:17] offset:1024
	v_mfma_f32_16x16x32_bf16 v[66:69], v[114:117], v[148:151], v[66:69]
	ds_read_b128 v[38:41], v100 offset:4128
	global_load_lds_dwordx4 v160, s[16:17] offset:2048
	v_mfma_f32_16x16x32_bf16 v[62:65], v[114:117], v[152:155], v[62:65]
	ds_read_b128 v[42:45], v100 offset:6176
	global_load_lds_dwordx4 v161, s[16:17] offset:3072
	v_mfma_f32_16x16x32_bf16 v[34:37], v[118:121], v[140:143], v[34:37]
	v_mfma_f32_16x16x32_bf16 v[26:29], v[118:121], v[144:147], v[26:29]
	v_mfma_f32_16x16x32_bf16 v[18:21], v[118:121], v[148:151], v[18:21]
	v_mfma_f32_16x16x32_bf16 v[14:17], v[118:121], v[152:155], v[14:17]
	v_mfma_f32_16x16x32_bf16 v[10:13], v[136:139], v[140:143], v[10:13]
	v_mfma_f32_16x16x32_bf16 v[6:9], v[136:139], v[144:147], v[6:9]
	v_mfma_f32_16x16x32_bf16 v[2:5], v[136:139], v[148:151], v[2:5]
	v_mfma_f32_16x16x32_bf16 v[86:89], v[136:139], v[152:155], v[86:89]
	s_add_u32 s14, s14, 0x80
	s_addc_u32 s15, s15, 0
	s_add_u32 s16, s16, 0x80
	s_addc_u32 s17, s17, 0
	s_waitcnt lgkmcnt(0)
	v_mfma_f32_16x16x32_bf16 v[94:97], v[22:25], v[46:49], v[94:97]
	ds_read_b128 v[110:113], v109 offset:32
	v_mfma_f32_16x16x32_bf16 v[90:93], v[22:25], v[50:53], v[90:93]
	ds_read_b128 v[140:143], v157 offset:32
	v_mfma_f32_16x16x32_bf16 v[82:85], v[22:25], v[54:57], v[82:85]
	ds_read_b128 v[144:147], v157 offset:2080
	v_mfma_f32_16x16x32_bf16 v[78:81], v[22:25], v[58:61], v[78:81]
	ds_read_b128 v[114:117], v109 offset:2080
	v_mfma_f32_16x16x32_bf16 v[74:77], v[30:33], v[46:49], v[74:77]
	ds_read_b128 v[148:151], v157 offset:4128
	v_mfma_f32_16x16x32_bf16 v[70:73], v[30:33], v[50:53], v[70:73]
	ds_read_b128 v[152:155], v157 offset:6176
	v_mfma_f32_16x16x32_bf16 v[66:69], v[30:33], v[54:57], v[66:69]
	ds_read_b128 v[118:121], v109 offset:4128
	v_mfma_f32_16x16x32_bf16 v[62:65], v[30:33], v[58:61], v[62:65]
	ds_read_b128 v[136:139], v109 offset:6176
	v_mfma_f32_16x16x32_bf16 v[34:37], v[38:41], v[46:49], v[34:37]
	v_mfma_f32_16x16x32_bf16 v[26:29], v[38:41], v[50:53], v[26:29]
	v_mfma_f32_16x16x32_bf16 v[18:21], v[38:41], v[54:57], v[18:21]
	v_mfma_f32_16x16x32_bf16 v[14:17], v[38:41], v[58:61], v[14:17]
	v_mfma_f32_16x16x32_bf16 v[10:13], v[42:45], v[46:49], v[10:13]
	v_mfma_f32_16x16x32_bf16 v[6:9], v[42:45], v[50:53], v[6:9]
	v_mfma_f32_16x16x32_bf16 v[2:5], v[42:45], v[54:57], v[2:5]
	v_mfma_f32_16x16x32_bf16 v[86:89], v[42:45], v[58:61], v[86:89]
	s_waitcnt lgkmcnt(0)
	s_waitcnt vmcnt(0)
	s_barrier
	s_add_u32 m0, s35, 0
	v_mfma_f32_16x16x32_bf16 v[94:97], v[110:113], v[140:143], v[94:97]
	ds_read_b128 v[22:25], v100 offset:32800
	global_load_lds_dwordx4 v158, s[14:15] offset:0
	v_mfma_f32_16x16x32_bf16 v[90:93], v[110:113], v[144:147], v[90:93]
	ds_read_b128 v[46:49], v156 offset:32800
	global_load_lds_dwordx4 v159, s[14:15] offset:1024
	v_mfma_f32_16x16x32_bf16 v[82:85], v[110:113], v[148:151], v[82:85]
	ds_read_b128 v[50:53], v156 offset:34848
	global_load_lds_dwordx4 v160, s[14:15] offset:2048
	v_mfma_f32_16x16x32_bf16 v[78:81], v[110:113], v[152:155], v[78:81]
	ds_read_b128 v[30:33], v100 offset:34848
	global_load_lds_dwordx4 v161, s[14:15] offset:3072
	s_add_u32 m0, s35, 16384
	v_mfma_f32_16x16x32_bf16 v[74:77], v[114:117], v[140:143], v[74:77]
	ds_read_b128 v[54:57], v156 offset:36896
	global_load_lds_dwordx4 v158, s[16:17] offset:0
	v_mfma_f32_16x16x32_bf16 v[70:73], v[114:117], v[144:147], v[70:73]
	ds_read_b128 v[58:61], v156 offset:38944
	global_load_lds_dwordx4 v159, s[16:17] offset:1024
	v_mfma_f32_16x16x32_bf16 v[66:69], v[114:117], v[148:151], v[66:69]
	ds_read_b128 v[38:41], v100 offset:36896
	global_load_lds_dwordx4 v160, s[16:17] offset:2048
	v_mfma_f32_16x16x32_bf16 v[62:65], v[114:117], v[152:155], v[62:65]
	ds_read_b128 v[42:45], v100 offset:38944
	global_load_lds_dwordx4 v161, s[16:17] offset:3072
	v_mfma_f32_16x16x32_bf16 v[34:37], v[118:121], v[140:143], v[34:37]
	v_mfma_f32_16x16x32_bf16 v[26:29], v[118:121], v[144:147], v[26:29]
	v_mfma_f32_16x16x32_bf16 v[18:21], v[118:121], v[148:151], v[18:21]
	v_mfma_f32_16x16x32_bf16 v[14:17], v[118:121], v[152:155], v[14:17]
	v_mfma_f32_16x16x32_bf16 v[10:13], v[136:139], v[140:143], v[10:13]
	v_mfma_f32_16x16x32_bf16 v[6:9], v[136:139], v[144:147], v[6:9]
	v_mfma_f32_16x16x32_bf16 v[2:5], v[136:139], v[148:151], v[2:5]
	v_mfma_f32_16x16x32_bf16 v[86:89], v[136:139], v[152:155], v[86:89]
	s_add_u32 s14, s14, 0x80
	s_addc_u32 s15, s15, 0
	s_add_u32 s16, s16, 0x80
	s_addc_u32 s17, s17, 0
	s_waitcnt lgkmcnt(0)
	v_mfma_f32_16x16x32_bf16 v[94:97], v[22:25], v[46:49], v[94:97]
	ds_read_b128 v[110:113], v109 offset:32800
	v_mfma_f32_16x16x32_bf16 v[90:93], v[22:25], v[50:53], v[90:93]
	ds_read_b128 v[140:143], v157 offset:32800
	v_mfma_f32_16x16x32_bf16 v[82:85], v[22:25], v[54:57], v[82:85]
	ds_read_b128 v[144:147], v157 offset:34848
	v_mfma_f32_16x16x32_bf16 v[78:81], v[22:25], v[58:61], v[78:81]
	ds_read_b128 v[114:117], v109 offset:34848
	v_mfma_f32_16x16x32_bf16 v[74:77], v[30:33], v[46:49], v[74:77]
	ds_read_b128 v[148:151], v157 offset:36896
	v_mfma_f32_16x16x32_bf16 v[70:73], v[30:33], v[50:53], v[70:73]
	ds_read_b128 v[152:155], v157 offset:38944
	v_mfma_f32_16x16x32_bf16 v[66:69], v[30:33], v[54:57], v[66:69]
	ds_read_b128 v[118:121], v109 offset:36896
	v_mfma_f32_16x16x32_bf16 v[62:65], v[30:33], v[58:61], v[62:65]
	ds_read_b128 v[136:139], v109 offset:38944
	v_mfma_f32_16x16x32_bf16 v[34:37], v[38:41], v[46:49], v[34:37]
	v_mfma_f32_16x16x32_bf16 v[26:29], v[38:41], v[50:53], v[26:29]
	v_mfma_f32_16x16x32_bf16 v[18:21], v[38:41], v[54:57], v[18:21]
	v_mfma_f32_16x16x32_bf16 v[14:17], v[38:41], v[58:61], v[14:17]
	v_mfma_f32_16x16x32_bf16 v[10:13], v[42:45], v[46:49], v[10:13]
	v_mfma_f32_16x16x32_bf16 v[6:9], v[42:45], v[50:53], v[6:9]
	v_mfma_f32_16x16x32_bf16 v[2:5], v[42:45], v[54:57], v[2:5]
	v_mfma_f32_16x16x32_bf16 v[86:89], v[42:45], v[58:61], v[86:89]
	s_waitcnt lgkmcnt(0)
	s_waitcnt vmcnt(0)
	s_add_u32 s34, s34, 1
	s_cmp_lt_u32 s34, 7
	s_cbranch_scc1 .Lk_outl0_loop
	s_barrier
	s_add_u32 m0, s35, 32768
	v_mfma_f32_16x16x32_bf16 v[94:97], v[110:113], v[140:143], v[94:97]
	ds_read_b128 v[22:25], v100 offset:32
	global_load_lds_dwordx4 v158, s[14:15] offset:0
	v_mfma_f32_16x16x32_bf16 v[90:93], v[110:113], v[144:147], v[90:93]
	ds_read_b128 v[46:49], v156 offset:32
	global_load_lds_dwordx4 v159, s[14:15] offset:1024
	v_mfma_f32_16x16x32_bf16 v[82:85], v[110:113], v[148:151], v[82:85]
	ds_read_b128 v[50:53], v156 offset:2080
	global_load_lds_dwordx4 v160, s[14:15] offset:2048
	v_mfma_f32_16x16x32_bf16 v[78:81], v[110:113], v[152:155], v[78:81]
	ds_read_b128 v[30:33], v100 offset:2080
	global_load_lds_dwordx4 v161, s[14:15] offset:3072
	s_add_u32 m0, s35, 49152
	v_mfma_f32_16x16x32_bf16 v[74:77], v[114:117], v[140:143], v[74:77]
	ds_read_b128 v[54:57], v156 offset:4128
	global_load_lds_dwordx4 v158, s[16:17] offset:0
	v_mfma_f32_16x16x32_bf16 v[70:73], v[114:117], v[144:147], v[70:73]
	ds_read_b128 v[58:61], v156 offset:6176
	global_load_lds_dwordx4 v159, s[16:17] offset:1024
	v_mfma_f32_16x16x32_bf16 v[66:69], v[114:117], v[148:151], v[66:69]
	ds_read_b128 v[38:41], v100 offset:4128
	global_load_lds_dwordx4 v160, s[16:17] offset:2048
	v_mfma_f32_16x16x32_bf16 v[62:65], v[114:117], v[152:155], v[62:65]
	ds_read_b128 v[42:45], v100 offset:6176
	global_load_lds_dwordx4 v161, s[16:17] offset:3072
	v_mfma_f32_16x16x32_bf16 v[34:37], v[118:121], v[140:143], v[34:37]
	v_mfma_f32_16x16x32_bf16 v[26:29], v[118:121], v[144:147], v[26:29]
	v_mfma_f32_16x16x32_bf16 v[18:21], v[118:121], v[148:151], v[18:21]
	v_mfma_f32_16x16x32_bf16 v[14:17], v[118:121], v[152:155], v[14:17]
	v_mfma_f32_16x16x32_bf16 v[10:13], v[136:139], v[140:143], v[10:13]
	v_mfma_f32_16x16x32_bf16 v[6:9], v[136:139], v[144:147], v[6:9]
	v_mfma_f32_16x16x32_bf16 v[2:5], v[136:139], v[148:151], v[2:5]
	v_mfma_f32_16x16x32_bf16 v[86:89], v[136:139], v[152:155], v[86:89]
	s_add_u32 s14, s14, 0x80
	s_addc_u32 s15, s15, 0
	s_add_u32 s16, s16, 0x80
	s_addc_u32 s17, s17, 0
	s_waitcnt lgkmcnt(0)
	v_mfma_f32_16x16x32_bf16 v[94:97], v[22:25], v[46:49], v[94:97]
	ds_read_b128 v[110:113], v109 offset:32
	v_mfma_f32_16x16x32_bf16 v[90:93], v[22:25], v[50:53], v[90:93]
	ds_read_b128 v[140:143], v157 offset:32
	v_mfma_f32_16x16x32_bf16 v[82:85], v[22:25], v[54:57], v[82:85]
	ds_read_b128 v[144:147], v157 offset:2080
	v_mfma_f32_16x16x32_bf16 v[78:81], v[22:25], v[58:61], v[78:81]
	ds_read_b128 v[114:117], v109 offset:2080
	v_mfma_f32_16x16x32_bf16 v[74:77], v[30:33], v[46:49], v[74:77]
	ds_read_b128 v[148:151], v157 offset:4128
	v_mfma_f32_16x16x32_bf16 v[70:73], v[30:33], v[50:53], v[70:73]
	ds_read_b128 v[152:155], v157 offset:6176
	v_mfma_f32_16x16x32_bf16 v[66:69], v[30:33], v[54:57], v[66:69]
	ds_read_b128 v[118:121], v109 offset:4128
	v_mfma_f32_16x16x32_bf16 v[62:65], v[30:33], v[58:61], v[62:65]
	ds_read_b128 v[136:139], v109 offset:6176
	v_mfma_f32_16x16x32_bf16 v[34:37], v[38:41], v[46:49], v[34:37]
	v_mfma_f32_16x16x32_bf16 v[26:29], v[38:41], v[50:53], v[26:29]
	v_mfma_f32_16x16x32_bf16 v[18:21], v[38:41], v[54:57], v[18:21]
	v_mfma_f32_16x16x32_bf16 v[14:17], v[38:41], v[58:61], v[14:17]
	v_mfma_f32_16x16x32_bf16 v[10:13], v[42:45], v[46:49], v[10:13]
	v_mfma_f32_16x16x32_bf16 v[6:9], v[42:45], v[50:53], v[6:9]
	v_mfma_f32_16x16x32_bf16 v[2:5], v[42:45], v[54:57], v[2:5]
	v_mfma_f32_16x16x32_bf16 v[86:89], v[42:45], v[58:61], v[86:89]
	s_waitcnt lgkmcnt(0)
	s_waitcnt vmcnt(0)
	s_barrier
	v_mfma_f32_16x16x32_bf16 v[94:97], v[110:113], v[140:143], v[94:97]
	ds_read_b128 v[22:25], v100 offset:32800
	v_mfma_f32_16x16x32_bf16 v[90:93], v[110:113], v[144:147], v[90:93]
	ds_read_b128 v[46:49], v156 offset:32800
	v_mfma_f32_16x16x32_bf16 v[82:85], v[110:113], v[148:151], v[82:85]
	ds_read_b128 v[50:53], v156 offset:34848
	v_mfma_f32_16x16x32_bf16 v[78:81], v[110:113], v[152:155], v[78:81]
	ds_read_b128 v[30:33], v100 offset:34848
	v_mfma_f32_16x16x32_bf16 v[74:77], v[114:117], v[140:143], v[74:77]
	ds_read_b128 v[54:57], v156 offset:36896
	v_mfma_f32_16x16x32_bf16 v[70:73], v[114:117], v[144:147], v[70:73]
	ds_read_b128 v[58:61], v156 offset:38944
	v_mfma_f32_16x16x32_bf16 v[66:69], v[114:117], v[148:151], v[66:69]
	ds_read_b128 v[38:41], v100 offset:36896
	v_mfma_f32_16x16x32_bf16 v[62:65], v[114:117], v[152:155], v[62:65]
	ds_read_b128 v[42:45], v100 offset:38944
	v_mfma_f32_16x16x32_bf16 v[34:37], v[118:121], v[140:143], v[34:37]
	v_mfma_f32_16x16x32_bf16 v[26:29], v[118:121], v[144:147], v[26:29]
	v_mfma_f32_16x16x32_bf16 v[18:21], v[118:121], v[148:151], v[18:21]
	v_mfma_f32_16x16x32_bf16 v[14:17], v[118:121], v[152:155], v[14:17]
	v_mfma_f32_16x16x32_bf16 v[10:13], v[136:139], v[140:143], v[10:13]
	v_mfma_f32_16x16x32_bf16 v[6:9], v[136:139], v[144:147], v[6:9]
	v_mfma_f32_16x16x32_bf16 v[2:5], v[136:139], v[148:151], v[2:5]
	v_mfma_f32_16x16x32_bf16 v[86:89], v[136:139], v[152:155], v[86:89]
	s_waitcnt lgkmcnt(0)
	v_mfma_f32_16x16x32_bf16 v[94:97], v[22:25], v[46:49], v[94:97]
	ds_read_b128 v[110:113], v109 offset:32800
	v_mfma_f32_16x16x32_bf16 v[90:93], v[22:25], v[50:53], v[90:93]
	ds_read_b128 v[140:143], v157 offset:32800
	v_mfma_f32_16x16x32_bf16 v[82:85], v[22:25], v[54:57], v[82:85]
	ds_read_b128 v[144:147], v157 offset:34848
	v_mfma_f32_16x16x32_bf16 v[78:81], v[22:25], v[58:61], v[78:81]
	ds_read_b128 v[114:117], v109 offset:34848
	v_mfma_f32_16x16x32_bf16 v[74:77], v[30:33], v[46:49], v[74:77]
	ds_read_b128 v[148:151], v157 offset:36896
	v_mfma_f32_16x16x32_bf16 v[70:73], v[30:33], v[50:53], v[70:73]
	ds_read_b128 v[152:155], v157 offset:38944
	v_mfma_f32_16x16x32_bf16 v[66:69], v[30:33], v[54:57], v[66:69]
	ds_read_b128 v[118:121], v109 offset:36896
	v_mfma_f32_16x16x32_bf16 v[62:65], v[30:33], v[58:61], v[62:65]
	ds_read_b128 v[136:139], v109 offset:38944
	v_mfma_f32_16x16x32_bf16 v[34:37], v[38:41], v[46:49], v[34:37]
	v_mfma_f32_16x16x32_bf16 v[26:29], v[38:41], v[50:53], v[26:29]
	v_mfma_f32_16x16x32_bf16 v[18:21], v[38:41], v[54:57], v[18:21]
	v_mfma_f32_16x16x32_bf16 v[14:17], v[38:41], v[58:61], v[14:17]
	v_mfma_f32_16x16x32_bf16 v[10:13], v[42:45], v[46:49], v[10:13]
	v_mfma_f32_16x16x32_bf16 v[6:9], v[42:45], v[50:53], v[6:9]
	v_mfma_f32_16x16x32_bf16 v[2:5], v[42:45], v[54:57], v[2:5]
	v_mfma_f32_16x16x32_bf16 v[86:89], v[42:45], v[58:61], v[86:89]
	s_waitcnt lgkmcnt(0)
	v_mfma_f32_16x16x32_bf16 v[94:97], v[110:113], v[140:143], v[94:97]
	v_mfma_f32_16x16x32_bf16 v[90:93], v[110:113], v[144:147], v[90:93]
	v_mfma_f32_16x16x32_bf16 v[82:85], v[110:113], v[148:151], v[82:85]
	v_mfma_f32_16x16x32_bf16 v[78:81], v[110:113], v[152:155], v[78:81]
	v_mfma_f32_16x16x32_bf16 v[74:77], v[114:117], v[140:143], v[74:77]
	v_mfma_f32_16x16x32_bf16 v[70:73], v[114:117], v[144:147], v[70:73]
	v_mfma_f32_16x16x32_bf16 v[66:69], v[114:117], v[148:151], v[66:69]
	v_mfma_f32_16x16x32_bf16 v[62:65], v[114:117], v[152:155], v[62:65]
	v_mfma_f32_16x16x32_bf16 v[34:37], v[118:121], v[140:143], v[34:37]
	v_mfma_f32_16x16x32_bf16 v[26:29], v[118:121], v[144:147], v[26:29]
	v_mfma_f32_16x16x32_bf16 v[18:21], v[118:121], v[148:151], v[18:21]
	v_mfma_f32_16x16x32_bf16 v[14:17], v[118:121], v[152:155], v[14:17]
	v_mfma_f32_16x16x32_bf16 v[10:13], v[136:139], v[140:143], v[10:13]
	v_mfma_f32_16x16x32_bf16 v[6:9], v[136:139], v[144:147], v[6:9]
	v_mfma_f32_16x16x32_bf16 v[2:5], v[136:139], v[148:151], v[2:5]
	v_mfma_f32_16x16x32_bf16 v[86:89], v[136:139], v[152:155], v[86:89]
	s_waitcnt vmcnt(7)
	v_add_u32_e32 v22, 0x400, v123
	s_barrier
	ds_write2_b32 v123, v94, v90 offset1:16
	ds_write2_b32 v123, v95, v91 offset0:132 offset1:148
	ds_write2_b32 v22, v96, v92 offset0:8 offset1:24
	ds_write2_b32 v22, v97, v93 offset0:140 offset1:156
	ds_write2_b32 v123, v82, v78 offset0:32 offset1:48
	ds_write2_b32 v123, v83, v79 offset0:164 offset1:180
	ds_write2_b32 v22, v84, v80 offset0:40 offset1:56
	ds_write2_b32 v22, v85, v81 offset0:172 offset1:188
	v_add_u32_e32 v22, 0x2000, v123
	v_add_u32_e32 v23, 0x2400, v123
	ds_write2_b32 v22, v74, v70 offset0:64 offset1:80
	ds_write2_b32 v22, v75, v71 offset0:196 offset1:212
	ds_write2_b32 v23, v76, v72 offset0:72 offset1:88
	ds_write2_b32 v23, v77, v73 offset0:204 offset1:220
	ds_write2_b32 v22, v66, v62 offset0:96 offset1:112
	ds_write2_b32 v22, v67, v63 offset0:228 offset1:244
	ds_write2_b32 v23, v68, v64 offset0:104 offset1:120
	ds_write2_b32 v23, v69, v65 offset0:236 offset1:252
	v_add_u32_e32 v22, 0x4000, v123
	v_add_u32_e32 v23, 0x4400, v123
	v_add_u32_e32 v24, 0x4800, v123
	ds_write2_b32 v22, v34, v26 offset0:128 offset1:144
	ds_write2_b32 v23, v35, v27 offset0:4 offset1:20
	ds_write2_b32 v23, v36, v28 offset0:136 offset1:152
	ds_write2_b32 v24, v37, v29 offset0:12 offset1:28
	ds_write2_b32 v22, v18, v14 offset0:160 offset1:176
	ds_write2_b32 v23, v19, v15 offset0:36 offset1:52
	ds_write2_b32 v23, v20, v16 offset0:168 offset1:184
	ds_write2_b32 v24, v21, v17 offset0:44 offset1:60
	v_add_u32_e32 v14, 0x6000, v123
	ds_write2_b32 v14, v10, v6 offset0:192 offset1:208
	v_add_u32_e32 v6, 0x6400, v123
	ds_write2_b32 v6, v11, v7 offset0:68 offset1:84
	ds_write2_b32 v6, v12, v8 offset0:200 offset1:216
	v_add_u32_e32 v7, 0x6800, v123
	s_lshl_b32 s4, s33, 9
	ds_write2_b32 v7, v13, v9 offset0:76 offset1:92
	ds_write2_b32 v14, v2, v86 offset0:224 offset1:240
	ds_write2_b32 v6, v3, v87 offset0:100 offset1:116
	ds_write2_b32 v6, v4, v88 offset0:232 offset1:248
	ds_write2_b32 v7, v5, v89 offset0:108 offset1:124
	v_lshl_add_u64 v[2:3], v[102:103], 0, s[4:5]
	v_lshl_add_u64 v[4:5], v[104:105], 0, s[4:5]
	s_lshl_b32 s4, s31, 10
	s_mul_hi_u32 s14, s31, 0x15555556
	s_lshl_b32 s15, s33, 7
	v_or_b32_e32 v6, s4, v125
	s_mulk_i32 s14, 0x3000
	v_or_b32_e32 v7, s4, v127
	v_or_b32_e32 v8, s4, v129
	v_or_b32_e32 v9, s4, v133
	v_subrev_u32_e32 v6, s14, v6
	v_subrev_u32_e32 v7, s14, v7
	v_subrev_u32_e32 v8, s14, v8
	v_subrev_u32_e32 v9, s14, v9
	s_mov_b32 s14, 0
	s_lshl_b32 s4, s15, 2
	v_mov_b32_e32 v10, v132
	v_mov_b32_e32 v11, v128
	v_mov_b32_e32 v12, v126
	v_mov_b32_e32 v13, v124
	s_waitcnt lgkmcnt(0)
	s_barrier

.LBB0_721:
	s_cmp_gt_i32 s44, 8
	s_cselect_b64 s[2:3], -1, 0
	s_cmp_lt_i32 s45, 9
	s_cselect_b64 s[4:5], -1, 0
	s_or_b64 s[2:3], s[2:3], s[4:5]
	s_and_b64 vcc, exec, s[2:3]
	s_cbranch_vccnz .LBB0_779
	s_load_dword s18, s[0:1], 0xf0
	v_lshl_or_b32 v2, s66, 2, v131
	s_add_u32 s4, s0, 0xf0
	s_movk_i32 s2, 0x3000
	v_and_b32_e32 v1, 0x3ff, v0
	s_addc_u32 s5, s1, 0
	v_cmp_gt_i32_e32 vcc, s2, v2
	s_and_saveexec_b64 s[2:3], vcc
	s_cbranch_execz .LBB0_725
	s_load_dwordx4 s[52:55], s[0:1], 0x90
	v_and_b32_e32 v10, 63, v1
	v_lshlrev_b32_e32 v2, 4, v10
	v_lshlrev_b32_e32 v3, 3, v10
	v_xor_b32_e32 v4, 32, v10
	v_lshlrev_b32_e32 v4, 2, v4
	v_xor_b32_e32 v5, 16, v10
	v_lshlrev_b32_e32 v5, 2, v5
	v_xor_b32_e32 v6, 8, v10
	v_lshlrev_b32_e32 v6, 2, v6
	v_xor_b32_e32 v7, 4, v10
	v_lshlrev_b32_e32 v7, 2, v7
	v_xor_b32_e32 v8, 2, v10
	v_lshlrev_b32_e32 v8, 2, v8
	v_xor_b32_e32 v9, 1, v10
	v_lshlrev_b32_e32 v9, 2, v9
	v_lshrrev_b32_e32 v11, 6, v1
	s_nop 0
	v_readfirstlane_b32 s6, v11
	s_lshl_b32 s19, s66, 2
	s_add_u32 s6, s6, s19
	s_waitcnt lgkmcnt(0)
	s_lshl_b32 s7, s18, 2
	global_load_dwordx4 v[68:71], v2, s[52:53] offset:0
	global_load_dwordx4 v[100:103], v2, s[54:55] offset:0
	global_load_dwordx4 v[72:75], v2, s[52:53] offset:1024
	global_load_dwordx4 v[104:107], v2, s[54:55] offset:1024
	global_load_dwordx4 v[76:79], v2, s[52:53] offset:2048
	global_load_dwordx4 v[108:111], v2, s[54:55] offset:2048
	global_load_dwordx4 v[80:83], v2, s[52:53] offset:3072
	global_load_dwordx4 v[112:115], v2, s[54:55] offset:3072
	s_lshl_b32 s19, s6, 12
	s_add_u32 s12, s42, s19
	s_addc_u32 s13, s43, 0
	s_add_u32 s12, s12, 0xfb24000
	s_addc_u32 s13, s13, 0
	s_sub_u32 s19, s6, 0x2000
	s_lshr_b32 s19, s19, 10
	s_add_u32 s19, s19, 1
	s_cmp_lt_u32 s6, 0x2000
	s_cselect_b32 s19, 0, s19
	s_mul_i32 s19, s19, 0x6000
	s_add_u32 s16, s42, s19
	s_addc_u32 s17, s43, 0
	s_add_u32 s16, s16, 0x6ea7000
	s_addc_u32 s17, s17, 0
	s_add_u32 s22, s16, 0x1000
	s_addc_u32 s23, s17, 0
	global_load_dwordx4 v[20:23], v2, s[12:13] offset:0 nt
	global_load_dwordx4 v[24:27], v2, s[12:13] offset:1024 nt
	global_load_dwordx4 v[28:31], v2, s[12:13] offset:2048 nt
	global_load_dwordx4 v[32:35], v2, s[12:13] offset:3072 nt
	global_load_dwordx4 v[36:39], v2, s[16:17] offset:0
	global_load_dwordx4 v[52:55], v2, s[22:23] offset:0
	global_load_dwordx4 v[40:43], v2, s[16:17] offset:1024
	global_load_dwordx4 v[56:59], v2, s[22:23] offset:1024
	global_load_dwordx4 v[44:47], v2, s[16:17] offset:2048
	global_load_dwordx4 v[60:63], v2, s[22:23] offset:2048
	global_load_dwordx4 v[48:51], v2, s[16:17] offset:3072
	global_load_dwordx4 v[64:67], v2, s[22:23] offset:3072
	s_waitcnt vmcnt(0)
.Lln1_l0_loop:
	s_mov_b64 s[8:9], s[12:13]
	s_lshl_b32 s19, s6, 11
	s_add_u32 s10, s42, s19
	s_addc_u32 s11, s43, 0
	s_add_u32 s10, s10, 0x9f24000
	s_addc_u32 s11, s11, 0
	v_pk_add_f32 v[12:13], v[20:21], v[22:23]
	v_pk_add_f32 v[12:13], v[12:13], v[24:25]
	v_pk_add_f32 v[12:13], v[12:13], v[26:27]
	v_pk_add_f32 v[12:13], v[12:13], v[28:29]
	v_pk_add_f32 v[12:13], v[12:13], v[30:31]
	v_pk_add_f32 v[12:13], v[12:13], v[32:33]
	v_pk_add_f32 v[12:13], v[12:13], v[34:35]
	v_add_f32_e32 v10, v12, v13
	ds_bpermute_b32 v11, v4, v10
	s_waitcnt lgkmcnt(0)
	v_add_f32_e32 v10, v10, v11
	ds_bpermute_b32 v11, v5, v10
	s_waitcnt lgkmcnt(0)
	v_add_f32_e32 v10, v10, v11
	ds_bpermute_b32 v11, v6, v10
	s_waitcnt lgkmcnt(0)
	v_add_f32_e32 v10, v10, v11
	ds_bpermute_b32 v11, v7, v10
	s_waitcnt lgkmcnt(0)
	v_add_f32_e32 v10, v10, v11
	ds_bpermute_b32 v11, v8, v10
	s_waitcnt lgkmcnt(0)
	v_add_f32_e32 v10, v10, v11
	ds_bpermute_b32 v11, v9, v10
	s_waitcnt lgkmcnt(0)
	v_add_f32_e32 v10, v10, v11
	v_mul_f32_e32 v14, 0x3a800000, v10
	v_pk_add_f32 v[20:21], v[20:21], v[14:15] op_sel_hi:[1,0] neg_lo:[0,1] neg_hi:[0,1]
	v_pk_add_f32 v[22:23], v[22:23], v[14:15] op_sel_hi:[1,0] neg_lo:[0,1] neg_hi:[0,1]
	v_pk_add_f32 v[24:25], v[24:25], v[14:15] op_sel_hi:[1,0] neg_lo:[0,1] neg_hi:[0,1]
	v_pk_add_f32 v[26:27], v[26:27], v[14:15] op_sel_hi:[1,0] neg_lo:[0,1] neg_hi:[0,1]
	v_pk_add_f32 v[28:29], v[28:29], v[14:15] op_sel_hi:[1,0] neg_lo:[0,1] neg_hi:[0,1]
	v_pk_add_f32 v[30:31], v[30:31], v[14:15] op_sel_hi:[1,0] neg_lo:[0,1] neg_hi:[0,1]
	v_pk_add_f32 v[32:33], v[32:33], v[14:15] op_sel_hi:[1,0] neg_lo:[0,1] neg_hi:[0,1]
	v_pk_add_f32 v[34:35], v[34:35], v[14:15] op_sel_hi:[1,0] neg_lo:[0,1] neg_hi:[0,1]
	v_pk_mul_f32 v[12:13], v[20:21], v[20:21]
	v_pk_fma_f32 v[12:13], v[22:23], v[22:23], v[12:13]
	v_pk_fma_f32 v[12:13], v[24:25], v[24:25], v[12:13]
	v_pk_fma_f32 v[12:13], v[26:27], v[26:27], v[12:13]
	v_pk_fma_f32 v[12:13], v[28:29], v[28:29], v[12:13]
	v_pk_fma_f32 v[12:13], v[30:31], v[30:31], v[12:13]
	v_pk_fma_f32 v[12:13], v[32:33], v[32:33], v[12:13]
	v_pk_fma_f32 v[12:13], v[34:35], v[34:35], v[12:13]
	v_add_f32_e32 v10, v12, v13
	ds_bpermute_b32 v11, v4, v10
	s_waitcnt lgkmcnt(0)
	v_add_f32_e32 v10, v10, v11
	ds_bpermute_b32 v11, v5, v10
	s_waitcnt lgkmcnt(0)
	v_add_f32_e32 v10, v10, v11
	ds_bpermute_b32 v11, v6, v10
	s_waitcnt lgkmcnt(0)
	v_add_f32_e32 v10, v10, v11
	ds_bpermute_b32 v11, v7, v10
	s_waitcnt lgkmcnt(0)
	v_add_f32_e32 v10, v10, v11
	ds_bpermute_b32 v11, v8, v10
	s_waitcnt lgkmcnt(0)
	v_add_f32_e32 v10, v10, v11
	ds_bpermute_b32 v11, v9, v10
	s_waitcnt lgkmcnt(0)
	v_add_f32_e32 v10, v10, v11
	v_mov_b32_e32 v11, 0x3727c5ac
	v_fmac_f32_e32 v11, 0x3a800000, v10
	v_rsq_f32_e32 v14, v11
	s_nop 0
	s_add_u32 s6, s6, s7
	s_cmp_lt_u32 s6, 0x3000
	s_cbranch_scc0 .Lln1_l0_nonext
	v_pk_mul_f32 v[20:21], v[20:21], v[14:15] op_sel_hi:[1,0]
	v_pk_fma_f32 v[132:133], v[68:69], v[20:21], v[100:101]
	v_pk_mul_f32 v[22:23], v[22:23], v[14:15] op_sel_hi:[1,0]
	v_pk_fma_f32 v[134:135], v[70:71], v[22:23], v[102:103]
	v_pk_mul_f32 v[24:25], v[24:25], v[14:15] op_sel_hi:[1,0]
	v_pk_fma_f32 v[136:137], v[72:73], v[24:25], v[104:105]
	v_pk_mul_f32 v[26:27], v[26:27], v[14:15] op_sel_hi:[1,0]
	v_pk_fma_f32 v[138:139], v[74:75], v[26:27], v[106:107]
	v_pk_mul_f32 v[28:29], v[28:29], v[14:15] op_sel_hi:[1,0]
	v_pk_fma_f32 v[140:141], v[76:77], v[28:29], v[108:109]
	v_pk_mul_f32 v[30:31], v[30:31], v[14:15] op_sel_hi:[1,0]
	v_pk_fma_f32 v[142:143], v[78:79], v[30:31], v[110:111]
	v_pk_mul_f32 v[32:33], v[32:33], v[14:15] op_sel_hi:[1,0]
	v_pk_fma_f32 v[144:145], v[80:81], v[32:33], v[112:113]
	v_pk_mul_f32 v[34:35], v[34:35], v[14:15] op_sel_hi:[1,0]
	v_pk_fma_f32 v[146:147], v[82:83], v[34:35], v[114:115]
	v_pk_add_f32 v[52:53], v[52:53], 1.0 op_sel_hi:[1,0]
	v_pk_fma_f32 v[52:53], v[52:53], v[132:133], v[36:37]
	v_pk_add_f32 v[54:55], v[54:55], 1.0 op_sel_hi:[1,0]
	v_pk_fma_f32 v[54:55], v[54:55], v[134:135], v[38:39]
	v_pk_add_f32 v[56:57], v[56:57], 1.0 op_sel_hi:[1,0]
	v_pk_fma_f32 v[56:57], v[56:57], v[136:137], v[40:41]
	v_pk_add_f32 v[58:59], v[58:59], 1.0 op_sel_hi:[1,0]
	v_pk_fma_f32 v[58:59], v[58:59], v[138:139], v[42:43]
	v_pk_add_f32 v[60:61], v[60:61], 1.0 op_sel_hi:[1,0]
	v_pk_fma_f32 v[60:61], v[60:61], v[140:141], v[44:45]
	v_pk_add_f32 v[62:63], v[62:63], 1.0 op_sel_hi:[1,0]
	v_pk_fma_f32 v[62:63], v[62:63], v[142:143], v[46:47]
	v_pk_add_f32 v[64:65], v[64:65], 1.0 op_sel_hi:[1,0]
	v_pk_fma_f32 v[64:65], v[64:65], v[144:145], v[48:49]
	v_pk_add_f32 v[66:67], v[66:67], 1.0 op_sel_hi:[1,0]
	v_pk_fma_f32 v[66:67], v[66:67], v[146:147], v[50:51]
	v_cvt_pk_bf16_f32 v148, v52, v53
	v_cvt_pk_bf16_f32 v149, v54, v55
	v_cvt_pk_bf16_f32 v150, v56, v57
	v_cvt_pk_bf16_f32 v151, v58, v59
	v_cvt_pk_bf16_f32 v152, v60, v61
	v_cvt_pk_bf16_f32 v153, v62, v63
	v_cvt_pk_bf16_f32 v154, v64, v65
	v_cvt_pk_bf16_f32 v155, v66, v67
	s_lshl_b32 s19, s6, 12
	s_add_u32 s12, s42, s19
	s_addc_u32 s13, s43, 0
	s_add_u32 s12, s12, 0xfb24000
	s_addc_u32 s13, s13, 0
	s_sub_u32 s19, s6, 0x2000
	s_lshr_b32 s19, s19, 10
	s_add_u32 s19, s19, 1
	s_cmp_lt_u32 s6, 0x2000
	s_cselect_b32 s19, 0, s19
	s_mul_i32 s19, s19, 0x6000
	s_add_u32 s16, s42, s19
	s_addc_u32 s17, s43, 0
	s_add_u32 s16, s16, 0x6ea7000
	s_addc_u32 s17, s17, 0
	s_add_u32 s22, s16, 0x1000
	s_addc_u32 s23, s17, 0
	global_load_dwordx4 v[20:23], v2, s[12:13] offset:0 nt
	global_load_dwordx4 v[24:27], v2, s[12:13] offset:1024 nt
	global_load_dwordx4 v[28:31], v2, s[12:13] offset:2048 nt
	global_load_dwordx4 v[32:35], v2, s[12:13] offset:3072 nt
	global_load_dwordx4 v[36:39], v2, s[16:17] offset:0
	global_load_dwordx4 v[52:55], v2, s[22:23] offset:0
	global_load_dwordx4 v[40:43], v2, s[16:17] offset:1024
	global_load_dwordx4 v[56:59], v2, s[22:23] offset:1024
	global_load_dwordx4 v[44:47], v2, s[16:17] offset:2048
	global_load_dwordx4 v[60:63], v2, s[22:23] offset:2048
	global_load_dwordx4 v[48:51], v2, s[16:17] offset:3072
	global_load_dwordx4 v[64:67], v2, s[22:23] offset:3072
	global_store_dwordx4 v2, v[132:135], s[8:9] offset:0
	global_store_dwordx4 v2, v[136:139], s[8:9] offset:1024
	global_store_dwordx4 v2, v[140:143], s[8:9] offset:2048
	global_store_dwordx4 v2, v[144:147], s[8:9] offset:3072
	global_store_dwordx2 v3, v[148:149], s[10:11] offset:0
	global_store_dwordx2 v3, v[150:151], s[10:11] offset:512
	global_store_dwordx2 v3, v[152:153], s[10:11] offset:1024
	global_store_dwordx2 v3, v[154:155], s[10:11] offset:1536
	s_waitcnt vmcnt(8)
	s_branch .Lln1_l0_loop
.Lln1_l0_nonext:
	v_pk_mul_f32 v[20:21], v[20:21], v[14:15] op_sel_hi:[1,0]
	v_pk_fma_f32 v[132:133], v[68:69], v[20:21], v[100:101]
	v_pk_mul_f32 v[22:23], v[22:23], v[14:15] op_sel_hi:[1,0]
	v_pk_fma_f32 v[134:135], v[70:71], v[22:23], v[102:103]
	v_pk_mul_f32 v[24:25], v[24:25], v[14:15] op_sel_hi:[1,0]
	v_pk_fma_f32 v[136:137], v[72:73], v[24:25], v[104:105]
	v_pk_mul_f32 v[26:27], v[26:27], v[14:15] op_sel_hi:[1,0]
	v_pk_fma_f32 v[138:139], v[74:75], v[26:27], v[106:107]
	v_pk_mul_f32 v[28:29], v[28:29], v[14:15] op_sel_hi:[1,0]
	v_pk_fma_f32 v[140:141], v[76:77], v[28:29], v[108:109]
	v_pk_mul_f32 v[30:31], v[30:31], v[14:15] op_sel_hi:[1,0]
	v_pk_fma_f32 v[142:143], v[78:79], v[30:31], v[110:111]
	v_pk_mul_f32 v[32:33], v[32:33], v[14:15] op_sel_hi:[1,0]
	v_pk_fma_f32 v[144:145], v[80:81], v[32:33], v[112:113]
	v_pk_mul_f32 v[34:35], v[34:35], v[14:15] op_sel_hi:[1,0]
	v_pk_fma_f32 v[146:147], v[82:83], v[34:35], v[114:115]
	v_pk_add_f32 v[52:53], v[52:53], 1.0 op_sel_hi:[1,0]
	v_pk_fma_f32 v[52:53], v[52:53], v[132:133], v[36:37]
	v_pk_add_f32 v[54:55], v[54:55], 1.0 op_sel_hi:[1,0]
	v_pk_fma_f32 v[54:55], v[54:55], v[134:135], v[38:39]
	v_pk_add_f32 v[56:57], v[56:57], 1.0 op_sel_hi:[1,0]
	v_pk_fma_f32 v[56:57], v[56:57], v[136:137], v[40:41]
	v_pk_add_f32 v[58:59], v[58:59], 1.0 op_sel_hi:[1,0]
	v_pk_fma_f32 v[58:59], v[58:59], v[138:139], v[42:43]
	v_pk_add_f32 v[60:61], v[60:61], 1.0 op_sel_hi:[1,0]
	v_pk_fma_f32 v[60:61], v[60:61], v[140:141], v[44:45]
	v_pk_add_f32 v[62:63], v[62:63], 1.0 op_sel_hi:[1,0]
	v_pk_fma_f32 v[62:63], v[62:63], v[142:143], v[46:47]
	v_pk_add_f32 v[64:65], v[64:65], 1.0 op_sel_hi:[1,0]
	v_pk_fma_f32 v[64:65], v[64:65], v[144:145], v[48:49]
	v_pk_add_f32 v[66:67], v[66:67], 1.0 op_sel_hi:[1,0]
	v_pk_fma_f32 v[66:67], v[66:67], v[146:147], v[50:51]
	v_cvt_pk_bf16_f32 v148, v52, v53
	v_cvt_pk_bf16_f32 v149, v54, v55
	v_cvt_pk_bf16_f32 v150, v56, v57
	v_cvt_pk_bf16_f32 v151, v58, v59
	v_cvt_pk_bf16_f32 v152, v60, v61
	v_cvt_pk_bf16_f32 v153, v62, v63
	v_cvt_pk_bf16_f32 v154, v64, v65
	v_cvt_pk_bf16_f32 v155, v66, v67
	global_store_dwordx4 v2, v[132:135], s[8:9] offset:0
	global_store_dwordx4 v2, v[136:139], s[8:9] offset:1024
	global_store_dwordx4 v2, v[140:143], s[8:9] offset:2048
	global_store_dwordx4 v2, v[144:147], s[8:9] offset:3072
	global_store_dwordx2 v3, v[148:149], s[10:11] offset:0
	global_store_dwordx2 v3, v[150:151], s[10:11] offset:512
	global_store_dwordx2 v3, v[152:153], s[10:11] offset:1024
	global_store_dwordx2 v3, v[154:155], s[10:11] offset:1536
	s_branch .LBB0_725

.LBB0_1292:
	s_and_b32 s70, s69, 0xff
	s_mul_i32 s4, s70, 0xab
	s_lshr_b32 s73, s4, 11
	s_mul_i32 s4, s73, 12
	s_sub_i32 s4, s69, s4
	s_and_b32 s4, s4, 0xff
	s_lshl_b32 s4, s4, 10
	s_or_b32 s8, s4, s52
	s_lshl_b32 s71, s8, 10
	s_lshl_b32 s4, s8, 11
	s_add_u32 s4, s53, s4
	s_addc_u32 s5, s54, 0
	s_lshl_b32 s6, s73, 17
	s_add_i32 s72, s6, 0x100000
	s_lshl_b32 s6, s72, 1
	s_add_u32 s6, s55, s6
	s_addc_u32 s7, s56, 0
	v_and_b32_e32 v164, 15, v0
	v_bfe_u32 v165, v0, 4, 2
	v_and_b32_e32 v111, 7, v164
	v_xor_b32_e32 v165, v165, v111
	v_lshlrev_b32_e32 v165, 4, v165
	v_lshl_or_b32 v165, v164, 7, v165
	v_bfe_u32 v164, v0, 7, 1
	v_lshl_or_b32 v100, v164, 13, v165
	v_bfe_u32 v164, v0, 6, 1
	v_lshl_or_b32 v158, v164, 13, v165
	v_or_b32_e32 v158, 0x4000, v158
	v_xor_b32_e32 v111, 64, v100
	v_xor_b32_e32 v159, 64, v158
	v_bfe_u32 v164, v0, 3, 3
	v_and_b32_e32 v165, 7, v0
	v_xor_b32_e32 v165, v165, v164
	v_lshlrev_b32_e32 v165, 4, v165
	v_lshl_or_b32 v165, v164, 11, v165
	v_lshrrev_b32_e32 v164, 6, v0
	v_and_b32_e32 v164, 3, v164
	v_lshl_or_b32 v160, v164, 16, v165
	v_add_u32_e32 v161, 0x3c00, v160
	v_add_u32_e32 v162, 0x7800, v160
	v_add_u32_e32 v163, 0xb400, v160
	v_lshlrev_b32_e32 v164, 12, v164
	s_nop 0
	v_readfirstlane_b32 s10, v164
	s_add_u32 s10, s10, 32
	v_mov_b32_e32 v94, 0
	v_mov_b32_e32 v95, 0
	v_mov_b32_e32 v96, 0
	v_mov_b32_e32 v97, 0
	v_mov_b32_e32 v90, 0
	v_mov_b32_e32 v91, 0
	v_mov_b32_e32 v92, 0
	v_mov_b32_e32 v93, 0
	v_mov_b32_e32 v82, 0
	v_mov_b32_e32 v83, 0
	v_mov_b32_e32 v84, 0
	v_mov_b32_e32 v85, 0
	v_mov_b32_e32 v78, 0
	v_mov_b32_e32 v79, 0
	v_mov_b32_e32 v80, 0
	v_mov_b32_e32 v81, 0
	v_mov_b32_e32 v74, 0
	v_mov_b32_e32 v75, 0
	v_mov_b32_e32 v76, 0
	v_mov_b32_e32 v77, 0
	v_mov_b32_e32 v70, 0
	v_mov_b32_e32 v71, 0
	v_mov_b32_e32 v72, 0
	v_mov_b32_e32 v73, 0
	v_mov_b32_e32 v66, 0
	v_mov_b32_e32 v67, 0
	v_mov_b32_e32 v68, 0
	v_mov_b32_e32 v69, 0
	v_mov_b32_e32 v58, 0
	v_mov_b32_e32 v59, 0
	v_mov_b32_e32 v60, 0
	v_mov_b32_e32 v61, 0
	v_mov_b32_e32 v26, 0
	v_mov_b32_e32 v27, 0
	v_mov_b32_e32 v28, 0
	v_mov_b32_e32 v29, 0
	v_mov_b32_e32 v22, 0
	v_mov_b32_e32 v23, 0
	v_mov_b32_e32 v24, 0
	v_mov_b32_e32 v25, 0
	v_mov_b32_e32 v18, 0
	v_mov_b32_e32 v19, 0
	v_mov_b32_e32 v20, 0
	v_mov_b32_e32 v21, 0
	v_mov_b32_e32 v14, 0
	v_mov_b32_e32 v15, 0
	v_mov_b32_e32 v16, 0
	v_mov_b32_e32 v17, 0
	v_mov_b32_e32 v10, 0
	v_mov_b32_e32 v11, 0
	v_mov_b32_e32 v12, 0
	v_mov_b32_e32 v13, 0
	v_mov_b32_e32 v6, 0
	v_mov_b32_e32 v7, 0
	v_mov_b32_e32 v8, 0
	v_mov_b32_e32 v9, 0
	v_mov_b32_e32 v2, 0
	v_mov_b32_e32 v3, 0
	v_mov_b32_e32 v4, 0
	v_mov_b32_e32 v5, 0
	v_mov_b32_e32 v86, 0
	v_mov_b32_e32 v87, 0
	v_mov_b32_e32 v88, 0
	v_mov_b32_e32 v89, 0
	v_mov_b32_e32 v114, 0
	v_mov_b32_e32 v115, 0
	v_mov_b32_e32 v116, 0
	v_mov_b32_e32 v117, 0
	v_mov_b32_e32 v118, 0
	v_mov_b32_e32 v119, 0
	v_mov_b32_e32 v120, 0
	v_mov_b32_e32 v121, 0
	v_mov_b32_e32 v122, 0
	v_mov_b32_e32 v123, 0
	v_mov_b32_e32 v124, 0
	v_mov_b32_e32 v125, 0
	v_mov_b32_e32 v138, 0
	v_mov_b32_e32 v139, 0
	v_mov_b32_e32 v140, 0
	v_mov_b32_e32 v141, 0
	v_mov_b32_e32 v142, 0
	v_mov_b32_e32 v143, 0
	v_mov_b32_e32 v144, 0
	v_mov_b32_e32 v145, 0
	v_mov_b32_e32 v146, 0
	v_mov_b32_e32 v147, 0
	v_mov_b32_e32 v148, 0
	v_mov_b32_e32 v149, 0
	v_mov_b32_e32 v150, 0
	v_mov_b32_e32 v151, 0
	v_mov_b32_e32 v152, 0
	v_mov_b32_e32 v153, 0
	v_mov_b32_e32 v154, 0
	v_mov_b32_e32 v155, 0
	v_mov_b32_e32 v156, 0
	v_mov_b32_e32 v157, 0
	s_waitcnt lgkmcnt(0)
	s_barrier
	s_add_u32 m0, s10, 0
	s_nop 0
	global_load_lds_dwordx4 v160, s[4:5] offset:0
	global_load_lds_dwordx4 v161, s[4:5] offset:1024
	global_load_lds_dwordx4 v162, s[4:5] offset:2048
	global_load_lds_dwordx4 v163, s[4:5] offset:3072
	s_add_u32 m0, s10, 16384
	s_nop 0
	global_load_lds_dwordx4 v160, s[6:7] offset:0
	global_load_lds_dwordx4 v161, s[6:7] offset:1024
	global_load_lds_dwordx4 v162, s[6:7] offset:2048
	global_load_lds_dwordx4 v163, s[6:7] offset:3072
	s_add_u32 s4, s4, 0x80
	s_addc_u32 s5, s5, 0
	s_add_u32 s6, s6, 0x80
	s_addc_u32 s7, s7, 0
	s_mov_b32 s9, 0
	s_waitcnt vmcnt(0)
.Lk_aol1a_loop:
	s_barrier
	s_add_u32 m0, s10, 32768
	v_mfma_f32_16x16x32_bf16 v[94:97], v[114:117], v[142:145], v[94:97]
	ds_read_b128 v[30:33], v100 offset:32
	global_load_lds_dwordx4 v160, s[4:5] offset:0
	v_mfma_f32_16x16x32_bf16 v[90:93], v[114:117], v[146:149], v[90:93]
	ds_read_b128 v[46:49], v158 offset:32
	global_load_lds_dwordx4 v161, s[4:5] offset:1024
	v_mfma_f32_16x16x32_bf16 v[82:85], v[114:117], v[150:153], v[82:85]
	ds_read_b128 v[50:53], v158 offset:2080
	global_load_lds_dwordx4 v162, s[4:5] offset:2048
	v_mfma_f32_16x16x32_bf16 v[78:81], v[114:117], v[154:157], v[78:81]
	ds_read_b128 v[34:37], v100 offset:2080
	global_load_lds_dwordx4 v163, s[4:5] offset:3072
	s_add_u32 m0, s10, 49152
	v_mfma_f32_16x16x32_bf16 v[74:77], v[118:121], v[142:145], v[74:77]
	ds_read_b128 v[54:57], v158 offset:4128
	global_load_lds_dwordx4 v160, s[6:7] offset:0
	v_mfma_f32_16x16x32_bf16 v[70:73], v[118:121], v[146:149], v[70:73]
	ds_read_b128 v[62:65], v158 offset:6176
	global_load_lds_dwordx4 v161, s[6:7] offset:1024
	v_mfma_f32_16x16x32_bf16 v[66:69], v[118:121], v[150:153], v[66:69]
	ds_read_b128 v[38:41], v100 offset:4128
	global_load_lds_dwordx4 v162, s[6:7] offset:2048
	v_mfma_f32_16x16x32_bf16 v[58:61], v[118:121], v[154:157], v[58:61]
	ds_read_b128 v[42:45], v100 offset:6176
	global_load_lds_dwordx4 v163, s[6:7] offset:3072
	v_mfma_f32_16x16x32_bf16 v[26:29], v[122:125], v[142:145], v[26:29]
	v_mfma_f32_16x16x32_bf16 v[22:25], v[122:125], v[146:149], v[22:25]
	v_mfma_f32_16x16x32_bf16 v[18:21], v[122:125], v[150:153], v[18:21]
	v_mfma_f32_16x16x32_bf16 v[14:17], v[122:125], v[154:157], v[14:17]
	v_mfma_f32_16x16x32_bf16 v[10:13], v[138:141], v[142:145], v[10:13]
	v_mfma_f32_16x16x32_bf16 v[6:9], v[138:141], v[146:149], v[6:9]
	v_mfma_f32_16x16x32_bf16 v[2:5], v[138:141], v[150:153], v[2:5]
	v_mfma_f32_16x16x32_bf16 v[86:89], v[138:141], v[154:157], v[86:89]
	s_add_u32 s4, s4, 0x80
	s_addc_u32 s5, s5, 0
	s_add_u32 s6, s6, 0x80
	s_addc_u32 s7, s7, 0
	s_waitcnt lgkmcnt(0)
	v_mfma_f32_16x16x32_bf16 v[94:97], v[30:33], v[46:49], v[94:97]
	ds_read_b128 v[114:117], v111 offset:32
	v_mfma_f32_16x16x32_bf16 v[90:93], v[30:33], v[50:53], v[90:93]
	ds_read_b128 v[142:145], v159 offset:32
	v_mfma_f32_16x16x32_bf16 v[82:85], v[30:33], v[54:57], v[82:85]
	ds_read_b128 v[146:149], v159 offset:2080
	v_mfma_f32_16x16x32_bf16 v[78:81], v[30:33], v[62:65], v[78:81]
	ds_read_b128 v[118:121], v111 offset:2080
	v_mfma_f32_16x16x32_bf16 v[74:77], v[34:37], v[46:49], v[74:77]
	ds_read_b128 v[150:153], v159 offset:4128
	v_mfma_f32_16x16x32_bf16 v[70:73], v[34:37], v[50:53], v[70:73]
	ds_read_b128 v[154:157], v159 offset:6176
	v_mfma_f32_16x16x32_bf16 v[66:69], v[34:37], v[54:57], v[66:69]
	ds_read_b128 v[122:125], v111 offset:4128
	v_mfma_f32_16x16x32_bf16 v[58:61], v[34:37], v[62:65], v[58:61]
	ds_read_b128 v[138:141], v111 offset:6176
	v_mfma_f32_16x16x32_bf16 v[26:29], v[38:41], v[46:49], v[26:29]
	v_mfma_f32_16x16x32_bf16 v[22:25], v[38:41], v[50:53], v[22:25]
	v_mfma_f32_16x16x32_bf16 v[18:21], v[38:41], v[54:57], v[18:21]
	v_mfma_f32_16x16x32_bf16 v[14:17], v[38:41], v[62:65], v[14:17]
	v_mfma_f32_16x16x32_bf16 v[10:13], v[42:45], v[46:49], v[10:13]
	v_mfma_f32_16x16x32_bf16 v[6:9], v[42:45], v[50:53], v[6:9]
	v_mfma_f32_16x16x32_bf16 v[2:5], v[42:45], v[54:57], v[2:5]
	v_mfma_f32_16x16x32_bf16 v[86:89], v[42:45], v[62:65], v[86:89]
	s_waitcnt lgkmcnt(0)
	s_waitcnt vmcnt(0)
	s_barrier
	s_add_u32 m0, s10, 0
	v_mfma_f32_16x16x32_bf16 v[94:97], v[114:117], v[142:145], v[94:97]
	ds_read_b128 v[30:33], v100 offset:32800
	global_load_lds_dwordx4 v160, s[4:5] offset:0
	v_mfma_f32_16x16x32_bf16 v[90:93], v[114:117], v[146:149], v[90:93]
	ds_read_b128 v[46:49], v158 offset:32800
	global_load_lds_dwordx4 v161, s[4:5] offset:1024
	v_mfma_f32_16x16x32_bf16 v[82:85], v[114:117], v[150:153], v[82:85]
	ds_read_b128 v[50:53], v158 offset:34848
	global_load_lds_dwordx4 v162, s[4:5] offset:2048
	v_mfma_f32_16x16x32_bf16 v[78:81], v[114:117], v[154:157], v[78:81]
	ds_read_b128 v[34:37], v100 offset:34848
	global_load_lds_dwordx4 v163, s[4:5] offset:3072
	s_add_u32 m0, s10, 16384
	v_mfma_f32_16x16x32_bf16 v[74:77], v[118:121], v[142:145], v[74:77]
	ds_read_b128 v[54:57], v158 offset:36896
	global_load_lds_dwordx4 v160, s[6:7] offset:0
	v_mfma_f32_16x16x32_bf16 v[70:73], v[118:121], v[146:149], v[70:73]
	ds_read_b128 v[62:65], v158 offset:38944
	global_load_lds_dwordx4 v161, s[6:7] offset:1024
	v_mfma_f32_16x16x32_bf16 v[66:69], v[118:121], v[150:153], v[66:69]
	ds_read_b128 v[38:41], v100 offset:36896
	global_load_lds_dwordx4 v162, s[6:7] offset:2048
	v_mfma_f32_16x16x32_bf16 v[58:61], v[118:121], v[154:157], v[58:61]
	ds_read_b128 v[42:45], v100 offset:38944
	global_load_lds_dwordx4 v163, s[6:7] offset:3072
	v_mfma_f32_16x16x32_bf16 v[26:29], v[122:125], v[142:145], v[26:29]
	v_mfma_f32_16x16x32_bf16 v[22:25], v[122:125], v[146:149], v[22:25]
	v_mfma_f32_16x16x32_bf16 v[18:21], v[122:125], v[150:153], v[18:21]
	v_mfma_f32_16x16x32_bf16 v[14:17], v[122:125], v[154:157], v[14:17]
	v_mfma_f32_16x16x32_bf16 v[10:13], v[138:141], v[142:145], v[10:13]
	v_mfma_f32_16x16x32_bf16 v[6:9], v[138:141], v[146:149], v[6:9]
	v_mfma_f32_16x16x32_bf16 v[2:5], v[138:141], v[150:153], v[2:5]
	v_mfma_f32_16x16x32_bf16 v[86:89], v[138:141], v[154:157], v[86:89]
	s_add_u32 s4, s4, 0x80
	s_addc_u32 s5, s5, 0
	s_add_u32 s6, s6, 0x80
	s_addc_u32 s7, s7, 0
	s_waitcnt lgkmcnt(0)
	v_mfma_f32_16x16x32_bf16 v[94:97], v[30:33], v[46:49], v[94:97]
	ds_read_b128 v[114:117], v111 offset:32800
	v_mfma_f32_16x16x32_bf16 v[90:93], v[30:33], v[50:53], v[90:93]
	ds_read_b128 v[142:145], v159 offset:32800
	v_mfma_f32_16x16x32_bf16 v[82:85], v[30:33], v[54:57], v[82:85]
	ds_read_b128 v[146:149], v159 offset:34848
	v_mfma_f32_16x16x32_bf16 v[78:81], v[30:33], v[62:65], v[78:81]
	ds_read_b128 v[118:121], v111 offset:34848
	v_mfma_f32_16x16x32_bf16 v[74:77], v[34:37], v[46:49], v[74:77]
	ds_read_b128 v[150:153], v159 offset:36896
	v_mfma_f32_16x16x32_bf16 v[70:73], v[34:37], v[50:53], v[70:73]
	ds_read_b128 v[154:157], v159 offset:38944
	v_mfma_f32_16x16x32_bf16 v[66:69], v[34:37], v[54:57], v[66:69]
	ds_read_b128 v[122:125], v111 offset:36896
	v_mfma_f32_16x16x32_bf16 v[58:61], v[34:37], v[62:65], v[58:61]
	ds_read_b128 v[138:141], v111 offset:38944
	v_mfma_f32_16x16x32_bf16 v[26:29], v[38:41], v[46:49], v[26:29]
	v_mfma_f32_16x16x32_bf16 v[22:25], v[38:41], v[50:53], v[22:25]
	v_mfma_f32_16x16x32_bf16 v[18:21], v[38:41], v[54:57], v[18:21]
	v_mfma_f32_16x16x32_bf16 v[14:17], v[38:41], v[62:65], v[14:17]
	v_mfma_f32_16x16x32_bf16 v[10:13], v[42:45], v[46:49], v[10:13]
	v_mfma_f32_16x16x32_bf16 v[6:9], v[42:45], v[50:53], v[6:9]
	v_mfma_f32_16x16x32_bf16 v[2:5], v[42:45], v[54:57], v[2:5]
	v_mfma_f32_16x16x32_bf16 v[86:89], v[42:45], v[62:65], v[86:89]
	s_waitcnt lgkmcnt(0)
	s_waitcnt vmcnt(0)
	s_add_u32 s9, s9, 1
	s_cmp_lt_u32 s9, 7
	s_cbranch_scc1 .Lk_aol1a_loop
	s_barrier
	s_add_u32 m0, s10, 32768
	v_mfma_f32_16x16x32_bf16 v[94:97], v[114:117], v[142:145], v[94:97]
	ds_read_b128 v[30:33], v100 offset:32
	global_load_lds_dwordx4 v160, s[4:5] offset:0
	v_mfma_f32_16x16x32_bf16 v[90:93], v[114:117], v[146:149], v[90:93]
	ds_read_b128 v[46:49], v158 offset:32
	global_load_lds_dwordx4 v161, s[4:5] offset:1024
	v_mfma_f32_16x16x32_bf16 v[82:85], v[114:117], v[150:153], v[82:85]
	ds_read_b128 v[50:53], v158 offset:2080
	global_load_lds_dwordx4 v162, s[4:5] offset:2048
	v_mfma_f32_16x16x32_bf16 v[78:81], v[114:117], v[154:157], v[78:81]
	ds_read_b128 v[34:37], v100 offset:2080
	global_load_lds_dwordx4 v163, s[4:5] offset:3072
	s_add_u32 m0, s10, 49152
	v_mfma_f32_16x16x32_bf16 v[74:77], v[118:121], v[142:145], v[74:77]
	ds_read_b128 v[54:57], v158 offset:4128
	global_load_lds_dwordx4 v160, s[6:7] offset:0
	v_mfma_f32_16x16x32_bf16 v[70:73], v[118:121], v[146:149], v[70:73]
	ds_read_b128 v[62:65], v158 offset:6176
	global_load_lds_dwordx4 v161, s[6:7] offset:1024
	v_mfma_f32_16x16x32_bf16 v[66:69], v[118:121], v[150:153], v[66:69]
	ds_read_b128 v[38:41], v100 offset:4128
	global_load_lds_dwordx4 v162, s[6:7] offset:2048
	v_mfma_f32_16x16x32_bf16 v[58:61], v[118:121], v[154:157], v[58:61]
	ds_read_b128 v[42:45], v100 offset:6176
	global_load_lds_dwordx4 v163, s[6:7] offset:3072
	v_mfma_f32_16x16x32_bf16 v[26:29], v[122:125], v[142:145], v[26:29]
	v_mfma_f32_16x16x32_bf16 v[22:25], v[122:125], v[146:149], v[22:25]
	v_mfma_f32_16x16x32_bf16 v[18:21], v[122:125], v[150:153], v[18:21]
	v_mfma_f32_16x16x32_bf16 v[14:17], v[122:125], v[154:157], v[14:17]
	v_mfma_f32_16x16x32_bf16 v[10:13], v[138:141], v[142:145], v[10:13]
	v_mfma_f32_16x16x32_bf16 v[6:9], v[138:141], v[146:149], v[6:9]
	v_mfma_f32_16x16x32_bf16 v[2:5], v[138:141], v[150:153], v[2:5]
	v_mfma_f32_16x16x32_bf16 v[86:89], v[138:141], v[154:157], v[86:89]
	s_add_u32 s4, s4, 0x80
	s_addc_u32 s5, s5, 0
	s_add_u32 s6, s6, 0x80
	s_addc_u32 s7, s7, 0
	s_waitcnt lgkmcnt(0)
	v_mfma_f32_16x16x32_bf16 v[94:97], v[30:33], v[46:49], v[94:97]
	ds_read_b128 v[114:117], v111 offset:32
	v_mfma_f32_16x16x32_bf16 v[90:93], v[30:33], v[50:53], v[90:93]
	ds_read_b128 v[142:145], v159 offset:32
	v_mfma_f32_16x16x32_bf16 v[82:85], v[30:33], v[54:57], v[82:85]
	ds_read_b128 v[146:149], v159 offset:2080
	v_mfma_f32_16x16x32_bf16 v[78:81], v[30:33], v[62:65], v[78:81]
	ds_read_b128 v[118:121], v111 offset:2080
	v_mfma_f32_16x16x32_bf16 v[74:77], v[34:37], v[46:49], v[74:77]
	ds_read_b128 v[150:153], v159 offset:4128
	v_mfma_f32_16x16x32_bf16 v[70:73], v[34:37], v[50:53], v[70:73]
	ds_read_b128 v[154:157], v159 offset:6176
	v_mfma_f32_16x16x32_bf16 v[66:69], v[34:37], v[54:57], v[66:69]
	ds_read_b128 v[122:125], v111 offset:4128
	v_mfma_f32_16x16x32_bf16 v[58:61], v[34:37], v[62:65], v[58:61]
	ds_read_b128 v[138:141], v111 offset:6176
	v_mfma_f32_16x16x32_bf16 v[26:29], v[38:41], v[46:49], v[26:29]
	v_mfma_f32_16x16x32_bf16 v[22:25], v[38:41], v[50:53], v[22:25]
	v_mfma_f32_16x16x32_bf16 v[18:21], v[38:41], v[54:57], v[18:21]
	v_mfma_f32_16x16x32_bf16 v[14:17], v[38:41], v[62:65], v[14:17]
	v_mfma_f32_16x16x32_bf16 v[10:13], v[42:45], v[46:49], v[10:13]
	v_mfma_f32_16x16x32_bf16 v[6:9], v[42:45], v[50:53], v[6:9]
	v_mfma_f32_16x16x32_bf16 v[2:5], v[42:45], v[54:57], v[2:5]
	v_mfma_f32_16x16x32_bf16 v[86:89], v[42:45], v[62:65], v[86:89]
	s_waitcnt lgkmcnt(0)
	s_waitcnt vmcnt(0)
	s_barrier
	v_mfma_f32_16x16x32_bf16 v[94:97], v[114:117], v[142:145], v[94:97]
	ds_read_b128 v[30:33], v100 offset:32800
	v_mfma_f32_16x16x32_bf16 v[90:93], v[114:117], v[146:149], v[90:93]
	ds_read_b128 v[46:49], v158 offset:32800
	v_mfma_f32_16x16x32_bf16 v[82:85], v[114:117], v[150:153], v[82:85]
	ds_read_b128 v[50:53], v158 offset:34848
	v_mfma_f32_16x16x32_bf16 v[78:81], v[114:117], v[154:157], v[78:81]
	ds_read_b128 v[34:37], v100 offset:34848
	v_mfma_f32_16x16x32_bf16 v[74:77], v[118:121], v[142:145], v[74:77]
	ds_read_b128 v[54:57], v158 offset:36896
	v_mfma_f32_16x16x32_bf16 v[70:73], v[118:121], v[146:149], v[70:73]
	ds_read_b128 v[62:65], v158 offset:38944
	v_mfma_f32_16x16x32_bf16 v[66:69], v[118:121], v[150:153], v[66:69]
	ds_read_b128 v[38:41], v100 offset:36896
	v_mfma_f32_16x16x32_bf16 v[58:61], v[118:121], v[154:157], v[58:61]
	ds_read_b128 v[42:45], v100 offset:38944
	v_mfma_f32_16x16x32_bf16 v[26:29], v[122:125], v[142:145], v[26:29]
	v_mfma_f32_16x16x32_bf16 v[22:25], v[122:125], v[146:149], v[22:25]
	v_mfma_f32_16x16x32_bf16 v[18:21], v[122:125], v[150:153], v[18:21]
	v_mfma_f32_16x16x32_bf16 v[14:17], v[122:125], v[154:157], v[14:17]
	v_mfma_f32_16x16x32_bf16 v[10:13], v[138:141], v[142:145], v[10:13]
	v_mfma_f32_16x16x32_bf16 v[6:9], v[138:141], v[146:149], v[6:9]
	v_mfma_f32_16x16x32_bf16 v[2:5], v[138:141], v[150:153], v[2:5]
	v_mfma_f32_16x16x32_bf16 v[86:89], v[138:141], v[154:157], v[86:89]
	s_waitcnt lgkmcnt(0)
	v_mfma_f32_16x16x32_bf16 v[94:97], v[30:33], v[46:49], v[94:97]
	ds_read_b128 v[114:117], v111 offset:32800
	v_mfma_f32_16x16x32_bf16 v[90:93], v[30:33], v[50:53], v[90:93]
	ds_read_b128 v[142:145], v159 offset:32800
	v_mfma_f32_16x16x32_bf16 v[82:85], v[30:33], v[54:57], v[82:85]
	ds_read_b128 v[146:149], v159 offset:34848
	v_mfma_f32_16x16x32_bf16 v[78:81], v[30:33], v[62:65], v[78:81]
	ds_read_b128 v[118:121], v111 offset:34848
	v_mfma_f32_16x16x32_bf16 v[74:77], v[34:37], v[46:49], v[74:77]
	ds_read_b128 v[150:153], v159 offset:36896
	v_mfma_f32_16x16x32_bf16 v[70:73], v[34:37], v[50:53], v[70:73]
	ds_read_b128 v[154:157], v159 offset:38944
	v_mfma_f32_16x16x32_bf16 v[66:69], v[34:37], v[54:57], v[66:69]
	ds_read_b128 v[122:125], v111 offset:36896
	v_mfma_f32_16x16x32_bf16 v[58:61], v[34:37], v[62:65], v[58:61]
	ds_read_b128 v[138:141], v111 offset:38944
	v_mfma_f32_16x16x32_bf16 v[26:29], v[38:41], v[46:49], v[26:29]
	v_mfma_f32_16x16x32_bf16 v[22:25], v[38:41], v[50:53], v[22:25]
	v_mfma_f32_16x16x32_bf16 v[18:21], v[38:41], v[54:57], v[18:21]
	v_mfma_f32_16x16x32_bf16 v[14:17], v[38:41], v[62:65], v[14:17]
	v_mfma_f32_16x16x32_bf16 v[10:13], v[42:45], v[46:49], v[10:13]
	v_mfma_f32_16x16x32_bf16 v[6:9], v[42:45], v[50:53], v[6:9]
	v_mfma_f32_16x16x32_bf16 v[2:5], v[42:45], v[54:57], v[2:5]
	v_mfma_f32_16x16x32_bf16 v[86:89], v[42:45], v[62:65], v[86:89]
	s_waitcnt lgkmcnt(0)
	v_mfma_f32_16x16x32_bf16 v[94:97], v[114:117], v[142:145], v[94:97]
	v_mfma_f32_16x16x32_bf16 v[90:93], v[114:117], v[146:149], v[90:93]
	v_mfma_f32_16x16x32_bf16 v[82:85], v[114:117], v[150:153], v[82:85]
	v_mfma_f32_16x16x32_bf16 v[78:81], v[114:117], v[154:157], v[78:81]
	v_mfma_f32_16x16x32_bf16 v[74:77], v[118:121], v[142:145], v[74:77]
	v_mfma_f32_16x16x32_bf16 v[70:73], v[118:121], v[146:149], v[70:73]
	v_mfma_f32_16x16x32_bf16 v[66:69], v[118:121], v[150:153], v[66:69]
	v_mfma_f32_16x16x32_bf16 v[58:61], v[118:121], v[154:157], v[58:61]
	v_mfma_f32_16x16x32_bf16 v[26:29], v[122:125], v[142:145], v[26:29]
	v_mfma_f32_16x16x32_bf16 v[22:25], v[122:125], v[146:149], v[22:25]
	v_mfma_f32_16x16x32_bf16 v[18:21], v[122:125], v[150:153], v[18:21]
	v_mfma_f32_16x16x32_bf16 v[14:17], v[122:125], v[154:157], v[14:17]
	v_mfma_f32_16x16x32_bf16 v[10:13], v[138:141], v[142:145], v[10:13]
	v_mfma_f32_16x16x32_bf16 v[6:9], v[138:141], v[146:149], v[6:9]
	v_mfma_f32_16x16x32_bf16 v[2:5], v[138:141], v[150:153], v[2:5]
	v_mfma_f32_16x16x32_bf16 v[86:89], v[138:141], v[154:157], v[86:89]
	s_mul_i32 s4, s68, s62
	s_add_i32 s4, s4, s67
	s_and_b32 s4, s4, 0xff
	s_waitcnt vmcnt(7)
	v_lshl_or_b32 v30, s4, 10, v132
	s_mul_hi_u32 s4, s4, 0x15555556
	s_mulk_i32 s4, 0xd000
	v_add_u32_e32 v30, s4, v30
	s_lshl_b32 s36, s73, 8
	v_add_u32_e32 v138, 0x400, v129
	v_add_u32_e32 v139, 0x2000, v129
	v_add_u32_e32 v140, 0x2400, v129
	v_add_u32_e32 v141, 0x4000, v129
	v_add_u32_e32 v142, 0x4400, v129
	v_add_u32_e32 v143, 0x4800, v129
	v_add_u32_e32 v144, 0x6000, v129
	v_add_u32_e32 v145, 0x6400, v129
	v_add_u32_e32 v146, 0x6800, v129
	v_lshl_add_u64 v[114:115], v[102:103], 0, s[36:37]
	v_cmp_gt_u32_e32 vcc, s66, v30
	s_barrier
	ds_write2_b32 v129, v94, v90 offset1:16
	ds_write2_b32 v129, v95, v91 offset0:132 offset1:148
	ds_write2_b32 v138, v96, v92 offset0:8 offset1:24
	ds_write2_b32 v138, v97, v93 offset0:140 offset1:156
	ds_write2_b32 v129, v82, v78 offset0:32 offset1:48
	ds_write2_b32 v129, v83, v79 offset0:164 offset1:180
	ds_write2_b32 v138, v84, v80 offset0:40 offset1:56
	ds_write2_b32 v138, v85, v81 offset0:172 offset1:188
	ds_write2_b32 v139, v74, v70 offset0:64 offset1:80
	ds_write2_b32 v139, v75, v71 offset0:196 offset1:212
	ds_write2_b32 v140, v76, v72 offset0:72 offset1:88
	ds_write2_b32 v140, v77, v73 offset0:204 offset1:220
	ds_write2_b32 v139, v66, v58 offset0:96 offset1:112
	ds_write2_b32 v139, v67, v59 offset0:228 offset1:244
	ds_write2_b32 v140, v68, v60 offset0:104 offset1:120
	ds_write2_b32 v140, v69, v61 offset0:236 offset1:252
	ds_write2_b32 v141, v26, v22 offset0:128 offset1:144
	ds_write2_b32 v142, v27, v23 offset0:4 offset1:20
	ds_write2_b32 v142, v28, v24 offset0:136 offset1:152
	ds_write2_b32 v143, v29, v25 offset0:12 offset1:28
	ds_write2_b32 v141, v18, v14 offset0:160 offset1:176
	ds_write2_b32 v142, v19, v15 offset0:36 offset1:52
	ds_write2_b32 v142, v20, v16 offset0:168 offset1:184
	ds_write2_b32 v143, v21, v17 offset0:44 offset1:60
	ds_write2_b32 v144, v10, v6 offset0:192 offset1:208
	ds_write2_b32 v145, v11, v7 offset0:68 offset1:84
	ds_write2_b32 v145, v12, v8 offset0:200 offset1:216
	ds_write2_b32 v146, v13, v9 offset0:76 offset1:92
	ds_write2_b32 v144, v2, v86 offset0:224 offset1:240
	ds_write2_b32 v145, v3, v87 offset0:100 offset1:116
	ds_write2_b32 v145, v4, v88 offset0:232 offset1:248
	ds_write2_b32 v146, v5, v89 offset0:108 offset1:124
	s_waitcnt lgkmcnt(0)
	s_barrier
	s_and_saveexec_b64 s[4:5], vcc
	s_xor_b64 s[4:5], exec, s[4:5]
	s_cbranch_execz .LBB0_1297
	s_mov_b32 s6, s8
	s_mov_b32 s7, 1
	s_mov_b32 s9, 0
	s_mov_b32 s10, 8

.LBB0_1300:
	s_or_b64 exec, exec, s[50:51]
	s_lshl_b32 s4, s73, 7
	s_lshl_b32 s5, s71, 1
	s_add_u32 s6, s58, s5
	s_addc_u32 s7, s59, 0
	s_lshl_b32 s5, s72, 1
	v_mov_b32_e32 v111, v101
	s_add_u32 s8, s60, s5
	s_addc_u32 s9, s61, 0
	s_waitcnt lgkmcnt(0)
	s_barrier
	ds_read2_b32 v[26:27], v129 offset1:16
	ds_read2_b32 v[148:149], v129 offset0:132 offset1:148
	ds_read2_b32 v[28:29], v138 offset0:8 offset1:24
	ds_read2_b32 v[150:151], v138 offset0:140 offset1:156
	ds_read2_b32 v[22:23], v129 offset0:32 offset1:48
	ds_read2_b32 v[152:153], v129 offset0:164 offset1:180
	ds_read2_b32 v[24:25], v138 offset0:40 offset1:56
	ds_read2_b32 v[154:155], v138 offset0:172 offset1:188
	ds_read2_b32 v[18:19], v139 offset0:64 offset1:80
	ds_read2_b32 v[156:157], v139 offset0:196 offset1:212
	ds_read2_b32 v[20:21], v140 offset0:72 offset1:88
	ds_read2_b32 v[158:159], v140 offset0:204 offset1:220
	ds_read2_b32 v[14:15], v139 offset0:96 offset1:112
	ds_read2_b32 v[160:161], v139 offset0:228 offset1:244
	ds_read2_b32 v[16:17], v140 offset0:104 offset1:120
	ds_read2_b32 v[162:163], v140 offset0:236 offset1:252
	ds_read2_b32 v[10:11], v141 offset0:128 offset1:144
	ds_read2_b32 v[164:165], v142 offset0:4 offset1:20
	ds_read2_b32 v[12:13], v142 offset0:136 offset1:152
	ds_read2_b32 v[166:167], v143 offset0:12 offset1:28
	ds_read2_b32 v[6:7], v141 offset0:160 offset1:176
	ds_read2_b32 v[168:169], v142 offset0:36 offset1:52
	ds_read2_b32 v[8:9], v142 offset0:168 offset1:184
	ds_read2_b32 v[170:171], v143 offset0:44 offset1:60
	ds_read2_b32 v[2:3], v144 offset0:192 offset1:208
	ds_read2_b32 v[172:173], v145 offset0:68 offset1:84
	ds_read2_b32 v[4:5], v145 offset0:200 offset1:216
	ds_read2_b32 v[174:175], v146 offset0:76 offset1:92
	ds_read2_b32 v[30:31], v144 offset0:224 offset1:240
	ds_read2_b32 v[176:177], v145 offset0:100 offset1:116
	ds_read2_b32 v[32:33], v145 offset0:232 offset1:248
	ds_read2_b32 v[178:179], v146 offset0:108 offset1:124
	s_waitcnt lgkmcnt(0)
	s_barrier
	v_mov_b32_e32 v94, v31
	v_mov_b32_e32 v95, v177
	v_mov_b32_e32 v96, v33
	v_mov_b32_e32 v97, v179
	v_mov_b32_e32 v31, v176
	v_mov_b32_e32 v33, v178
	v_mov_b32_e32 v66, v3
	v_mov_b32_e32 v67, v173
	v_mov_b32_e32 v68, v5
	v_mov_b32_e32 v69, v175
	v_mov_b32_e32 v3, v172
	v_mov_b32_e32 v5, v174
	v_mov_b32_e32 v70, v7
	v_mov_b32_e32 v71, v169
	v_mov_b32_e32 v72, v9
	v_mov_b32_e32 v73, v171
	v_mov_b32_e32 v7, v168
	v_mov_b32_e32 v9, v170
	v_mov_b32_e32 v74, v11
	v_mov_b32_e32 v75, v165
	v_mov_b32_e32 v76, v13
	v_mov_b32_e32 v77, v167
	v_mov_b32_e32 v11, v164
	v_mov_b32_e32 v13, v166
	v_mov_b32_e32 v78, v15
	v_mov_b32_e32 v79, v161
	v_mov_b32_e32 v80, v17
	v_mov_b32_e32 v81, v163
	v_mov_b32_e32 v15, v160
	v_mov_b32_e32 v17, v162
	v_mov_b32_e32 v82, v19
	v_mov_b32_e32 v83, v157
	v_mov_b32_e32 v84, v21
	v_mov_b32_e32 v85, v159
	v_mov_b32_e32 v19, v156
	v_mov_b32_e32 v21, v158
	v_mov_b32_e32 v86, v23
	v_mov_b32_e32 v87, v153
	v_mov_b32_e32 v88, v25
	v_mov_b32_e32 v89, v155
	v_mov_b32_e32 v23, v152
	v_mov_b32_e32 v25, v154
	v_mov_b32_e32 v90, v27
	v_mov_b32_e32 v91, v149
	v_mov_b32_e32 v92, v29
	v_mov_b32_e32 v93, v151
	v_mov_b32_e32 v27, v148
	v_mov_b32_e32 v29, v150
	s_waitcnt lgkmcnt(0)
	s_barrier
	v_and_b32_e32 v174, 15, v0
	v_bfe_u32 v175, v0, 4, 2
	v_and_b32_e32 v111, 7, v174
	v_xor_b32_e32 v175, v175, v111
	v_lshlrev_b32_e32 v175, 4, v175
	v_lshl_or_b32 v175, v174, 7, v175
	v_bfe_u32 v174, v0, 7, 1
	v_lshl_or_b32 v100, v174, 13, v175
	v_bfe_u32 v174, v0, 6, 1
	v_lshl_or_b32 v168, v174, 13, v175
	v_or_b32_e32 v168, 0x4000, v168
	v_xor_b32_e32 v111, 64, v100
	v_xor_b32_e32 v169, 64, v168
	v_bfe_u32 v174, v0, 3, 3
	v_and_b32_e32 v175, 7, v0
	v_xor_b32_e32 v175, v175, v174
	v_lshlrev_b32_e32 v175, 4, v175
	v_lshl_or_b32 v175, v174, 11, v175
	v_lshrrev_b32_e32 v174, 6, v0
	v_and_b32_e32 v174, 3, v174
	v_lshl_or_b32 v170, v174, 16, v175
	v_add_u32_e32 v171, 0x3c00, v170
	v_add_u32_e32 v172, 0x7800, v170
	v_add_u32_e32 v173, 0xb400, v170
	v_lshlrev_b32_e32 v174, 12, v174
	s_nop 0
	v_readfirstlane_b32 s36, v174
	s_add_u32 s36, s36, 32
	v_mov_b32_e32 v116, 0
	v_mov_b32_e32 v117, 0
	v_mov_b32_e32 v118, 0
	v_mov_b32_e32 v119, 0
	v_mov_b32_e32 v120, 0
	v_mov_b32_e32 v121, 0
	v_mov_b32_e32 v122, 0
	v_mov_b32_e32 v123, 0
	v_mov_b32_e32 v124, 0
	v_mov_b32_e32 v125, 0
	v_mov_b32_e32 v126, 0
	v_mov_b32_e32 v127, 0
	v_mov_b32_e32 v148, 0
	v_mov_b32_e32 v149, 0
	v_mov_b32_e32 v150, 0
	v_mov_b32_e32 v151, 0
	v_mov_b32_e32 v152, 0
	v_mov_b32_e32 v153, 0
	v_mov_b32_e32 v154, 0
	v_mov_b32_e32 v155, 0
	v_mov_b32_e32 v156, 0
	v_mov_b32_e32 v157, 0
	v_mov_b32_e32 v158, 0
	v_mov_b32_e32 v159, 0
	v_mov_b32_e32 v160, 0
	v_mov_b32_e32 v161, 0
	v_mov_b32_e32 v162, 0
	v_mov_b32_e32 v163, 0
	v_mov_b32_e32 v164, 0
	v_mov_b32_e32 v165, 0
	v_mov_b32_e32 v166, 0
	v_mov_b32_e32 v167, 0
	s_waitcnt lgkmcnt(0)
	s_barrier
	s_add_u32 m0, s36, 0
	s_nop 0
	global_load_lds_dwordx4 v170, s[6:7] offset:0
	global_load_lds_dwordx4 v171, s[6:7] offset:1024
	global_load_lds_dwordx4 v172, s[6:7] offset:2048
	global_load_lds_dwordx4 v173, s[6:7] offset:3072
	s_add_u32 m0, s36, 16384
	s_nop 0
	global_load_lds_dwordx4 v170, s[8:9] offset:0
	global_load_lds_dwordx4 v171, s[8:9] offset:1024
	global_load_lds_dwordx4 v172, s[8:9] offset:2048
	global_load_lds_dwordx4 v173, s[8:9] offset:3072
	s_add_u32 s6, s6, 0x80
	s_addc_u32 s7, s7, 0
	s_add_u32 s8, s8, 0x80
	s_addc_u32 s9, s9, 0
	s_mov_b32 s5, 0
	s_waitcnt vmcnt(0)
.Lk_aol1b_loop:
	s_barrier
	s_add_u32 m0, s36, 32768
	v_mfma_f32_16x16x32_bf16 v[26:29], v[116:119], v[152:155], v[26:29]
	ds_read_b128 v[34:37], v100 offset:32
	global_load_lds_dwordx4 v170, s[6:7] offset:0
	v_mfma_f32_16x16x32_bf16 v[90:93], v[116:119], v[156:159], v[90:93]
	ds_read_b128 v[50:53], v168 offset:32
	global_load_lds_dwordx4 v171, s[6:7] offset:1024
	v_mfma_f32_16x16x32_bf16 v[22:25], v[116:119], v[160:163], v[22:25]
	ds_read_b128 v[54:57], v168 offset:2080
	global_load_lds_dwordx4 v172, s[6:7] offset:2048
	v_mfma_f32_16x16x32_bf16 v[86:89], v[116:119], v[164:167], v[86:89]
	ds_read_b128 v[38:41], v100 offset:2080
	global_load_lds_dwordx4 v173, s[6:7] offset:3072
	s_add_u32 m0, s36, 49152
	v_mfma_f32_16x16x32_bf16 v[18:21], v[120:123], v[152:155], v[18:21]
	ds_read_b128 v[58:61], v168 offset:4128
	global_load_lds_dwordx4 v170, s[8:9] offset:0
	v_mfma_f32_16x16x32_bf16 v[82:85], v[120:123], v[156:159], v[82:85]
	ds_read_b128 v[62:65], v168 offset:6176
	global_load_lds_dwordx4 v171, s[8:9] offset:1024
	v_mfma_f32_16x16x32_bf16 v[14:17], v[120:123], v[160:163], v[14:17]
	ds_read_b128 v[42:45], v100 offset:4128
	global_load_lds_dwordx4 v172, s[8:9] offset:2048
	v_mfma_f32_16x16x32_bf16 v[78:81], v[120:123], v[164:167], v[78:81]
	ds_read_b128 v[46:49], v100 offset:6176
	global_load_lds_dwordx4 v173, s[8:9] offset:3072
	v_mfma_f32_16x16x32_bf16 v[10:13], v[124:127], v[152:155], v[10:13]
	v_mfma_f32_16x16x32_bf16 v[74:77], v[124:127], v[156:159], v[74:77]
	v_mfma_f32_16x16x32_bf16 v[6:9], v[124:127], v[160:163], v[6:9]
	v_mfma_f32_16x16x32_bf16 v[70:73], v[124:127], v[164:167], v[70:73]
	v_mfma_f32_16x16x32_bf16 v[2:5], v[148:151], v[152:155], v[2:5]
	v_mfma_f32_16x16x32_bf16 v[66:69], v[148:151], v[156:159], v[66:69]
	v_mfma_f32_16x16x32_bf16 v[30:33], v[148:151], v[160:163], v[30:33]
	v_mfma_f32_16x16x32_bf16 v[94:97], v[148:151], v[164:167], v[94:97]
	s_add_u32 s6, s6, 0x80
	s_addc_u32 s7, s7, 0
	s_add_u32 s8, s8, 0x80
	s_addc_u32 s9, s9, 0
	s_waitcnt lgkmcnt(0)
	v_mfma_f32_16x16x32_bf16 v[26:29], v[34:37], v[50:53], v[26:29]
	ds_read_b128 v[116:119], v111 offset:32
	v_mfma_f32_16x16x32_bf16 v[90:93], v[34:37], v[54:57], v[90:93]
	ds_read_b128 v[152:155], v169 offset:32
	v_mfma_f32_16x16x32_bf16 v[22:25], v[34:37], v[58:61], v[22:25]
	ds_read_b128 v[156:159], v169 offset:2080
	v_mfma_f32_16x16x32_bf16 v[86:89], v[34:37], v[62:65], v[86:89]
	ds_read_b128 v[120:123], v111 offset:2080
	v_mfma_f32_16x16x32_bf16 v[18:21], v[38:41], v[50:53], v[18:21]
	ds_read_b128 v[160:163], v169 offset:4128
	v_mfma_f32_16x16x32_bf16 v[82:85], v[38:41], v[54:57], v[82:85]
	ds_read_b128 v[164:167], v169 offset:6176
	v_mfma_f32_16x16x32_bf16 v[14:17], v[38:41], v[58:61], v[14:17]
	ds_read_b128 v[124:127], v111 offset:4128
	v_mfma_f32_16x16x32_bf16 v[78:81], v[38:41], v[62:65], v[78:81]
	ds_read_b128 v[148:151], v111 offset:6176
	v_mfma_f32_16x16x32_bf16 v[10:13], v[42:45], v[50:53], v[10:13]
	v_mfma_f32_16x16x32_bf16 v[74:77], v[42:45], v[54:57], v[74:77]
	v_mfma_f32_16x16x32_bf16 v[6:9], v[42:45], v[58:61], v[6:9]
	v_mfma_f32_16x16x32_bf16 v[70:73], v[42:45], v[62:65], v[70:73]
	v_mfma_f32_16x16x32_bf16 v[2:5], v[46:49], v[50:53], v[2:5]
	v_mfma_f32_16x16x32_bf16 v[66:69], v[46:49], v[54:57], v[66:69]
	v_mfma_f32_16x16x32_bf16 v[30:33], v[46:49], v[58:61], v[30:33]
	v_mfma_f32_16x16x32_bf16 v[94:97], v[46:49], v[62:65], v[94:97]
	s_waitcnt lgkmcnt(0)
	s_waitcnt vmcnt(0)
	s_barrier
	s_add_u32 m0, s36, 0
	v_mfma_f32_16x16x32_bf16 v[26:29], v[116:119], v[152:155], v[26:29]
	ds_read_b128 v[34:37], v100 offset:32800
	global_load_lds_dwordx4 v170, s[6:7] offset:0
	v_mfma_f32_16x16x32_bf16 v[90:93], v[116:119], v[156:159], v[90:93]
	ds_read_b128 v[50:53], v168 offset:32800
	global_load_lds_dwordx4 v171, s[6:7] offset:1024
	v_mfma_f32_16x16x32_bf16 v[22:25], v[116:119], v[160:163], v[22:25]
	ds_read_b128 v[54:57], v168 offset:34848
	global_load_lds_dwordx4 v172, s[6:7] offset:2048
	v_mfma_f32_16x16x32_bf16 v[86:89], v[116:119], v[164:167], v[86:89]
	ds_read_b128 v[38:41], v100 offset:34848
	global_load_lds_dwordx4 v173, s[6:7] offset:3072
	s_add_u32 m0, s36, 16384
	v_mfma_f32_16x16x32_bf16 v[18:21], v[120:123], v[152:155], v[18:21]
	ds_read_b128 v[58:61], v168 offset:36896
	global_load_lds_dwordx4 v170, s[8:9] offset:0
	v_mfma_f32_16x16x32_bf16 v[82:85], v[120:123], v[156:159], v[82:85]
	ds_read_b128 v[62:65], v168 offset:38944
	global_load_lds_dwordx4 v171, s[8:9] offset:1024
	v_mfma_f32_16x16x32_bf16 v[14:17], v[120:123], v[160:163], v[14:17]
	ds_read_b128 v[42:45], v100 offset:36896
	global_load_lds_dwordx4 v172, s[8:9] offset:2048
	v_mfma_f32_16x16x32_bf16 v[78:81], v[120:123], v[164:167], v[78:81]
	ds_read_b128 v[46:49], v100 offset:38944
	global_load_lds_dwordx4 v173, s[8:9] offset:3072
	v_mfma_f32_16x16x32_bf16 v[10:13], v[124:127], v[152:155], v[10:13]
	v_mfma_f32_16x16x32_bf16 v[74:77], v[124:127], v[156:159], v[74:77]
	v_mfma_f32_16x16x32_bf16 v[6:9], v[124:127], v[160:163], v[6:9]
	v_mfma_f32_16x16x32_bf16 v[70:73], v[124:127], v[164:167], v[70:73]
	v_mfma_f32_16x16x32_bf16 v[2:5], v[148:151], v[152:155], v[2:5]
	v_mfma_f32_16x16x32_bf16 v[66:69], v[148:151], v[156:159], v[66:69]
	v_mfma_f32_16x16x32_bf16 v[30:33], v[148:151], v[160:163], v[30:33]
	v_mfma_f32_16x16x32_bf16 v[94:97], v[148:151], v[164:167], v[94:97]
	s_add_u32 s6, s6, 0x80
	s_addc_u32 s7, s7, 0
	s_add_u32 s8, s8, 0x80
	s_addc_u32 s9, s9, 0
	s_waitcnt lgkmcnt(0)
	v_mfma_f32_16x16x32_bf16 v[26:29], v[34:37], v[50:53], v[26:29]
	ds_read_b128 v[116:119], v111 offset:32800
	v_mfma_f32_16x16x32_bf16 v[90:93], v[34:37], v[54:57], v[90:93]
	ds_read_b128 v[152:155], v169 offset:32800
	v_mfma_f32_16x16x32_bf16 v[22:25], v[34:37], v[58:61], v[22:25]
	ds_read_b128 v[156:159], v169 offset:34848
	v_mfma_f32_16x16x32_bf16 v[86:89], v[34:37], v[62:65], v[86:89]
	ds_read_b128 v[120:123], v111 offset:34848
	v_mfma_f32_16x16x32_bf16 v[18:21], v[38:41], v[50:53], v[18:21]
	ds_read_b128 v[160:163], v169 offset:36896
	v_mfma_f32_16x16x32_bf16 v[82:85], v[38:41], v[54:57], v[82:85]
	ds_read_b128 v[164:167], v169 offset:38944
	v_mfma_f32_16x16x32_bf16 v[14:17], v[38:41], v[58:61], v[14:17]
	ds_read_b128 v[124:127], v111 offset:36896
	v_mfma_f32_16x16x32_bf16 v[78:81], v[38:41], v[62:65], v[78:81]
	ds_read_b128 v[148:151], v111 offset:38944
	v_mfma_f32_16x16x32_bf16 v[10:13], v[42:45], v[50:53], v[10:13]
	v_mfma_f32_16x16x32_bf16 v[74:77], v[42:45], v[54:57], v[74:77]
	v_mfma_f32_16x16x32_bf16 v[6:9], v[42:45], v[58:61], v[6:9]
	v_mfma_f32_16x16x32_bf16 v[70:73], v[42:45], v[62:65], v[70:73]
	v_mfma_f32_16x16x32_bf16 v[2:5], v[46:49], v[50:53], v[2:5]
	v_mfma_f32_16x16x32_bf16 v[66:69], v[46:49], v[54:57], v[66:69]
	v_mfma_f32_16x16x32_bf16 v[30:33], v[46:49], v[58:61], v[30:33]
	v_mfma_f32_16x16x32_bf16 v[94:97], v[46:49], v[62:65], v[94:97]
	s_waitcnt lgkmcnt(0)
	s_waitcnt vmcnt(0)
	s_add_u32 s5, s5, 1
	s_cmp_lt_u32 s5, 7
	s_cbranch_scc1 .Lk_aol1b_loop
	s_barrier
	s_add_u32 m0, s36, 32768
	v_mfma_f32_16x16x32_bf16 v[26:29], v[116:119], v[152:155], v[26:29]
	ds_read_b128 v[34:37], v100 offset:32
	global_load_lds_dwordx4 v170, s[6:7] offset:0
	v_mfma_f32_16x16x32_bf16 v[90:93], v[116:119], v[156:159], v[90:93]
	ds_read_b128 v[50:53], v168 offset:32
	global_load_lds_dwordx4 v171, s[6:7] offset:1024
	v_mfma_f32_16x16x32_bf16 v[22:25], v[116:119], v[160:163], v[22:25]
	ds_read_b128 v[54:57], v168 offset:2080
	global_load_lds_dwordx4 v172, s[6:7] offset:2048
	v_mfma_f32_16x16x32_bf16 v[86:89], v[116:119], v[164:167], v[86:89]
	ds_read_b128 v[38:41], v100 offset:2080
	global_load_lds_dwordx4 v173, s[6:7] offset:3072
	s_add_u32 m0, s36, 49152
	v_mfma_f32_16x16x32_bf16 v[18:21], v[120:123], v[152:155], v[18:21]
	ds_read_b128 v[58:61], v168 offset:4128
	global_load_lds_dwordx4 v170, s[8:9] offset:0
	v_mfma_f32_16x16x32_bf16 v[82:85], v[120:123], v[156:159], v[82:85]
	ds_read_b128 v[62:65], v168 offset:6176
	global_load_lds_dwordx4 v171, s[8:9] offset:1024
	v_mfma_f32_16x16x32_bf16 v[14:17], v[120:123], v[160:163], v[14:17]
	ds_read_b128 v[42:45], v100 offset:4128
	global_load_lds_dwordx4 v172, s[8:9] offset:2048
	v_mfma_f32_16x16x32_bf16 v[78:81], v[120:123], v[164:167], v[78:81]
	ds_read_b128 v[46:49], v100 offset:6176
	global_load_lds_dwordx4 v173, s[8:9] offset:3072
	v_mfma_f32_16x16x32_bf16 v[10:13], v[124:127], v[152:155], v[10:13]
	v_mfma_f32_16x16x32_bf16 v[74:77], v[124:127], v[156:159], v[74:77]
	v_mfma_f32_16x16x32_bf16 v[6:9], v[124:127], v[160:163], v[6:9]
	v_mfma_f32_16x16x32_bf16 v[70:73], v[124:127], v[164:167], v[70:73]
	v_mfma_f32_16x16x32_bf16 v[2:5], v[148:151], v[152:155], v[2:5]
	v_mfma_f32_16x16x32_bf16 v[66:69], v[148:151], v[156:159], v[66:69]
	v_mfma_f32_16x16x32_bf16 v[30:33], v[148:151], v[160:163], v[30:33]
	v_mfma_f32_16x16x32_bf16 v[94:97], v[148:151], v[164:167], v[94:97]
	s_add_u32 s6, s6, 0x80
	s_addc_u32 s7, s7, 0
	s_add_u32 s8, s8, 0x80
	s_addc_u32 s9, s9, 0
	s_waitcnt lgkmcnt(0)
	v_mfma_f32_16x16x32_bf16 v[26:29], v[34:37], v[50:53], v[26:29]
	ds_read_b128 v[116:119], v111 offset:32
	v_mfma_f32_16x16x32_bf16 v[90:93], v[34:37], v[54:57], v[90:93]
	ds_read_b128 v[152:155], v169 offset:32
	v_mfma_f32_16x16x32_bf16 v[22:25], v[34:37], v[58:61], v[22:25]
	ds_read_b128 v[156:159], v169 offset:2080
	v_mfma_f32_16x16x32_bf16 v[86:89], v[34:37], v[62:65], v[86:89]
	ds_read_b128 v[120:123], v111 offset:2080
	v_mfma_f32_16x16x32_bf16 v[18:21], v[38:41], v[50:53], v[18:21]
	ds_read_b128 v[160:163], v169 offset:4128
	v_mfma_f32_16x16x32_bf16 v[82:85], v[38:41], v[54:57], v[82:85]
	ds_read_b128 v[164:167], v169 offset:6176
	v_mfma_f32_16x16x32_bf16 v[14:17], v[38:41], v[58:61], v[14:17]
	ds_read_b128 v[124:127], v111 offset:4128
	v_mfma_f32_16x16x32_bf16 v[78:81], v[38:41], v[62:65], v[78:81]
	ds_read_b128 v[148:151], v111 offset:6176
	v_mfma_f32_16x16x32_bf16 v[10:13], v[42:45], v[50:53], v[10:13]
	v_mfma_f32_16x16x32_bf16 v[74:77], v[42:45], v[54:57], v[74:77]
	v_mfma_f32_16x16x32_bf16 v[6:9], v[42:45], v[58:61], v[6:9]
	v_mfma_f32_16x16x32_bf16 v[70:73], v[42:45], v[62:65], v[70:73]
	v_mfma_f32_16x16x32_bf16 v[2:5], v[46:49], v[50:53], v[2:5]
	v_mfma_f32_16x16x32_bf16 v[66:69], v[46:49], v[54:57], v[66:69]
	v_mfma_f32_16x16x32_bf16 v[30:33], v[46:49], v[58:61], v[30:33]
	v_mfma_f32_16x16x32_bf16 v[94:97], v[46:49], v[62:65], v[94:97]
	s_waitcnt lgkmcnt(0)
	s_waitcnt vmcnt(0)
	s_barrier
	v_mfma_f32_16x16x32_bf16 v[26:29], v[116:119], v[152:155], v[26:29]
	ds_read_b128 v[34:37], v100 offset:32800
	v_mfma_f32_16x16x32_bf16 v[90:93], v[116:119], v[156:159], v[90:93]
	ds_read_b128 v[50:53], v168 offset:32800
	v_mfma_f32_16x16x32_bf16 v[22:25], v[116:119], v[160:163], v[22:25]
	ds_read_b128 v[54:57], v168 offset:34848
	v_mfma_f32_16x16x32_bf16 v[86:89], v[116:119], v[164:167], v[86:89]
	ds_read_b128 v[38:41], v100 offset:34848
	v_mfma_f32_16x16x32_bf16 v[18:21], v[120:123], v[152:155], v[18:21]
	ds_read_b128 v[58:61], v168 offset:36896
	v_mfma_f32_16x16x32_bf16 v[82:85], v[120:123], v[156:159], v[82:85]
	ds_read_b128 v[62:65], v168 offset:38944
	v_mfma_f32_16x16x32_bf16 v[14:17], v[120:123], v[160:163], v[14:17]
	ds_read_b128 v[42:45], v100 offset:36896
	v_mfma_f32_16x16x32_bf16 v[78:81], v[120:123], v[164:167], v[78:81]
	ds_read_b128 v[46:49], v100 offset:38944
	v_mfma_f32_16x16x32_bf16 v[10:13], v[124:127], v[152:155], v[10:13]
	v_mfma_f32_16x16x32_bf16 v[74:77], v[124:127], v[156:159], v[74:77]
	v_mfma_f32_16x16x32_bf16 v[6:9], v[124:127], v[160:163], v[6:9]
	v_mfma_f32_16x16x32_bf16 v[70:73], v[124:127], v[164:167], v[70:73]
	v_mfma_f32_16x16x32_bf16 v[2:5], v[148:151], v[152:155], v[2:5]
	v_mfma_f32_16x16x32_bf16 v[66:69], v[148:151], v[156:159], v[66:69]
	v_mfma_f32_16x16x32_bf16 v[30:33], v[148:151], v[160:163], v[30:33]
	v_mfma_f32_16x16x32_bf16 v[94:97], v[148:151], v[164:167], v[94:97]
	s_waitcnt lgkmcnt(0)
	v_mfma_f32_16x16x32_bf16 v[26:29], v[34:37], v[50:53], v[26:29]
	ds_read_b128 v[116:119], v111 offset:32800
	v_mfma_f32_16x16x32_bf16 v[90:93], v[34:37], v[54:57], v[90:93]
	ds_read_b128 v[152:155], v169 offset:32800
	v_mfma_f32_16x16x32_bf16 v[22:25], v[34:37], v[58:61], v[22:25]
	ds_read_b128 v[156:159], v169 offset:34848
	v_mfma_f32_16x16x32_bf16 v[86:89], v[34:37], v[62:65], v[86:89]
	ds_read_b128 v[120:123], v111 offset:34848
	v_mfma_f32_16x16x32_bf16 v[18:21], v[38:41], v[50:53], v[18:21]
	ds_read_b128 v[160:163], v169 offset:36896
	v_mfma_f32_16x16x32_bf16 v[82:85], v[38:41], v[54:57], v[82:85]
	ds_read_b128 v[164:167], v169 offset:38944
	v_mfma_f32_16x16x32_bf16 v[14:17], v[38:41], v[58:61], v[14:17]
	ds_read_b128 v[124:127], v111 offset:36896
	v_mfma_f32_16x16x32_bf16 v[78:81], v[38:41], v[62:65], v[78:81]
	ds_read_b128 v[148:151], v111 offset:38944
	v_mfma_f32_16x16x32_bf16 v[10:13], v[42:45], v[50:53], v[10:13]
	v_mfma_f32_16x16x32_bf16 v[74:77], v[42:45], v[54:57], v[74:77]
	v_mfma_f32_16x16x32_bf16 v[6:9], v[42:45], v[58:61], v[6:9]
	v_mfma_f32_16x16x32_bf16 v[70:73], v[42:45], v[62:65], v[70:73]
	v_mfma_f32_16x16x32_bf16 v[2:5], v[46:49], v[50:53], v[2:5]
	v_mfma_f32_16x16x32_bf16 v[66:69], v[46:49], v[54:57], v[66:69]
	v_mfma_f32_16x16x32_bf16 v[30:33], v[46:49], v[58:61], v[30:33]
	v_mfma_f32_16x16x32_bf16 v[94:97], v[46:49], v[62:65], v[94:97]
	s_waitcnt lgkmcnt(0)
	v_mfma_f32_16x16x32_bf16 v[26:29], v[116:119], v[152:155], v[26:29]
	v_mfma_f32_16x16x32_bf16 v[90:93], v[116:119], v[156:159], v[90:93]
	v_mfma_f32_16x16x32_bf16 v[22:25], v[116:119], v[160:163], v[22:25]
	v_mfma_f32_16x16x32_bf16 v[86:89], v[116:119], v[164:167], v[86:89]
	v_mfma_f32_16x16x32_bf16 v[18:21], v[120:123], v[152:155], v[18:21]
	v_mfma_f32_16x16x32_bf16 v[82:85], v[120:123], v[156:159], v[82:85]
	v_mfma_f32_16x16x32_bf16 v[14:17], v[120:123], v[160:163], v[14:17]
	v_mfma_f32_16x16x32_bf16 v[78:81], v[120:123], v[164:167], v[78:81]
	v_mfma_f32_16x16x32_bf16 v[10:13], v[124:127], v[152:155], v[10:13]
	v_mfma_f32_16x16x32_bf16 v[74:77], v[124:127], v[156:159], v[74:77]
	v_mfma_f32_16x16x32_bf16 v[6:9], v[124:127], v[160:163], v[6:9]
	v_mfma_f32_16x16x32_bf16 v[70:73], v[124:127], v[164:167], v[70:73]
	v_mfma_f32_16x16x32_bf16 v[2:5], v[148:151], v[152:155], v[2:5]
	v_mfma_f32_16x16x32_bf16 v[66:69], v[148:151], v[156:159], v[66:69]
	v_mfma_f32_16x16x32_bf16 v[30:33], v[148:151], v[160:163], v[30:33]
	v_mfma_f32_16x16x32_bf16 v[94:97], v[148:151], v[164:167], v[94:97]
	s_lshl_b32 s36, s4, 1
	s_lshl_b32 s4, s70, 10
	s_mul_hi_u32 s5, s70, 0x15555556
	s_barrier
	ds_write2_b32 v129, v26, v90 offset1:16
	ds_write2_b32 v129, v27, v91 offset0:132 offset1:148
	ds_write2_b32 v138, v28, v92 offset0:8 offset1:24
	ds_write2_b32 v138, v29, v93 offset0:140 offset1:156
	ds_write2_b32 v129, v22, v86 offset0:32 offset1:48
	ds_write2_b32 v129, v23, v87 offset0:164 offset1:180
	ds_write2_b32 v138, v24, v88 offset0:40 offset1:56
	ds_write2_b32 v138, v25, v89 offset0:172 offset1:188
	ds_write2_b32 v139, v18, v82 offset0:64 offset1:80
	ds_write2_b32 v139, v19, v83 offset0:196 offset1:212
	ds_write2_b32 v140, v20, v84 offset0:72 offset1:88
	ds_write2_b32 v140, v21, v85 offset0:204 offset1:220
	ds_write2_b32 v139, v14, v78 offset0:96 offset1:112
	ds_write2_b32 v139, v15, v79 offset0:228 offset1:244
	ds_write2_b32 v140, v16, v80 offset0:104 offset1:120
	ds_write2_b32 v140, v17, v81 offset0:236 offset1:252
	ds_write2_b32 v141, v10, v74 offset0:128 offset1:144
	ds_write2_b32 v142, v11, v75 offset0:4 offset1:20
	ds_write2_b32 v142, v12, v76 offset0:136 offset1:152
	ds_write2_b32 v143, v13, v77 offset0:12 offset1:28
	ds_write2_b32 v141, v6, v70 offset0:160 offset1:176
	ds_write2_b32 v142, v7, v71 offset0:36 offset1:52
	ds_write2_b32 v142, v8, v72 offset0:168 offset1:184
	ds_write2_b32 v143, v9, v73 offset0:44 offset1:60
	ds_write2_b32 v144, v2, v66 offset0:192 offset1:208
	ds_write2_b32 v145, v3, v67 offset0:68 offset1:84
	ds_write2_b32 v145, v4, v68 offset0:200 offset1:216
	ds_write2_b32 v146, v5, v69 offset0:76 offset1:92
	ds_write2_b32 v144, v30, v94 offset0:224 offset1:240
	ds_write2_b32 v145, v31, v95 offset0:100 offset1:116
	ds_write2_b32 v145, v32, v96 offset0:232 offset1:248
	ds_write2_b32 v146, v33, v97 offset0:108 offset1:124
	v_or_b32_e32 v4, s4, v134
	s_mulk_i32 s5, 0x3000
	v_or_b32_e32 v5, s4, v132
	v_lshl_add_u64 v[2:3], v[106:107], 0, s[36:37]
	v_subrev_u32_e32 v4, s5, v4
	v_subrev_u32_e32 v100, s5, v5
	s_mov_b32 s4, 0
	s_waitcnt lgkmcnt(0)
	s_barrier

.LBB0_1372:
	s_and_b32 s28, s11, 0xff
	s_mul_i32 s2, s28, 0xab
	s_lshr_b32 s29, s2, 11
	s_mul_i32 s2, s29, 12
	s_sub_i32 s2, s11, s2
	s_and_b32 s2, s2, 0xff
	s_lshl_b32 s2, s2, 21
	s_or_b32 s2, s2, s21
	s_add_u32 s14, s16, s2
	s_addc_u32 s15, s17, 0
	s_lshl_b32 s2, s29, 18
	s_add_u32 s12, s18, s2
	s_addc_u32 s13, s19, 0
	v_and_b32_e32 v162, 15, v0
	v_bfe_u32 v163, v0, 4, 2
	v_and_b32_e32 v107, 7, v162
	v_xor_b32_e32 v163, v163, v107
	v_lshlrev_b32_e32 v163, 4, v163
	v_lshl_or_b32 v163, v162, 7, v163
	v_bfe_u32 v162, v0, 7, 1
	v_lshl_or_b32 v98, v162, 13, v163
	v_bfe_u32 v162, v0, 6, 1
	v_lshl_or_b32 v156, v162, 13, v163
	v_or_b32_e32 v156, 0x4000, v156
	v_xor_b32_e32 v107, 64, v98
	v_xor_b32_e32 v157, 64, v156
	v_bfe_u32 v162, v0, 3, 3
	v_and_b32_e32 v163, 7, v0
	v_xor_b32_e32 v163, v163, v162
	v_lshlrev_b32_e32 v163, 4, v163
	v_lshl_or_b32 v163, v162, 11, v163
	v_lshrrev_b32_e32 v162, 6, v0
	v_and_b32_e32 v162, 3, v162
	v_lshl_or_b32 v158, v162, 16, v163
	v_add_u32_e32 v159, 0x3c00, v158
	v_add_u32_e32 v160, 0x7800, v158
	v_add_u32_e32 v161, 0xb400, v158
	v_lshlrev_b32_e32 v162, 12, v162
	s_nop 0
	v_readfirstlane_b32 s31, v162
	s_add_u32 s31, s31, 32
	v_mov_b32_e32 v94, 0
	v_mov_b32_e32 v95, 0
	v_mov_b32_e32 v96, 0
	v_mov_b32_e32 v97, 0
	v_mov_b32_e32 v90, 0
	v_mov_b32_e32 v91, 0
	v_mov_b32_e32 v92, 0
	v_mov_b32_e32 v93, 0
	v_mov_b32_e32 v82, 0
	v_mov_b32_e32 v83, 0
	v_mov_b32_e32 v84, 0
	v_mov_b32_e32 v85, 0
	v_mov_b32_e32 v78, 0
	v_mov_b32_e32 v79, 0
	v_mov_b32_e32 v80, 0
	v_mov_b32_e32 v81, 0
	v_mov_b32_e32 v74, 0
	v_mov_b32_e32 v75, 0
	v_mov_b32_e32 v76, 0
	v_mov_b32_e32 v77, 0
	v_mov_b32_e32 v70, 0
	v_mov_b32_e32 v71, 0
	v_mov_b32_e32 v72, 0
	v_mov_b32_e32 v73, 0
	v_mov_b32_e32 v66, 0
	v_mov_b32_e32 v67, 0
	v_mov_b32_e32 v68, 0
	v_mov_b32_e32 v69, 0
	v_mov_b32_e32 v62, 0
	v_mov_b32_e32 v63, 0
	v_mov_b32_e32 v64, 0
	v_mov_b32_e32 v65, 0
	v_mov_b32_e32 v58, 0
	v_mov_b32_e32 v59, 0
	v_mov_b32_e32 v60, 0
	v_mov_b32_e32 v61, 0
	v_mov_b32_e32 v42, 0
	v_mov_b32_e32 v43, 0
	v_mov_b32_e32 v44, 0
	v_mov_b32_e32 v45, 0
	v_mov_b32_e32 v22, 0
	v_mov_b32_e32 v23, 0
	v_mov_b32_e32 v24, 0
	v_mov_b32_e32 v25, 0
	v_mov_b32_e32 v14, 0
	v_mov_b32_e32 v15, 0
	v_mov_b32_e32 v16, 0
	v_mov_b32_e32 v17, 0
	v_mov_b32_e32 v10, 0
	v_mov_b32_e32 v11, 0
	v_mov_b32_e32 v12, 0
	v_mov_b32_e32 v13, 0
	v_mov_b32_e32 v6, 0
	v_mov_b32_e32 v7, 0
	v_mov_b32_e32 v8, 0
	v_mov_b32_e32 v9, 0
	v_mov_b32_e32 v2, 0
	v_mov_b32_e32 v3, 0
	v_mov_b32_e32 v4, 0
	v_mov_b32_e32 v5, 0
	v_mov_b32_e32 v86, 0
	v_mov_b32_e32 v87, 0
	v_mov_b32_e32 v88, 0
	v_mov_b32_e32 v89, 0
	v_mov_b32_e32 v108, 0
	v_mov_b32_e32 v109, 0
	v_mov_b32_e32 v110, 0
	v_mov_b32_e32 v111, 0
	v_mov_b32_e32 v112, 0
	v_mov_b32_e32 v113, 0
	v_mov_b32_e32 v114, 0
	v_mov_b32_e32 v115, 0
	v_mov_b32_e32 v116, 0
	v_mov_b32_e32 v117, 0
	v_mov_b32_e32 v118, 0
	v_mov_b32_e32 v119, 0
	v_mov_b32_e32 v136, 0
	v_mov_b32_e32 v137, 0
	v_mov_b32_e32 v138, 0
	v_mov_b32_e32 v139, 0
	v_mov_b32_e32 v140, 0
	v_mov_b32_e32 v141, 0
	v_mov_b32_e32 v142, 0
	v_mov_b32_e32 v143, 0
	v_mov_b32_e32 v144, 0
	v_mov_b32_e32 v145, 0
	v_mov_b32_e32 v146, 0
	v_mov_b32_e32 v147, 0
	v_mov_b32_e32 v148, 0
	v_mov_b32_e32 v149, 0
	v_mov_b32_e32 v150, 0
	v_mov_b32_e32 v151, 0
	v_mov_b32_e32 v152, 0
	v_mov_b32_e32 v153, 0
	v_mov_b32_e32 v154, 0
	v_mov_b32_e32 v155, 0
	s_waitcnt lgkmcnt(0)
	s_barrier
	s_add_u32 m0, s31, 0
	s_nop 0
	global_load_lds_dwordx4 v158, s[14:15] offset:0
	global_load_lds_dwordx4 v159, s[14:15] offset:1024
	global_load_lds_dwordx4 v160, s[14:15] offset:2048
	global_load_lds_dwordx4 v161, s[14:15] offset:3072
	s_add_u32 m0, s31, 16384
	s_nop 0
	global_load_lds_dwordx4 v158, s[12:13] offset:0
	global_load_lds_dwordx4 v159, s[12:13] offset:1024
	global_load_lds_dwordx4 v160, s[12:13] offset:2048
	global_load_lds_dwordx4 v161, s[12:13] offset:3072
	s_add_u32 s14, s14, 0x80
	s_addc_u32 s15, s15, 0
	s_add_u32 s12, s12, 0x80
	s_addc_u32 s13, s13, 0
	s_mov_b32 s30, 0
	s_waitcnt vmcnt(0)
.Lk_outl1_loop:
	s_barrier
	s_add_u32 m0, s31, 32768
	v_mfma_f32_16x16x32_bf16 v[94:97], v[108:111], v[140:143], v[94:97]
	ds_read_b128 v[18:21], v98 offset:32
	global_load_lds_dwordx4 v158, s[14:15] offset:0
	v_mfma_f32_16x16x32_bf16 v[90:93], v[108:111], v[144:147], v[90:93]
	ds_read_b128 v[38:41], v156 offset:32
	global_load_lds_dwordx4 v159, s[14:15] offset:1024
	v_mfma_f32_16x16x32_bf16 v[82:85], v[108:111], v[148:151], v[82:85]
	ds_read_b128 v[46:49], v156 offset:2080
	global_load_lds_dwordx4 v160, s[14:15] offset:2048
	v_mfma_f32_16x16x32_bf16 v[78:81], v[108:111], v[152:155], v[78:81]
	ds_read_b128 v[26:29], v98 offset:2080
	global_load_lds_dwordx4 v161, s[14:15] offset:3072
	s_add_u32 m0, s31, 49152
	v_mfma_f32_16x16x32_bf16 v[74:77], v[112:115], v[140:143], v[74:77]
	ds_read_b128 v[50:53], v156 offset:4128
	global_load_lds_dwordx4 v158, s[12:13] offset:0
	v_mfma_f32_16x16x32_bf16 v[70:73], v[112:115], v[144:147], v[70:73]
	ds_read_b128 v[54:57], v156 offset:6176
	global_load_lds_dwordx4 v159, s[12:13] offset:1024
	v_mfma_f32_16x16x32_bf16 v[66:69], v[112:115], v[148:151], v[66:69]
	ds_read_b128 v[30:33], v98 offset:4128
	global_load_lds_dwordx4 v160, s[12:13] offset:2048
	v_mfma_f32_16x16x32_bf16 v[62:65], v[112:115], v[152:155], v[62:65]
	ds_read_b128 v[34:37], v98 offset:6176
	global_load_lds_dwordx4 v161, s[12:13] offset:3072
	v_mfma_f32_16x16x32_bf16 v[58:61], v[116:119], v[140:143], v[58:61]
	v_mfma_f32_16x16x32_bf16 v[42:45], v[116:119], v[144:147], v[42:45]
	v_mfma_f32_16x16x32_bf16 v[22:25], v[116:119], v[148:151], v[22:25]
	v_mfma_f32_16x16x32_bf16 v[14:17], v[116:119], v[152:155], v[14:17]
	v_mfma_f32_16x16x32_bf16 v[10:13], v[136:139], v[140:143], v[10:13]
	v_mfma_f32_16x16x32_bf16 v[6:9], v[136:139], v[144:147], v[6:9]
	v_mfma_f32_16x16x32_bf16 v[2:5], v[136:139], v[148:151], v[2:5]
	v_mfma_f32_16x16x32_bf16 v[86:89], v[136:139], v[152:155], v[86:89]
	s_add_u32 s14, s14, 0x80
	s_addc_u32 s15, s15, 0
	s_add_u32 s12, s12, 0x80
	s_addc_u32 s13, s13, 0
	s_waitcnt lgkmcnt(0)
	v_mfma_f32_16x16x32_bf16 v[94:97], v[18:21], v[38:41], v[94:97]
	ds_read_b128 v[108:111], v107 offset:32
	v_mfma_f32_16x16x32_bf16 v[90:93], v[18:21], v[46:49], v[90:93]
	ds_read_b128 v[140:143], v157 offset:32
	v_mfma_f32_16x16x32_bf16 v[82:85], v[18:21], v[50:53], v[82:85]
	ds_read_b128 v[144:147], v157 offset:2080
	v_mfma_f32_16x16x32_bf16 v[78:81], v[18:21], v[54:57], v[78:81]
	ds_read_b128 v[112:115], v107 offset:2080
	v_mfma_f32_16x16x32_bf16 v[74:77], v[26:29], v[38:41], v[74:77]
	ds_read_b128 v[148:151], v157 offset:4128
	v_mfma_f32_16x16x32_bf16 v[70:73], v[26:29], v[46:49], v[70:73]
	ds_read_b128 v[152:155], v157 offset:6176
	v_mfma_f32_16x16x32_bf16 v[66:69], v[26:29], v[50:53], v[66:69]
	ds_read_b128 v[116:119], v107 offset:4128
	v_mfma_f32_16x16x32_bf16 v[62:65], v[26:29], v[54:57], v[62:65]
	ds_read_b128 v[136:139], v107 offset:6176
	v_mfma_f32_16x16x32_bf16 v[58:61], v[30:33], v[38:41], v[58:61]
	v_mfma_f32_16x16x32_bf16 v[42:45], v[30:33], v[46:49], v[42:45]
	v_mfma_f32_16x16x32_bf16 v[22:25], v[30:33], v[50:53], v[22:25]
	v_mfma_f32_16x16x32_bf16 v[14:17], v[30:33], v[54:57], v[14:17]
	v_mfma_f32_16x16x32_bf16 v[10:13], v[34:37], v[38:41], v[10:13]
	v_mfma_f32_16x16x32_bf16 v[6:9], v[34:37], v[46:49], v[6:9]
	v_mfma_f32_16x16x32_bf16 v[2:5], v[34:37], v[50:53], v[2:5]
	v_mfma_f32_16x16x32_bf16 v[86:89], v[34:37], v[54:57], v[86:89]
	s_waitcnt lgkmcnt(0)
	s_waitcnt vmcnt(0)
	s_barrier
	s_add_u32 m0, s31, 0
	v_mfma_f32_16x16x32_bf16 v[94:97], v[108:111], v[140:143], v[94:97]
	ds_read_b128 v[18:21], v98 offset:32800
	global_load_lds_dwordx4 v158, s[14:15] offset:0
	v_mfma_f32_16x16x32_bf16 v[90:93], v[108:111], v[144:147], v[90:93]
	ds_read_b128 v[38:41], v156 offset:32800
	global_load_lds_dwordx4 v159, s[14:15] offset:1024
	v_mfma_f32_16x16x32_bf16 v[82:85], v[108:111], v[148:151], v[82:85]
	ds_read_b128 v[46:49], v156 offset:34848
	global_load_lds_dwordx4 v160, s[14:15] offset:2048
	v_mfma_f32_16x16x32_bf16 v[78:81], v[108:111], v[152:155], v[78:81]
	ds_read_b128 v[26:29], v98 offset:34848
	global_load_lds_dwordx4 v161, s[14:15] offset:3072
	s_add_u32 m0, s31, 16384
	v_mfma_f32_16x16x32_bf16 v[74:77], v[112:115], v[140:143], v[74:77]
	ds_read_b128 v[50:53], v156 offset:36896
	global_load_lds_dwordx4 v158, s[12:13] offset:0
	v_mfma_f32_16x16x32_bf16 v[70:73], v[112:115], v[144:147], v[70:73]
	ds_read_b128 v[54:57], v156 offset:38944
	global_load_lds_dwordx4 v159, s[12:13] offset:1024
	v_mfma_f32_16x16x32_bf16 v[66:69], v[112:115], v[148:151], v[66:69]
	ds_read_b128 v[30:33], v98 offset:36896
	global_load_lds_dwordx4 v160, s[12:13] offset:2048
	v_mfma_f32_16x16x32_bf16 v[62:65], v[112:115], v[152:155], v[62:65]
	ds_read_b128 v[34:37], v98 offset:38944
	global_load_lds_dwordx4 v161, s[12:13] offset:3072
	v_mfma_f32_16x16x32_bf16 v[58:61], v[116:119], v[140:143], v[58:61]
	v_mfma_f32_16x16x32_bf16 v[42:45], v[116:119], v[144:147], v[42:45]
	v_mfma_f32_16x16x32_bf16 v[22:25], v[116:119], v[148:151], v[22:25]
	v_mfma_f32_16x16x32_bf16 v[14:17], v[116:119], v[152:155], v[14:17]
	v_mfma_f32_16x16x32_bf16 v[10:13], v[136:139], v[140:143], v[10:13]
	v_mfma_f32_16x16x32_bf16 v[6:9], v[136:139], v[144:147], v[6:9]
	v_mfma_f32_16x16x32_bf16 v[2:5], v[136:139], v[148:151], v[2:5]
	v_mfma_f32_16x16x32_bf16 v[86:89], v[136:139], v[152:155], v[86:89]
	s_add_u32 s14, s14, 0x80
	s_addc_u32 s15, s15, 0
	s_add_u32 s12, s12, 0x80
	s_addc_u32 s13, s13, 0
	s_waitcnt lgkmcnt(0)
	v_mfma_f32_16x16x32_bf16 v[94:97], v[18:21], v[38:41], v[94:97]
	ds_read_b128 v[108:111], v107 offset:32800
	v_mfma_f32_16x16x32_bf16 v[90:93], v[18:21], v[46:49], v[90:93]
	ds_read_b128 v[140:143], v157 offset:32800
	v_mfma_f32_16x16x32_bf16 v[82:85], v[18:21], v[50:53], v[82:85]
	ds_read_b128 v[144:147], v157 offset:34848
	v_mfma_f32_16x16x32_bf16 v[78:81], v[18:21], v[54:57], v[78:81]
	ds_read_b128 v[112:115], v107 offset:34848
	v_mfma_f32_16x16x32_bf16 v[74:77], v[26:29], v[38:41], v[74:77]
	ds_read_b128 v[148:151], v157 offset:36896
	v_mfma_f32_16x16x32_bf16 v[70:73], v[26:29], v[46:49], v[70:73]
	ds_read_b128 v[152:155], v157 offset:38944
	v_mfma_f32_16x16x32_bf16 v[66:69], v[26:29], v[50:53], v[66:69]
	ds_read_b128 v[116:119], v107 offset:36896
	v_mfma_f32_16x16x32_bf16 v[62:65], v[26:29], v[54:57], v[62:65]
	ds_read_b128 v[136:139], v107 offset:38944
	v_mfma_f32_16x16x32_bf16 v[58:61], v[30:33], v[38:41], v[58:61]
	v_mfma_f32_16x16x32_bf16 v[42:45], v[30:33], v[46:49], v[42:45]
	v_mfma_f32_16x16x32_bf16 v[22:25], v[30:33], v[50:53], v[22:25]
	v_mfma_f32_16x16x32_bf16 v[14:17], v[30:33], v[54:57], v[14:17]
	v_mfma_f32_16x16x32_bf16 v[10:13], v[34:37], v[38:41], v[10:13]
	v_mfma_f32_16x16x32_bf16 v[6:9], v[34:37], v[46:49], v[6:9]
	v_mfma_f32_16x16x32_bf16 v[2:5], v[34:37], v[50:53], v[2:5]
	v_mfma_f32_16x16x32_bf16 v[86:89], v[34:37], v[54:57], v[86:89]
	s_waitcnt lgkmcnt(0)
	s_waitcnt vmcnt(0)
	s_add_u32 s30, s30, 1
	s_cmp_lt_u32 s30, 7
	s_cbranch_scc1 .Lk_outl1_loop
	s_barrier
	s_add_u32 m0, s31, 32768
	v_mfma_f32_16x16x32_bf16 v[94:97], v[108:111], v[140:143], v[94:97]
	ds_read_b128 v[18:21], v98 offset:32
	global_load_lds_dwordx4 v158, s[14:15] offset:0
	v_mfma_f32_16x16x32_bf16 v[90:93], v[108:111], v[144:147], v[90:93]
	ds_read_b128 v[38:41], v156 offset:32
	global_load_lds_dwordx4 v159, s[14:15] offset:1024
	v_mfma_f32_16x16x32_bf16 v[82:85], v[108:111], v[148:151], v[82:85]
	ds_read_b128 v[46:49], v156 offset:2080
	global_load_lds_dwordx4 v160, s[14:15] offset:2048
	v_mfma_f32_16x16x32_bf16 v[78:81], v[108:111], v[152:155], v[78:81]
	ds_read_b128 v[26:29], v98 offset:2080
	global_load_lds_dwordx4 v161, s[14:15] offset:3072
	s_add_u32 m0, s31, 49152
	v_mfma_f32_16x16x32_bf16 v[74:77], v[112:115], v[140:143], v[74:77]
	ds_read_b128 v[50:53], v156 offset:4128
	global_load_lds_dwordx4 v158, s[12:13] offset:0
	v_mfma_f32_16x16x32_bf16 v[70:73], v[112:115], v[144:147], v[70:73]
	ds_read_b128 v[54:57], v156 offset:6176
	global_load_lds_dwordx4 v159, s[12:13] offset:1024
	v_mfma_f32_16x16x32_bf16 v[66:69], v[112:115], v[148:151], v[66:69]
	ds_read_b128 v[30:33], v98 offset:4128
	global_load_lds_dwordx4 v160, s[12:13] offset:2048
	v_mfma_f32_16x16x32_bf16 v[62:65], v[112:115], v[152:155], v[62:65]
	ds_read_b128 v[34:37], v98 offset:6176
	global_load_lds_dwordx4 v161, s[12:13] offset:3072
	v_mfma_f32_16x16x32_bf16 v[58:61], v[116:119], v[140:143], v[58:61]
	v_mfma_f32_16x16x32_bf16 v[42:45], v[116:119], v[144:147], v[42:45]
	v_mfma_f32_16x16x32_bf16 v[22:25], v[116:119], v[148:151], v[22:25]
	v_mfma_f32_16x16x32_bf16 v[14:17], v[116:119], v[152:155], v[14:17]
	v_mfma_f32_16x16x32_bf16 v[10:13], v[136:139], v[140:143], v[10:13]
	v_mfma_f32_16x16x32_bf16 v[6:9], v[136:139], v[144:147], v[6:9]
	v_mfma_f32_16x16x32_bf16 v[2:5], v[136:139], v[148:151], v[2:5]
	v_mfma_f32_16x16x32_bf16 v[86:89], v[136:139], v[152:155], v[86:89]
	s_add_u32 s14, s14, 0x80
	s_addc_u32 s15, s15, 0
	s_add_u32 s12, s12, 0x80
	s_addc_u32 s13, s13, 0
	s_waitcnt lgkmcnt(0)
	v_mfma_f32_16x16x32_bf16 v[94:97], v[18:21], v[38:41], v[94:97]
	ds_read_b128 v[108:111], v107 offset:32
	v_mfma_f32_16x16x32_bf16 v[90:93], v[18:21], v[46:49], v[90:93]
	ds_read_b128 v[140:143], v157 offset:32
	v_mfma_f32_16x16x32_bf16 v[82:85], v[18:21], v[50:53], v[82:85]
	ds_read_b128 v[144:147], v157 offset:2080
	v_mfma_f32_16x16x32_bf16 v[78:81], v[18:21], v[54:57], v[78:81]
	ds_read_b128 v[112:115], v107 offset:2080
	v_mfma_f32_16x16x32_bf16 v[74:77], v[26:29], v[38:41], v[74:77]
	ds_read_b128 v[148:151], v157 offset:4128
	v_mfma_f32_16x16x32_bf16 v[70:73], v[26:29], v[46:49], v[70:73]
	ds_read_b128 v[152:155], v157 offset:6176
	v_mfma_f32_16x16x32_bf16 v[66:69], v[26:29], v[50:53], v[66:69]
	ds_read_b128 v[116:119], v107 offset:4128
	v_mfma_f32_16x16x32_bf16 v[62:65], v[26:29], v[54:57], v[62:65]
	ds_read_b128 v[136:139], v107 offset:6176
	v_mfma_f32_16x16x32_bf16 v[58:61], v[30:33], v[38:41], v[58:61]
	v_mfma_f32_16x16x32_bf16 v[42:45], v[30:33], v[46:49], v[42:45]
	v_mfma_f32_16x16x32_bf16 v[22:25], v[30:33], v[50:53], v[22:25]
	v_mfma_f32_16x16x32_bf16 v[14:17], v[30:33], v[54:57], v[14:17]
	v_mfma_f32_16x16x32_bf16 v[10:13], v[34:37], v[38:41], v[10:13]
	v_mfma_f32_16x16x32_bf16 v[6:9], v[34:37], v[46:49], v[6:9]
	v_mfma_f32_16x16x32_bf16 v[2:5], v[34:37], v[50:53], v[2:5]
	v_mfma_f32_16x16x32_bf16 v[86:89], v[34:37], v[54:57], v[86:89]
	s_waitcnt lgkmcnt(0)
	s_waitcnt vmcnt(0)
	s_barrier
	v_mfma_f32_16x16x32_bf16 v[94:97], v[108:111], v[140:143], v[94:97]
	ds_read_b128 v[18:21], v98 offset:32800
	v_mfma_f32_16x16x32_bf16 v[90:93], v[108:111], v[144:147], v[90:93]
	ds_read_b128 v[38:41], v156 offset:32800
	v_mfma_f32_16x16x32_bf16 v[82:85], v[108:111], v[148:151], v[82:85]
	ds_read_b128 v[46:49], v156 offset:34848
	v_mfma_f32_16x16x32_bf16 v[78:81], v[108:111], v[152:155], v[78:81]
	ds_read_b128 v[26:29], v98 offset:34848
	v_mfma_f32_16x16x32_bf16 v[74:77], v[112:115], v[140:143], v[74:77]
	ds_read_b128 v[50:53], v156 offset:36896
	v_mfma_f32_16x16x32_bf16 v[70:73], v[112:115], v[144:147], v[70:73]
	ds_read_b128 v[54:57], v156 offset:38944
	v_mfma_f32_16x16x32_bf16 v[66:69], v[112:115], v[148:151], v[66:69]
	ds_read_b128 v[30:33], v98 offset:36896
	v_mfma_f32_16x16x32_bf16 v[62:65], v[112:115], v[152:155], v[62:65]
	ds_read_b128 v[34:37], v98 offset:38944
	v_mfma_f32_16x16x32_bf16 v[58:61], v[116:119], v[140:143], v[58:61]
	v_mfma_f32_16x16x32_bf16 v[42:45], v[116:119], v[144:147], v[42:45]
	v_mfma_f32_16x16x32_bf16 v[22:25], v[116:119], v[148:151], v[22:25]
	v_mfma_f32_16x16x32_bf16 v[14:17], v[116:119], v[152:155], v[14:17]
	v_mfma_f32_16x16x32_bf16 v[10:13], v[136:139], v[140:143], v[10:13]
	v_mfma_f32_16x16x32_bf16 v[6:9], v[136:139], v[144:147], v[6:9]
	v_mfma_f32_16x16x32_bf16 v[2:5], v[136:139], v[148:151], v[2:5]
	v_mfma_f32_16x16x32_bf16 v[86:89], v[136:139], v[152:155], v[86:89]
	s_waitcnt lgkmcnt(0)
	v_mfma_f32_16x16x32_bf16 v[94:97], v[18:21], v[38:41], v[94:97]
	ds_read_b128 v[108:111], v107 offset:32800
	v_mfma_f32_16x16x32_bf16 v[90:93], v[18:21], v[46:49], v[90:93]
	ds_read_b128 v[140:143], v157 offset:32800
	v_mfma_f32_16x16x32_bf16 v[82:85], v[18:21], v[50:53], v[82:85]
	ds_read_b128 v[144:147], v157 offset:34848
	v_mfma_f32_16x16x32_bf16 v[78:81], v[18:21], v[54:57], v[78:81]
	ds_read_b128 v[112:115], v107 offset:34848
	v_mfma_f32_16x16x32_bf16 v[74:77], v[26:29], v[38:41], v[74:77]
	ds_read_b128 v[148:151], v157 offset:36896
	v_mfma_f32_16x16x32_bf16 v[70:73], v[26:29], v[46:49], v[70:73]
	ds_read_b128 v[152:155], v157 offset:38944
	v_mfma_f32_16x16x32_bf16 v[66:69], v[26:29], v[50:53], v[66:69]
	ds_read_b128 v[116:119], v107 offset:36896
	v_mfma_f32_16x16x32_bf16 v[62:65], v[26:29], v[54:57], v[62:65]
	ds_read_b128 v[136:139], v107 offset:38944
	v_mfma_f32_16x16x32_bf16 v[58:61], v[30:33], v[38:41], v[58:61]
	v_mfma_f32_16x16x32_bf16 v[42:45], v[30:33], v[46:49], v[42:45]
	v_mfma_f32_16x16x32_bf16 v[22:25], v[30:33], v[50:53], v[22:25]
	v_mfma_f32_16x16x32_bf16 v[14:17], v[30:33], v[54:57], v[14:17]
	v_mfma_f32_16x16x32_bf16 v[10:13], v[34:37], v[38:41], v[10:13]
	v_mfma_f32_16x16x32_bf16 v[6:9], v[34:37], v[46:49], v[6:9]
	v_mfma_f32_16x16x32_bf16 v[2:5], v[34:37], v[50:53], v[2:5]
	v_mfma_f32_16x16x32_bf16 v[86:89], v[34:37], v[54:57], v[86:89]
	s_waitcnt lgkmcnt(0)
	v_mfma_f32_16x16x32_bf16 v[94:97], v[108:111], v[140:143], v[94:97]
	v_mfma_f32_16x16x32_bf16 v[90:93], v[108:111], v[144:147], v[90:93]
	v_mfma_f32_16x16x32_bf16 v[82:85], v[108:111], v[148:151], v[82:85]
	v_mfma_f32_16x16x32_bf16 v[78:81], v[108:111], v[152:155], v[78:81]
	v_mfma_f32_16x16x32_bf16 v[74:77], v[112:115], v[140:143], v[74:77]
	v_mfma_f32_16x16x32_bf16 v[70:73], v[112:115], v[144:147], v[70:73]
	v_mfma_f32_16x16x32_bf16 v[66:69], v[112:115], v[148:151], v[66:69]
	v_mfma_f32_16x16x32_bf16 v[62:65], v[112:115], v[152:155], v[62:65]
	v_mfma_f32_16x16x32_bf16 v[58:61], v[116:119], v[140:143], v[58:61]
	v_mfma_f32_16x16x32_bf16 v[42:45], v[116:119], v[144:147], v[42:45]
	v_mfma_f32_16x16x32_bf16 v[22:25], v[116:119], v[148:151], v[22:25]
	v_mfma_f32_16x16x32_bf16 v[14:17], v[116:119], v[152:155], v[14:17]
	v_mfma_f32_16x16x32_bf16 v[10:13], v[136:139], v[140:143], v[10:13]
	v_mfma_f32_16x16x32_bf16 v[6:9], v[136:139], v[144:147], v[6:9]
	v_mfma_f32_16x16x32_bf16 v[2:5], v[136:139], v[148:151], v[2:5]
	v_mfma_f32_16x16x32_bf16 v[86:89], v[136:139], v[152:155], v[86:89]
	s_waitcnt vmcnt(7)
	v_add_u32_e32 v18, 0x400, v123
	s_barrier
	ds_write2_b32 v123, v94, v90 offset1:16
	ds_write2_b32 v123, v95, v91 offset0:132 offset1:148
	ds_write2_b32 v18, v96, v92 offset0:8 offset1:24
	ds_write2_b32 v18, v97, v93 offset0:140 offset1:156
	ds_write2_b32 v123, v82, v78 offset0:32 offset1:48
	ds_write2_b32 v123, v83, v79 offset0:164 offset1:180
	ds_write2_b32 v18, v84, v80 offset0:40 offset1:56
	ds_write2_b32 v18, v85, v81 offset0:172 offset1:188
	v_add_u32_e32 v18, 0x2000, v123
	v_add_u32_e32 v19, 0x2400, v123
	ds_write2_b32 v18, v74, v70 offset0:64 offset1:80
	ds_write2_b32 v18, v75, v71 offset0:196 offset1:212
	ds_write2_b32 v19, v76, v72 offset0:72 offset1:88
	ds_write2_b32 v19, v77, v73 offset0:204 offset1:220
	ds_write2_b32 v18, v66, v62 offset0:96 offset1:112
	ds_write2_b32 v18, v67, v63 offset0:228 offset1:244
	ds_write2_b32 v19, v68, v64 offset0:104 offset1:120
	ds_write2_b32 v19, v69, v65 offset0:236 offset1:252
	v_add_u32_e32 v18, 0x4000, v123
	v_add_u32_e32 v19, 0x4400, v123
	v_add_u32_e32 v20, 0x4800, v123
	ds_write2_b32 v18, v58, v42 offset0:128 offset1:144
	ds_write2_b32 v19, v59, v43 offset0:4 offset1:20
	ds_write2_b32 v19, v60, v44 offset0:136 offset1:152
	ds_write2_b32 v20, v61, v45 offset0:12 offset1:28
	ds_write2_b32 v18, v22, v14 offset0:160 offset1:176
	ds_write2_b32 v19, v23, v15 offset0:36 offset1:52
	ds_write2_b32 v19, v24, v16 offset0:168 offset1:184
	ds_write2_b32 v20, v25, v17 offset0:44 offset1:60
	v_add_u32_e32 v14, 0x6000, v123
	ds_write2_b32 v14, v10, v6 offset0:192 offset1:208
	v_add_u32_e32 v6, 0x6400, v123
	ds_write2_b32 v6, v11, v7 offset0:68 offset1:84
	ds_write2_b32 v6, v12, v8 offset0:200 offset1:216
	v_add_u32_e32 v7, 0x6800, v123
	s_lshl_b32 s2, s29, 9
	ds_write2_b32 v7, v13, v9 offset0:76 offset1:92
	ds_write2_b32 v14, v2, v86 offset0:224 offset1:240
	ds_write2_b32 v6, v3, v87 offset0:100 offset1:116
	ds_write2_b32 v6, v4, v88 offset0:232 offset1:248
	ds_write2_b32 v7, v5, v89 offset0:108 offset1:124
	v_lshl_add_u64 v[2:3], v[100:101], 0, s[2:3]
	v_lshl_add_u64 v[4:5], v[102:103], 0, s[2:3]
	s_lshl_b32 s2, s28, 10
	s_mul_hi_u32 s12, s28, 0x15555556
	s_lshl_b32 s13, s29, 7
	v_or_b32_e32 v6, s2, v125
	s_mulk_i32 s12, 0x3000
	v_or_b32_e32 v7, s2, v127
	v_or_b32_e32 v8, s2, v129
	v_or_b32_e32 v9, s2, v133
	v_subrev_u32_e32 v6, s12, v6
	v_subrev_u32_e32 v7, s12, v7
	v_subrev_u32_e32 v8, s12, v8
	v_subrev_u32_e32 v9, s12, v9
	s_mov_b32 s12, 0
	s_lshl_b32 s2, s13, 2
	v_mov_b32_e32 v10, v132
	v_mov_b32_e32 v11, v128
	v_mov_b32_e32 v12, v126
	v_mov_b32_e32 v13, v124
	s_waitcnt lgkmcnt(0)
	s_barrier

.LBB0_1431:
	s_cmp_gt_i32 s44, 17
	s_cselect_b64 s[2:3], -1, 0
	s_cmp_lt_i32 s45, 18
	s_cselect_b64 s[4:5], -1, 0
	s_or_b64 s[2:3], s[2:3], s[4:5]
	s_and_b64 vcc, exec, s[2:3]
	s_cbranch_vccnz .LBB0_1489
	s_load_dword s20, s[0:1], 0xf0
	v_lshl_or_b32 v2, s66, 2, v131
	s_add_u32 s4, s0, 0xf0
	s_movk_i32 s2, 0x3000
	v_and_b32_e32 v1, 0x3ff, v0
	s_addc_u32 s5, s1, 0
	v_cmp_gt_i32_e32 vcc, s2, v2
	s_and_saveexec_b64 s[2:3], vcc
	s_cbranch_execz .LBB0_1435
	s_load_dwordx4 s[52:55], s[0:1], 0x90
	v_and_b32_e32 v10, 63, v1
	v_lshlrev_b32_e32 v2, 4, v10
	v_lshlrev_b32_e32 v3, 3, v10
	v_xor_b32_e32 v4, 32, v10
	v_lshlrev_b32_e32 v4, 2, v4
	v_xor_b32_e32 v5, 16, v10
	v_lshlrev_b32_e32 v5, 2, v5
	v_xor_b32_e32 v6, 8, v10
	v_lshlrev_b32_e32 v6, 2, v6
	v_xor_b32_e32 v7, 4, v10
	v_lshlrev_b32_e32 v7, 2, v7
	v_xor_b32_e32 v8, 2, v10
	v_lshlrev_b32_e32 v8, 2, v8
	v_xor_b32_e32 v9, 1, v10
	v_lshlrev_b32_e32 v9, 2, v9
	v_lshrrev_b32_e32 v11, 6, v1
	s_nop 0
	v_readfirstlane_b32 s6, v11
	s_lshl_b32 s19, s66, 2
	s_add_u32 s6, s6, s19
	s_waitcnt lgkmcnt(0)
	s_lshl_b32 s7, s20, 2
	s_add_u32 s52, s52, 0x1000
	s_addc_u32 s53, s53, 0
	s_add_u32 s54, s54, 0x1000
	s_addc_u32 s55, s55, 0
	global_load_dwordx4 v[68:71], v2, s[52:53] offset:0
	global_load_dwordx4 v[100:103], v2, s[54:55] offset:0
	global_load_dwordx4 v[72:75], v2, s[52:53] offset:1024
	global_load_dwordx4 v[104:107], v2, s[54:55] offset:1024
	global_load_dwordx4 v[76:79], v2, s[52:53] offset:2048
	global_load_dwordx4 v[108:111], v2, s[54:55] offset:2048
	global_load_dwordx4 v[80:83], v2, s[52:53] offset:3072
	global_load_dwordx4 v[112:115], v2, s[54:55] offset:3072
	s_lshl_b32 s19, s6, 12
	s_add_u32 s12, s42, s19
	s_addc_u32 s13, s43, 0
	s_add_u32 s12, s12, 0xfb24000
	s_addc_u32 s13, s13, 0
	s_sub_u32 s19, s6, 0x2000
	s_lshr_b32 s19, s19, 10
	s_add_u32 s19, s19, 1
	s_cmp_lt_u32 s6, 0x2000
	s_cselect_b32 s19, 0, s19
	s_mul_i32 s19, s19, 0x6000
	s_add_u32 s16, s42, s19
	s_addc_u32 s17, s43, 0
	s_add_u32 s16, s16, 0x6ec5000
	s_addc_u32 s17, s17, 0
	s_add_u32 s22, s16, 0x1000
	s_addc_u32 s23, s17, 0
	global_load_dwordx4 v[20:23], v2, s[12:13] offset:0 nt
	global_load_dwordx4 v[24:27], v2, s[12:13] offset:1024 nt
	global_load_dwordx4 v[28:31], v2, s[12:13] offset:2048 nt
	global_load_dwordx4 v[32:35], v2, s[12:13] offset:3072 nt
	global_load_dwordx4 v[36:39], v2, s[16:17] offset:0
	global_load_dwordx4 v[52:55], v2, s[22:23] offset:0
	global_load_dwordx4 v[40:43], v2, s[16:17] offset:1024
	global_load_dwordx4 v[56:59], v2, s[22:23] offset:1024
	global_load_dwordx4 v[44:47], v2, s[16:17] offset:2048
	global_load_dwordx4 v[60:63], v2, s[22:23] offset:2048
	global_load_dwordx4 v[48:51], v2, s[16:17] offset:3072
	global_load_dwordx4 v[64:67], v2, s[22:23] offset:3072
	s_waitcnt vmcnt(0)
.Lln1_l1_loop:
	s_mov_b64 s[8:9], s[12:13]
	s_lshl_b32 s19, s6, 11
	s_add_u32 s10, s42, s19
	s_addc_u32 s11, s43, 0
	s_add_u32 s10, s10, 0x9f24000
	s_addc_u32 s11, s11, 0
	v_pk_add_f32 v[12:13], v[20:21], v[22:23]
	v_pk_add_f32 v[12:13], v[12:13], v[24:25]
	v_pk_add_f32 v[12:13], v[12:13], v[26:27]
	v_pk_add_f32 v[12:13], v[12:13], v[28:29]
	v_pk_add_f32 v[12:13], v[12:13], v[30:31]
	v_pk_add_f32 v[12:13], v[12:13], v[32:33]
	v_pk_add_f32 v[12:13], v[12:13], v[34:35]
	v_add_f32_e32 v10, v12, v13
	ds_bpermute_b32 v11, v4, v10
	s_waitcnt lgkmcnt(0)
	v_add_f32_e32 v10, v10, v11
	ds_bpermute_b32 v11, v5, v10
	s_waitcnt lgkmcnt(0)
	v_add_f32_e32 v10, v10, v11
	ds_bpermute_b32 v11, v6, v10
	s_waitcnt lgkmcnt(0)
	v_add_f32_e32 v10, v10, v11
	ds_bpermute_b32 v11, v7, v10
	s_waitcnt lgkmcnt(0)
	v_add_f32_e32 v10, v10, v11
	ds_bpermute_b32 v11, v8, v10
	s_waitcnt lgkmcnt(0)
	v_add_f32_e32 v10, v10, v11
	ds_bpermute_b32 v11, v9, v10
	s_waitcnt lgkmcnt(0)
	v_add_f32_e32 v10, v10, v11
	v_mul_f32_e32 v14, 0x3a800000, v10
	v_pk_add_f32 v[20:21], v[20:21], v[14:15] op_sel_hi:[1,0] neg_lo:[0,1] neg_hi:[0,1]
	v_pk_add_f32 v[22:23], v[22:23], v[14:15] op_sel_hi:[1,0] neg_lo:[0,1] neg_hi:[0,1]
	v_pk_add_f32 v[24:25], v[24:25], v[14:15] op_sel_hi:[1,0] neg_lo:[0,1] neg_hi:[0,1]
	v_pk_add_f32 v[26:27], v[26:27], v[14:15] op_sel_hi:[1,0] neg_lo:[0,1] neg_hi:[0,1]
	v_pk_add_f32 v[28:29], v[28:29], v[14:15] op_sel_hi:[1,0] neg_lo:[0,1] neg_hi:[0,1]
	v_pk_add_f32 v[30:31], v[30:31], v[14:15] op_sel_hi:[1,0] neg_lo:[0,1] neg_hi:[0,1]
	v_pk_add_f32 v[32:33], v[32:33], v[14:15] op_sel_hi:[1,0] neg_lo:[0,1] neg_hi:[0,1]
	v_pk_add_f32 v[34:35], v[34:35], v[14:15] op_sel_hi:[1,0] neg_lo:[0,1] neg_hi:[0,1]
	v_pk_mul_f32 v[12:13], v[20:21], v[20:21]
	v_pk_fma_f32 v[12:13], v[22:23], v[22:23], v[12:13]
	v_pk_fma_f32 v[12:13], v[24:25], v[24:25], v[12:13]
	v_pk_fma_f32 v[12:13], v[26:27], v[26:27], v[12:13]
	v_pk_fma_f32 v[12:13], v[28:29], v[28:29], v[12:13]
	v_pk_fma_f32 v[12:13], v[30:31], v[30:31], v[12:13]
	v_pk_fma_f32 v[12:13], v[32:33], v[32:33], v[12:13]
	v_pk_fma_f32 v[12:13], v[34:35], v[34:35], v[12:13]
	v_add_f32_e32 v10, v12, v13
	ds_bpermute_b32 v11, v4, v10
	s_waitcnt lgkmcnt(0)
	v_add_f32_e32 v10, v10, v11
	ds_bpermute_b32 v11, v5, v10
	s_waitcnt lgkmcnt(0)
	v_add_f32_e32 v10, v10, v11
	ds_bpermute_b32 v11, v6, v10
	s_waitcnt lgkmcnt(0)
	v_add_f32_e32 v10, v10, v11
	ds_bpermute_b32 v11, v7, v10
	s_waitcnt lgkmcnt(0)
	v_add_f32_e32 v10, v10, v11
	ds_bpermute_b32 v11, v8, v10
	s_waitcnt lgkmcnt(0)
	v_add_f32_e32 v10, v10, v11
	ds_bpermute_b32 v11, v9, v10
	s_waitcnt lgkmcnt(0)
	v_add_f32_e32 v10, v10, v11
	v_mov_b32_e32 v11, 0x3727c5ac
	v_fmac_f32_e32 v11, 0x3a800000, v10
	v_rsq_f32_e32 v14, v11
	s_nop 0
	s_add_u32 s6, s6, s7
	s_cmp_lt_u32 s6, 0x3000
	s_cbranch_scc0 .Lln1_l1_nonext
	v_pk_mul_f32 v[20:21], v[20:21], v[14:15] op_sel_hi:[1,0]
	v_pk_fma_f32 v[132:133], v[68:69], v[20:21], v[100:101]
	v_pk_mul_f32 v[22:23], v[22:23], v[14:15] op_sel_hi:[1,0]
	v_pk_fma_f32 v[134:135], v[70:71], v[22:23], v[102:103]
	v_pk_mul_f32 v[24:25], v[24:25], v[14:15] op_sel_hi:[1,0]
	v_pk_fma_f32 v[136:137], v[72:73], v[24:25], v[104:105]
	v_pk_mul_f32 v[26:27], v[26:27], v[14:15] op_sel_hi:[1,0]
	v_pk_fma_f32 v[138:139], v[74:75], v[26:27], v[106:107]
	v_pk_mul_f32 v[28:29], v[28:29], v[14:15] op_sel_hi:[1,0]
	v_pk_fma_f32 v[140:141], v[76:77], v[28:29], v[108:109]
	v_pk_mul_f32 v[30:31], v[30:31], v[14:15] op_sel_hi:[1,0]
	v_pk_fma_f32 v[142:143], v[78:79], v[30:31], v[110:111]
	v_pk_mul_f32 v[32:33], v[32:33], v[14:15] op_sel_hi:[1,0]
	v_pk_fma_f32 v[144:145], v[80:81], v[32:33], v[112:113]
	v_pk_mul_f32 v[34:35], v[34:35], v[14:15] op_sel_hi:[1,0]
	v_pk_fma_f32 v[146:147], v[82:83], v[34:35], v[114:115]
	v_pk_add_f32 v[52:53], v[52:53], 1.0 op_sel_hi:[1,0]
	v_pk_fma_f32 v[52:53], v[52:53], v[132:133], v[36:37]
	v_pk_add_f32 v[54:55], v[54:55], 1.0 op_sel_hi:[1,0]
	v_pk_fma_f32 v[54:55], v[54:55], v[134:135], v[38:39]
	v_pk_add_f32 v[56:57], v[56:57], 1.0 op_sel_hi:[1,0]
	v_pk_fma_f32 v[56:57], v[56:57], v[136:137], v[40:41]
	v_pk_add_f32 v[58:59], v[58:59], 1.0 op_sel_hi:[1,0]
	v_pk_fma_f32 v[58:59], v[58:59], v[138:139], v[42:43]
	v_pk_add_f32 v[60:61], v[60:61], 1.0 op_sel_hi:[1,0]
	v_pk_fma_f32 v[60:61], v[60:61], v[140:141], v[44:45]
	v_pk_add_f32 v[62:63], v[62:63], 1.0 op_sel_hi:[1,0]
	v_pk_fma_f32 v[62:63], v[62:63], v[142:143], v[46:47]
	v_pk_add_f32 v[64:65], v[64:65], 1.0 op_sel_hi:[1,0]
	v_pk_fma_f32 v[64:65], v[64:65], v[144:145], v[48:49]
	v_pk_add_f32 v[66:67], v[66:67], 1.0 op_sel_hi:[1,0]
	v_pk_fma_f32 v[66:67], v[66:67], v[146:147], v[50:51]
	v_cvt_pk_bf16_f32 v148, v52, v53
	v_cvt_pk_bf16_f32 v149, v54, v55
	v_cvt_pk_bf16_f32 v150, v56, v57
	v_cvt_pk_bf16_f32 v151, v58, v59
	v_cvt_pk_bf16_f32 v152, v60, v61
	v_cvt_pk_bf16_f32 v153, v62, v63
	v_cvt_pk_bf16_f32 v154, v64, v65
	v_cvt_pk_bf16_f32 v155, v66, v67
	s_lshl_b32 s19, s6, 12
	s_add_u32 s12, s42, s19
	s_addc_u32 s13, s43, 0
	s_add_u32 s12, s12, 0xfb24000
	s_addc_u32 s13, s13, 0
	s_sub_u32 s19, s6, 0x2000
	s_lshr_b32 s19, s19, 10
	s_add_u32 s19, s19, 1
	s_cmp_lt_u32 s6, 0x2000
	s_cselect_b32 s19, 0, s19
	s_mul_i32 s19, s19, 0x6000
	s_add_u32 s16, s42, s19
	s_addc_u32 s17, s43, 0
	s_add_u32 s16, s16, 0x6ec5000
	s_addc_u32 s17, s17, 0
	s_add_u32 s22, s16, 0x1000
	s_addc_u32 s23, s17, 0
	global_load_dwordx4 v[20:23], v2, s[12:13] offset:0 nt
	global_load_dwordx4 v[24:27], v2, s[12:13] offset:1024 nt
	global_load_dwordx4 v[28:31], v2, s[12:13] offset:2048 nt
	global_load_dwordx4 v[32:35], v2, s[12:13] offset:3072 nt
	global_load_dwordx4 v[36:39], v2, s[16:17] offset:0
	global_load_dwordx4 v[52:55], v2, s[22:23] offset:0
	global_load_dwordx4 v[40:43], v2, s[16:17] offset:1024
	global_load_dwordx4 v[56:59], v2, s[22:23] offset:1024
	global_load_dwordx4 v[44:47], v2, s[16:17] offset:2048
	global_load_dwordx4 v[60:63], v2, s[22:23] offset:2048
	global_load_dwordx4 v[48:51], v2, s[16:17] offset:3072
	global_load_dwordx4 v[64:67], v2, s[22:23] offset:3072
	global_store_dwordx4 v2, v[132:135], s[8:9] offset:0
	global_store_dwordx4 v2, v[136:139], s[8:9] offset:1024
	global_store_dwordx4 v2, v[140:143], s[8:9] offset:2048
	global_store_dwordx4 v2, v[144:147], s[8:9] offset:3072
	global_store_dwordx2 v3, v[148:149], s[10:11] offset:0
	global_store_dwordx2 v3, v[150:151], s[10:11] offset:512
	global_store_dwordx2 v3, v[152:153], s[10:11] offset:1024
	global_store_dwordx2 v3, v[154:155], s[10:11] offset:1536
	s_waitcnt vmcnt(8)
	s_branch .Lln1_l1_loop
